# GEMM unit transitions: first two K-loop waits of a unit that follows an epilogue use vmcnt(8+stores) so the epilogue's stores need not drain before the first two MFMA segments (6 GEMM loops)
# baseline (speedup 1.0000x reference)
; #define LAS __attribute__((address_space(3)))
; template <class Epi>
; __device__ __forceinline__ void gemm_phase(LAS unsigned char* lds, const GemmD g, const Epi& E, int G, int c) {
;     int tid_ = threadIdx.x; asm volatile("" : "+v"(tid_));
;     const int tid = tid_, wid = __builtin_amdgcn_readfirstlane(tid >> 6), lane = tid & 63, wr = wid >> 2, wc = wid & 3, fr = lane & 15, fq = lane >> 4;
;     const int K = g.K, nt = K / BK;
;     unsigned voffA[2], voffB[2];
; #pragma unroll
;     for (int i = 0; i < 2; ++i) { int R, C; stage_rc(tid * 16 + i * 8192, R, C); const int Rb = Epi::PERM ? ((R & ~31) + perm32(R & 31)) : R;
;         voffA[i] = (unsigned)(R * g.lda + C) * 2u; voffB[i] = (unsigned)(Rb * g.ldb + C) * 2u; }
;     const size_t kstep = (size_t)(BK * 2);
;     const size_t hstepA = (size_t)HALF * g.lda * 2, hstepB = (size_t)HALF * g.ldb * 2;
;     const unsigned ldsw = (unsigned)wid * 1024u;
;     const int aoff = lds_byte(wr * 64 + fr, fq * 8), boff = lds_byte(wc * 32 + fr, fq * 8);
; __global__ void __launch_bounds__(512, 2) mega_fwd(Params p_) {
;     ...
;         case 8: {
;             GemmD g{}; g.A = Hm; g.Bt = WdT; g.lda = DFF; g.ldb = DFF; g.K = DFF; g.nM = 64; g.nN = 8; g.nZ = 1; g.zdiv = 1;
;             EpiRes E{outp, outp, layer == 1 ? (bf16_t*)nullptr : (bf16_t*)(ws + WS_XBM), rsa, (LAS float*)(lds + RED_OFF)}; gemm_phase(lds, g, E, G, c);
.LBB0_84:
	s_mov_b32 s99, 0
	s_add_u32 s4, s58, 0x3000000
	s_addc_u32 s5, s59, 0
	v_writelane_b32 v238, s4, 53
	s_nop 1
	v_writelane_b32 v238, s5, 54
	s_add_u32 s4, s58, 0x3800000
	s_addc_u32 s5, s59, 0
	s_add_u32 s74, s58, 0xc300000
	s_addc_u32 s75, s59, 0
	s_add_u32 s24, s58, 0x4200000
	v_writelane_b32 v238, s4, 55
	s_addc_u32 s25, s59, 0
	s_nop 0
	v_writelane_b32 v238, s5, 56
	s_add_u32 s4, s58, 0x4250000
	s_addc_u32 s5, s59, 0
	s_add_u32 s76, s58, 0x4300000
	s_addc_u32 s77, s59, 0
	s_add_u32 s40, s58, 0x8300000
	s_addc_u32 s41, s59, 0
	s_add_u32 s14, s58, 0x1c300000
	v_writelane_b32 v238, s4, 57
	s_addc_u32 s15, s59, 0
	s_lshl_b32 s2, s2, 14
	v_writelane_b32 v238, s5, 58
	s_add_i32 s2, s2, 0
	v_writelane_b32 v238, s2, 59
	s_add_i32 s2, s8, -8
	s_and_b64 s[4:5], exec, s[78:79]
	s_cselect_b32 s2, s2, s8
	s_cmp_lt_i32 s2, 4
	s_mov_b64 s[4:5], -1
	v_writelane_b32 v238, s2, 60
	s_cbranch_scc1 .LBB0_309
	v_readlane_b32 s2, v238, 60
	s_cmp_lt_i32 s2, 6
	s_cbranch_scc1 .LBB0_256
	s_add_u32 s60, s58, 0xef00000
	s_addc_u32 s61, s59, 0
	v_readlane_b32 s2, v238, 60
	s_cmp_lt_i32 s2, 7
	s_cbranch_scc1 .LBB0_210
	s_add_u32 s62, s58, 0x20300000
	s_addc_u32 s63, s59, 0
	v_readlane_b32 s2, v238, 60
	s_cmp_lt_i32 s2, 8
	s_cbranch_scc1 .LBB0_192
	v_readlane_b32 s2, v238, 60
	s_cmp_eq_u32 s2, 8
	s_cbranch_scc0 .LBB0_191
	v_readlane_b32 s4, v240, 59
	v_mov_b32_e32 v0, v176
	v_readlane_b32 s5, v240, 60
	s_andn2_b64 vcc, exec, s[4:5]
	v_readfirstlane_b32 s19, v0
	s_cbranch_vccnz .LBB0_149
	v_lshlrev_b32_e32 v1, 4, v0
	v_add_u32_e32 v2, 0x2000, v1
	v_ashrrev_i32_e32 v3, 31, v2
	v_lshrrev_b32_e32 v3, 22, v3
	v_add_u32_e32 v3, v2, v3
	v_ashrrev_i32_e32 v142, 10, v3
	v_mul_i32_i24_e32 v3, 0x400, v142
	v_sub_u32_e32 v2, v2, v3
	v_lshrrev_b32_e32 v3, 4, v2
	v_bitop3_b32 v2, v3, v2, 32 bitop3:0x6c
	v_ashrrev_i32_e32 v3, 31, v2
	v_lshrrev_b32_e32 v3, 26, v3
	v_add_u32_e32 v3, v2, v3
	v_lshlrev_b32_e32 v4, 3, v142
	v_ashrrev_i32_e32 v144, 6, v3
	v_and_b32_e32 v4, -16, v4
	v_add_u32_e32 v4, v144, v4
	v_and_b32_e32 v5, 3, v144
	s_mov_b32 s6, 0x7fffe0
	v_lshrrev_b32_e32 v6, 2, v4
	v_lshlrev_b32_e32 v7, 1, v4
	v_and_b32_e32 v3, 0xc0, v3
	v_and_or_b32 v5, v4, s6, v5
	v_and_b32_e32 v6, 4, v6
	v_and_b32_e32 v7, 24, v7
	v_sub_u32_e32 v2, v2, v3
	v_or3_b32 v5, v5, v6, v7
	v_lshlrev_b32_e32 v6, 5, v142
	v_ashrrev_i16_sdwa v2, v200, sext(v2) dst_sel:DWORD dst_unused:UNUSED_PAD src0_sel:DWORD src1_sel:BYTE_0
	v_and_b32_e32 v147, 32, v6
	v_bfe_i32 v151, v2, 0, 16
	s_movk_i32 s9, 0x1600
	v_mul_u32_u24_e32 v5, 0x1600, v5
	v_add_u32_e32 v2, v147, v151
	v_mul_lo_u32 v3, v4, s9
	v_add_lshl_u32 v128, v5, v2, 1
	v_add_lshl_u32 v130, v2, v3, 1
	v_bfe_i32 v2, v0, 27, 1
	v_lshrrev_b32_e32 v2, 22, v2
	v_add_u32_e32 v2, v1, v2
	v_and_b32_e32 v2, 0xfffffc00, v2
	v_sub_u32_e32 v1, v1, v2
	v_lshrrev_b32_e32 v2, 4, v1
	v_ashrrev_i32_e32 v3, 31, v0
	v_bitop3_b32 v1, v2, v1, 32 bitop3:0x6c
	v_lshrrev_b32_e32 v3, 26, v3
	v_bfe_u32 v145, v0, 4, 2
	v_and_b32_e32 v146, 15, v0
	v_ashrrev_i32_e32 v2, 31, v1
	v_add_u32_e32 v0, v0, v3
	v_lshrrev_b32_e32 v2, 26, v2
	v_ashrrev_i32_e32 v153, 6, v0
	v_add_u32_e32 v2, v1, v2
	v_lshlrev_b32_e32 v0, 3, v153
	v_ashrrev_i32_e32 v152, 6, v2
	v_and_b32_e32 v0, -16, v0
	v_add_u32_e32 v0, v152, v0
	v_and_b32_e32 v3, 3, v152
	v_lshrrev_b32_e32 v4, 2, v0
	v_lshlrev_b32_e32 v5, 1, v0
	v_and_b32_e32 v2, 0xc0, v2
	v_and_or_b32 v3, v0, s6, v3
	v_and_b32_e32 v4, 4, v4
	v_and_b32_e32 v5, 24, v5
	v_sub_u32_e32 v1, v1, v2
	s_ashr_i32 s22, s19, 8
	v_or3_b32 v3, v3, v4, v5
	v_lshlrev_b32_e32 v4, 5, v153
	v_ashrrev_i16_sdwa v1, v200, sext(v1) dst_sel:DWORD dst_unused:UNUSED_PAD src0_sel:DWORD src1_sel:BYTE_0
	s_ashr_i32 s2, s19, 6
	s_lshl_b32 s23, s22, 6
	v_and_b32_e32 v154, 32, v4
	v_bfe_i32 v155, v1, 0, 16
	v_readlane_b32 s6, v239, 21
	s_and_b32 s4, s2, 3
	v_add_u32_e32 v1, v154, v155
	v_mul_lo_u32 v0, v0, s9
	s_add_i32 s6, s6, s23
	s_lshl_b32 s5, s4, 5
	v_add_lshl_u32 v132, v1, v0, 1
	v_or_b32_e32 v0, s6, v146
	v_readlane_b32 s6, v239, 23
	v_lshlrev_b32_e32 v143, 3, v145
	v_mul_u32_u24_e32 v3, 0x1600, v3
	s_or_b32 s6, s6, s5
	v_or_b32_e32 v6, 16, v0
	v_add_lshl_u32 v178, v3, v1, 1
	v_or_b32_e32 v2, s6, v143
	v_ashrrev_i32_e32 v1, 31, v0
	v_ashrrev_i32_e32 v7, 31, v6
	v_ashrrev_i32_e32 v3, 31, v2
	v_lshlrev_b64 v[4:5], 13, v[0:1]
	v_lshlrev_b64 v[6:7], 13, v[6:7]
	v_lshl_add_u64 v[4:5], s[56:57], 0, v[4:5]
; #define PG8_STAGE(bufoff, gbase, voff) do { _Pragma("unroll") for (int _i = 0; _i < 2; ++_i) \
;         __builtin_amdgcn_global_load_lds((const unsigned*)((const char*)(gbase) + (voff)[_i]), (LAS unsigned*)(lds + (bufoff) + ldsw + _i * 8192), 16, 0, 0); } while (0)
; #define PG8_WAIT_V(n) asm volatile("s_waitcnt vmcnt(" #n ")" ::: "memory")
; #define PG8_BAR __builtin_amdgcn_s_barrier()
; template <class Epi>
; __device__ __forceinline__ void gemm_phase(LAS unsigned char* lds, const GemmD g, const Epi& E, int G, int c) {
;     ...
;     const char* cA = PG8_APTR(cz, cpm); const char* cB = PG8_BPTR(cz, cpn);
;     PG8_STAGE(PG8_SB(0, 0), cB, voffB); PG8_STAGE(PG8_SB(0, 1), cB + hstepB, voffB); PG8_STAGE(PG8_SA(0, 0), cA, voffA); PG8_STAGE(PG8_SA(0, 1), cA + hstepA, voffA);
;     if (wr == 1) PG8_BAR;
;     PG8_WAIT_V(2); PG8_BAR;
;     PG8_STAGE(PG8_SB(1, 0), cB + kstep, voffB); PG8_STAGE(PG8_SA(1, 0), cA + kstep, voffA); PG8_STAGE(PG8_SB(1, 1), cB + hstepB + kstep, voffB);
;     PG8_WAIT_V(6); PG8_BAR;
;     __device__ __forceinline__ void preload(f32x4 (&acc)[2][2][4][2], int pm, int pn, int z, int wr, int wc, int fr, int fq) const {
;         const int row0 = pm * BM + wr * 64 + fr, col0 = pn * BM + wc * 32 + 8 * fq;
; #pragma unroll
;         for (int ai = 0; ai < 2; ++ai)
; #pragma unroll
;             for (int m = 0; m < 4; ++m) { const size_t off = (size_t)(row0 + ai * HALF + m * 16) * DM + col0;
; #pragma unroll
;                 for (int bj = 0; bj < 2; ++bj)
; #pragma unroll
;                     for (int n = 0; n < 2; ++n) acc[ai][bj][m][n] = *(const f32x4*)(xin + off + bj * HALF + 4 * n); }
	v_lshlrev_b64 v[2:3], 2, v[2:3]
	v_lshl_add_u64 v[6:7], s[56:57], 0, v[6:7]
	v_lshl_add_u64 v[4:5], v[4:5], 0, v[2:3]
	v_lshl_add_u64 v[6:7], v[6:7], 0, v[2:3]
	global_load_dwordx4 v[116:119], v[4:5], off offset:16
	global_load_dwordx4 v[124:127], v[4:5], off
	global_load_dwordx4 v[112:115], v[4:5], off offset:528
	global_load_dwordx4 v[120:123], v[4:5], off offset:512
	global_load_dwordx4 v[96:99], v[6:7], off offset:16
	global_load_dwordx4 v[104:107], v[6:7], off
	global_load_dwordx4 v[100:103], v[6:7], off offset:528
	global_load_dwordx4 v[108:111], v[6:7], off offset:512
	v_or_b32_e32 v6, 32, v0
	v_or_b32_e32 v0, 48, v0
	v_ashrrev_i32_e32 v7, 31, v6
	v_ashrrev_i32_e32 v1, 31, v0
	v_lshlrev_b64 v[6:7], 13, v[6:7]
	v_lshlrev_b64 v[0:1], 13, v[0:1]
	v_lshl_add_u64 v[6:7], s[56:57], 0, v[6:7]
	v_lshl_add_u64 v[0:1], s[56:57], 0, v[0:1]
	s_mov_b32 s6, 0x100000
	v_lshl_add_u64 v[6:7], v[6:7], 0, v[2:3]
	v_lshl_add_u64 v[0:1], v[0:1], 0, v[2:3]
	v_add_co_u32_e32 v2, vcc, s6, v4
	s_mov_b64 s[10:11], 0x100000
	s_nop 0
	v_addc_co_u32_e32 v3, vcc, 0, v5, vcc
	s_mov_b32 s6, 0x120000
	global_load_dwordx4 v[80:83], v[6:7], off offset:16
	global_load_dwordx4 v[88:91], v[6:7], off
	global_load_dwordx4 v[84:87], v[6:7], off offset:528
	global_load_dwordx4 v[92:95], v[6:7], off offset:512
	global_load_dwordx4 v[64:67], v[0:1], off offset:16
	global_load_dwordx4 v[72:75], v[0:1], off
	global_load_dwordx4 v[68:71], v[0:1], off offset:528
	global_load_dwordx4 v[76:79], v[0:1], off offset:512
	v_lshl_add_u64 v[0:1], v[4:5], 0, s[10:11]
	global_load_dwordx4 v[52:55], v[2:3], off
	global_load_dwordx4 v[48:51], v[0:1], off offset:528
	global_load_dwordx4 v[56:59], v[0:1], off offset:16
	global_load_dwordx4 v[60:63], v[0:1], off offset:512
	v_add_co_u32_e32 v2, vcc, s6, v4
	s_mov_b64 s[10:11], 0x120000
	s_nop 0
	v_addc_co_u32_e32 v3, vcc, 0, v5, vcc
	s_mov_b32 s6, 0x140000
	v_lshl_add_u64 v[0:1], v[4:5], 0, s[10:11]
	global_load_dwordx4 v[40:43], v[2:3], off
	global_load_dwordx4 v[36:39], v[0:1], off offset:528
	global_load_dwordx4 v[32:35], v[0:1], off offset:16
	global_load_dwordx4 v[44:47], v[0:1], off offset:512
	s_mov_b64 s[10:11], 0x140000
	v_add_co_u32_e32 v2, vcc, s6, v4
	v_lshl_add_u64 v[0:1], v[4:5], 0, s[10:11]
	s_nop 0
	v_addc_co_u32_e32 v3, vcc, 0, v5, vcc
	s_mov_b32 s6, 0x160000
	v_readlane_b32 s9, v239, 22
	s_lshl_b32 s2, s2, 10
	global_load_dwordx4 v[20:23], v[2:3], off
	global_load_dwordx4 v[24:27], v[0:1], off offset:528
	global_load_dwordx4 v[16:19], v[0:1], off offset:16
	global_load_dwordx4 v[28:31], v[0:1], off offset:512
	v_add_co_u32_e32 v0, vcc, s6, v4
	s_mul_i32 s6, s9, 0x2c0000
	s_add_u32 s88, s60, s6
	s_mul_hi_i32 s6, s9, 0x2c0000
	s_mov_b64 s[10:11], 0x160000
	s_addc_u32 s89, s61, s6
	s_add_i32 s6, s2, 0
	v_lshl_add_u64 v[12:13], v[4:5], 0, s[10:11]
	v_addc_co_u32_e32 v1, vcc, 0, v5, vcc
	s_add_i32 m0, s6, 0x10000
	global_load_dwordx4 v[4:7], v[0:1], off
	global_load_dwordx4 v[8:11], v[12:13], off offset:528
	s_nop 0
	global_load_dwordx4 v[0:3], v[12:13], off offset:16
	s_nop 0
	global_load_dwordx4 v[12:15], v[12:13], off offset:512
	v_mov_b32_e32 v129, v179
	global_load_lds_dwordx4 v178, s[88:89]
	s_add_i32 m0, s6, 0x12000
	s_add_u32 s10, s88, 0x160000
	global_load_lds_dwordx4 v128, s[88:89]
	s_addc_u32 s11, s89, 0
	s_add_i32 m0, s6, 0x14000
	v_mov_b32_e32 v133, v179
	global_load_lds_dwordx4 v178, s[10:11]
	s_add_i32 m0, s6, 0x16000
	v_mov_b32_e32 v131, v179
	global_load_lds_dwordx4 v128, s[10:11]
	v_readlane_b32 s10, v239, 28
	s_mul_i32 s9, s10, 0x2c0000
	s_add_u32 s46, s62, s9
	s_mul_hi_i32 s9, s10, 0x2c0000
	s_addc_u32 s47, s63, s9
	s_add_i32 s9, s6, 0x2000
	s_mov_b32 m0, s6
	s_add_u32 s16, s46, 0x160000
	v_readlane_b32 s11, v239, 29
	global_load_lds_dwordx4 v132, s[46:47]
	s_mov_b32 m0, s9
	s_addc_u32 s17, s47, 0
	s_add_i32 s10, s6, 0x4000
	global_load_lds_dwordx4 v130, s[46:47]
	s_mov_b32 m0, s10
	s_add_i32 s11, s6, 0x6000
	global_load_lds_dwordx4 v132, s[16:17]
	s_mov_b32 m0, s11
	s_cmp_eq_u32 s22, 1
	global_load_lds_dwordx4 v130, s[16:17]
	v_lshl_add_u64 v[140:141], s[88:89], 0, v[178:179]
	v_lshl_add_u64 v[138:139], s[88:89], 0, v[128:129]
	v_lshl_add_u64 v[134:135], s[46:47], 0, v[132:133]
	s_cselect_b64 s[66:67], -1, 0
	s_cmp_lg_u32 s22, 1
	v_lshl_add_u64 v[136:137], s[46:47], 0, v[130:131]
	s_cbranch_scc1 .LBB0_92
	s_barrier

; #define PG8_BAR __builtin_amdgcn_s_barrier()
; #define PG8_PIN_ACC() do { _Pragma("unroll") for (int a = 0; a < 2; ++a) _Pragma("unroll") for (int b = 0; b < 2; ++b) _Pragma("unroll") for (int m = 0; m < 4; ++m) \
;         asm volatile("" : "+v"(acc[a][b][m][0]), "+v"(acc[a][b][m][1])); } while (0)
; template <class Epi>
; __device__ __forceinline__ void gemm_phase(LAS unsigned char* lds, const GemmD g, const Epi& E, int G, int c) {
;     ...
;         if (!has_next) break;
;         if constexpr (Epi::PRELOAD) { E.preload(acc, npm, npn, nz, wr, wc, fr, fq); PG8_PIN_ACC(); }
;         else {
; #pragma unroll
;         for (int a = 0; a < 2; ++a)
; #pragma unroll
;             for (int b = 0; b < 2; ++b)
; #pragma unroll
;                 for (int m = 0; m < 4; ++m)
; #pragma unroll
;                     for (int n = 0; n < 2; ++n) acc[a][b][m][n] = (f32x4){0.f, 0.f, 0.f, 0.f};
;         }
;         cpm = npm; cpn = npn; cz = nz; cA = nA; cB = nB; ++ui;
;         if (wr == 1) PG8_BAR;
.LBB0_198:
	s_mov_b32 s99, 1
	s_andn2_b64 vcc, exec, s[4:5]
	s_mov_b32 s23, s64
	s_mov_b32 s22, s66
	s_mov_b64 s[86:87], s[84:85]
	s_mov_b64 s[42:43], s[82:83]
	s_cbranch_vccz .LBB0_208

; #define PG8_STAGE(bufoff, gbase, voff) do { _Pragma("unroll") for (int _i = 0; _i < 2; ++_i) \
;         __builtin_amdgcn_global_load_lds((const unsigned*)((const char*)(gbase) + (voff)[_i]), (LAS unsigned*)(lds + (bufoff) + ldsw + _i * 8192), 16, 0, 0); } while (0)
; #define PG8_LDA(dst, b, h) do { _Pragma("unroll") for (int m = 0; m < 4; ++m) _Pragma("unroll") for (int k = 0; k < 2; ++k) dst[m][k] = *(const LAS bf16x8*)(lds + PG8_SA(b, h) + aoff + m * 2048 + k * 1024); } while (0)
; #define PG8_LDB(dst, b, h) do { _Pragma("unroll") for (int n = 0; n < 2; ++n) _Pragma("unroll") for (int k = 0; k < 2; ++k) dst[n][k] = *(const LAS bf16x8*)(lds + PG8_SB(b, h) + boff + n * 2048 + k * 1024); } while (0)
; #define PG8_MMA(ai, bj, At, Bt) do { __builtin_amdgcn_s_setprio(1); _Pragma("unroll") for (int m = 0; m < 4; ++m) _Pragma("unroll") for (int n = 0; n < 2; ++n) _Pragma("unroll") for (int k = 0; k < 2; ++k) \
;         acc[ai][bj][m][n] = __builtin_amdgcn_mfma_f32_16x16x32_bf16(Bt[n][k], At[m][k], acc[ai][bj][m][n], 0, 0, 0); __builtin_amdgcn_s_setprio(0); } while (0)
; #define PG8_WAIT_V(n) asm volatile("s_waitcnt vmcnt(" #n ")" ::: "memory")
; #define PG8_WAIT_L(n) asm volatile("s_waitcnt lgkmcnt(" #n ")" ::: "memory")
; #define PG8_BAR __builtin_amdgcn_s_barrier()
; #define PG8_SCHED __builtin_amdgcn_sched_barrier(0)
; template <class Epi>
; __device__ __forceinline__ void gemm_phase(LAS unsigned char* lds, const GemmD g, const Epi& E, int G, int c) {
;     ...
;         for (int t = 0; t < nt; t += 2) {
;             const bool last = (t == nt - 2);
;             const char* a1 = cA + (size_t)(t + 1) * kstep;
;             const char* a2 = last ? nA : cA + (size_t)(t + 2) * kstep; const char* b2 = last ? nB : cB + (size_t)(t + 2) * kstep;
;             const char* a3 = a2 + kstep; const char* b3 = b2 + kstep;
;             PG8_LDB(B0, 0, 0); PG8_LDB(B1, 0, 1); PG8_SCHED; PG8_LDA(At, 0, 0); PG8_STAGE(PG8_SA(1, 1), a1 + hstepA, voffA);
;             PG8_WAIT_V(8); PG8_WAIT_L(0); PG8_BAR; PG8_MMA(0, 0, At, B0); PG8_MMA(0, 1, At, B1); PG8_BAR; PG8_SCHED;
;             PG8_LDA(At, 0, 1); PG8_STAGE(PG8_SB(0, 0), b2, voffB); PG8_STAGE(PG8_SB(0, 1), b2 + hstepB, voffB); PG8_STAGE(PG8_SA(0, 0), a2, voffA);
;             PG8_WAIT_V(8); PG8_WAIT_L(0); PG8_BAR; PG8_MMA(1, 0, At, B0); PG8_MMA(1, 1, At, B1); PG8_BAR; PG8_SCHED;
.LBB0_202:
	s_add_u32 s4, s42, 0xfff80080
	s_addc_u32 s5, s43, -1
	s_add_i32 s35, 0, 0x10000
	s_cmp_eq_u32 s33, 28
	s_cselect_b32 s5, s26, s5
	s_cselect_b32 s4, s27, s4
	v_add_u32_e32 v142, s35, v145
	s_cselect_b32 s87, s28, s31
	s_cselect_b32 s86, s29, s30
	s_add_i32 s36, 0, 0x14000
	ds_read_b128 v[138:141], v142
	ds_read_b128 v[152:155], v142 offset:1024
	ds_read_b128 v[156:159], v142 offset:2048
	ds_read_b128 v[160:163], v142 offset:3072
	v_add_u32_e32 v142, s36, v145
	ds_read_b128 v[164:167], v142
	ds_read_b128 v[168:171], v142 offset:1024
	ds_read_b128 v[172:175], v142 offset:2048
	ds_read_b128 v[180:183], v142 offset:3072
	v_lshl_add_u64 v[146:147], s[42:43], 0, v[134:135]
	s_add_i32 m0, s6, 0xc000
	ds_read_b128 v[184:187], v151
	ds_read_b128 v[188:191], v151 offset:1024
	ds_read_b128 v[192:195], v151 offset:2048
	ds_read_b128 v[210:213], v151 offset:3072
	ds_read_b128 v[214:217], v151 offset:4096
	ds_read_b128 v[218:221], v151 offset:5120
	ds_read_b128 v[222:225], v151 offset:6144
	ds_read_b128 v[226:229], v151 offset:7168
	global_load_lds_dwordx4 v[146:147], off
	v_lshl_add_u64 v[146:147], s[42:43], 0, v[136:137]
	s_add_i32 m0, s6, 0xe000
	s_nop 0
	global_load_lds_dwordx4 v[146:147], off
	s_cmp_lg_u32 s99, 0
	s_cbranch_scc1 .Lrw_FfnUp_0_r
	s_waitcnt vmcnt(8)
	s_branch .Lrw_FfnUp_0_d
.Lrw_FfnUp_0_r:
	s_waitcnt vmcnt(16)
.Lrw_FfnUp_0_d:
	s_waitcnt lgkmcnt(0)
	s_barrier
	s_setprio 1
	s_waitcnt lgkmcnt(0)
	v_mfma_f32_16x16x32_bf16 v[124:127], v[138:141], v[184:187], v[124:127]
	v_mfma_f32_16x16x32_bf16 v[116:119], v[156:159], v[184:187], v[116:119]
	v_mfma_f32_16x16x32_bf16 v[108:111], v[138:141], v[192:195], v[108:111]
	v_mfma_f32_16x16x32_bf16 v[100:103], v[156:159], v[192:195], v[100:103]
	v_mfma_f32_16x16x32_bf16 v[92:95], v[138:141], v[214:217], v[92:95]
	v_mfma_f32_16x16x32_bf16 v[84:87], v[156:159], v[214:217], v[84:87]
	v_mfma_f32_16x16x32_bf16 v[76:79], v[138:141], v[222:225], v[76:79]
	v_mfma_f32_16x16x32_bf16 v[68:71], v[156:159], v[222:225], v[68:71]
	v_mfma_f32_16x16x32_bf16 v[124:127], v[152:155], v[188:191], v[124:127]
	v_mfma_f32_16x16x32_bf16 v[116:119], v[160:163], v[188:191], v[116:119]
	v_mfma_f32_16x16x32_bf16 v[108:111], v[152:155], v[210:213], v[108:111]
	v_mfma_f32_16x16x32_bf16 v[100:103], v[160:163], v[210:213], v[100:103]
	v_mfma_f32_16x16x32_bf16 v[92:95], v[152:155], v[218:221], v[92:95]
	v_mfma_f32_16x16x32_bf16 v[84:87], v[160:163], v[218:221], v[84:87]
	v_mfma_f32_16x16x32_bf16 v[76:79], v[152:155], v[226:229], v[76:79]
	v_mfma_f32_16x16x32_bf16 v[68:71], v[160:163], v[226:229], v[68:71]
	s_setprio 0
	s_setprio 1
	v_mfma_f32_16x16x32_bf16 v[120:123], v[164:167], v[184:187], v[120:123]
	v_mfma_f32_16x16x32_bf16 v[112:115], v[172:175], v[184:187], v[112:115]
	v_mfma_f32_16x16x32_bf16 v[104:107], v[164:167], v[192:195], v[104:107]
	v_mfma_f32_16x16x32_bf16 v[96:99], v[172:175], v[192:195], v[96:99]
	v_mfma_f32_16x16x32_bf16 v[88:91], v[164:167], v[214:217], v[88:91]
	v_mfma_f32_16x16x32_bf16 v[80:83], v[172:175], v[214:217], v[80:83]
	v_mfma_f32_16x16x32_bf16 v[72:75], v[164:167], v[222:225], v[72:75]
	v_mfma_f32_16x16x32_bf16 v[64:67], v[172:175], v[222:225], v[64:67]
	v_mfma_f32_16x16x32_bf16 v[120:123], v[168:171], v[188:191], v[120:123]
	v_mfma_f32_16x16x32_bf16 v[112:115], v[180:183], v[188:191], v[112:115]
	v_mfma_f32_16x16x32_bf16 v[104:107], v[168:171], v[210:213], v[104:107]
	v_mfma_f32_16x16x32_bf16 v[96:99], v[180:183], v[210:213], v[96:99]
	v_mfma_f32_16x16x32_bf16 v[88:91], v[168:171], v[218:221], v[88:91]
	v_mfma_f32_16x16x32_bf16 v[80:83], v[180:183], v[218:221], v[80:83]
	v_mfma_f32_16x16x32_bf16 v[72:75], v[168:171], v[226:229], v[72:75]
	v_mfma_f32_16x16x32_bf16 v[64:67], v[180:183], v[226:229], v[64:67]
	s_setprio 0
	s_barrier
	s_add_i32 s35, s35, s2
	v_lshl_add_u64 v[146:147], s[86:87], 0, v[178:179]
	s_mov_b32 m0, s35
	ds_read_b128 v[184:187], v151 offset:16384
	ds_read_b128 v[188:191], v151 offset:17408
	ds_read_b128 v[192:195], v151 offset:18432
	ds_read_b128 v[210:213], v151 offset:19456
	ds_read_b128 v[214:217], v151 offset:20480
	ds_read_b128 v[218:221], v151 offset:21504
	ds_read_b128 v[222:225], v151 offset:22528
	ds_read_b128 v[226:229], v151 offset:23552
	global_load_lds_dwordx4 v[146:147], off
	s_add_i32 m0, s35, 0x2000
	s_add_u32 s38, s86, 0x80000
	v_lshl_add_u64 v[198:199], s[86:87], 0, v[128:129]
	s_addc_u32 s39, s87, 0
	s_add_i32 s35, s36, s2
	global_load_lds_dwordx4 v[198:199], off
	v_lshl_add_u64 v[230:231], s[38:39], 0, v[178:179]
	s_mov_b32 m0, s35
	v_lshl_add_u64 v[232:233], s[4:5], 0, v[130:131]
	global_load_lds_dwordx4 v[230:231], off
	v_lshl_add_u64 v[230:231], s[38:39], 0, v[128:129]
	s_add_i32 m0, s35, 0x2000
	s_nop 0
	global_load_lds_dwordx4 v[230:231], off
	v_lshl_add_u64 v[230:231], s[4:5], 0, v[132:133]
	s_mov_b32 m0, s6
	s_nop 0
	global_load_lds_dwordx4 v[230:231], off
	s_mov_b32 m0, s9
	s_nop 0
	global_load_lds_dwordx4 v[232:233], off
	s_cmp_lg_u32 s99, 0
	s_cbranch_scc1 .Lrw_FfnUp_1_r
	s_waitcnt vmcnt(8)
	s_branch .Lrw_FfnUp_1_d
.Lrw_FfnUp_1_r:
	s_waitcnt vmcnt(16)
	s_mov_b32 s99, 0
; #define PG8_STAGE(bufoff, gbase, voff) do { _Pragma("unroll") for (int _i = 0; _i < 2; ++_i) \
;         __builtin_amdgcn_global_load_lds((const unsigned*)((const char*)(gbase) + (voff)[_i]), (LAS unsigned*)(lds + (bufoff) + ldsw + _i * 8192), 16, 0, 0); } while (0)
; #define PG8_LDA(dst, b, h) do { _Pragma("unroll") for (int m = 0; m < 4; ++m) _Pragma("unroll") for (int k = 0; k < 2; ++k) dst[m][k] = *(const LAS bf16x8*)(lds + PG8_SA(b, h) + aoff + m * 2048 + k * 1024); } while (0)
; #define PG8_LDB(dst, b, h) do { _Pragma("unroll") for (int n = 0; n < 2; ++n) _Pragma("unroll") for (int k = 0; k < 2; ++k) dst[n][k] = *(const LAS bf16x8*)(lds + PG8_SB(b, h) + boff + n * 2048 + k * 1024); } while (0)
; #define PG8_MMA(ai, bj, At, Bt) do { __builtin_amdgcn_s_setprio(1); _Pragma("unroll") for (int m = 0; m < 4; ++m) _Pragma("unroll") for (int n = 0; n < 2; ++n) _Pragma("unroll") for (int k = 0; k < 2; ++k) \
;         acc[ai][bj][m][n] = __builtin_amdgcn_mfma_f32_16x16x32_bf16(Bt[n][k], At[m][k], acc[ai][bj][m][n], 0, 0, 0); __builtin_amdgcn_s_setprio(0); } while (0)
; #define PG8_WAIT_V(n) asm volatile("s_waitcnt vmcnt(" #n ")" ::: "memory")
; #define PG8_WAIT_L(n) asm volatile("s_waitcnt lgkmcnt(" #n ")" ::: "memory")
; #define PG8_BAR __builtin_amdgcn_s_barrier()
; #define PG8_SCHED __builtin_amdgcn_sched_barrier(0)
; template <class Epi>
; __device__ __forceinline__ void gemm_phase(LAS unsigned char* lds, const GemmD g, const Epi& E, int G, int c) {
;     ...
;             PG8_WAIT_V(8); PG8_WAIT_L(0); PG8_BAR; PG8_MMA(1, 0, At, B0); PG8_MMA(1, 1, At, B1); PG8_BAR; PG8_SCHED;
;             PG8_LDB(B0, 1, 0); PG8_LDB(B1, 1, 1); PG8_SCHED; PG8_LDA(At, 1, 0); PG8_STAGE(PG8_SA(0, 1), a2 + hstepA, voffA);
;             PG8_WAIT_V(8); PG8_WAIT_L(0); PG8_BAR; PG8_MMA(0, 0, At, B0); PG8_MMA(0, 1, At, B1); PG8_BAR; PG8_SCHED;
.Lrw_FfnUp_1_d:
	s_waitcnt lgkmcnt(0)
	s_barrier
	s_setprio 1
	s_waitcnt lgkmcnt(0)
	v_mfma_f32_16x16x32_bf16 v[60:63], v[138:141], v[184:187], v[60:63]
	v_mfma_f32_16x16x32_bf16 v[52:55], v[156:159], v[184:187], v[52:55]
	v_mfma_f32_16x16x32_bf16 v[44:47], v[138:141], v[192:195], v[44:47]
	v_mfma_f32_16x16x32_bf16 v[36:39], v[156:159], v[192:195], v[36:39]
	v_mfma_f32_16x16x32_bf16 v[28:31], v[138:141], v[214:217], v[28:31]
	v_mfma_f32_16x16x32_bf16 v[20:23], v[156:159], v[214:217], v[20:23]
	v_mfma_f32_16x16x32_bf16 v[12:15], v[138:141], v[222:225], v[12:15]
	v_mfma_f32_16x16x32_bf16 v[4:7], v[156:159], v[222:225], v[4:7]
	v_mfma_f32_16x16x32_bf16 v[60:63], v[152:155], v[188:191], v[60:63]
	v_mfma_f32_16x16x32_bf16 v[52:55], v[160:163], v[188:191], v[52:55]
	v_mfma_f32_16x16x32_bf16 v[44:47], v[152:155], v[210:213], v[44:47]
	v_mfma_f32_16x16x32_bf16 v[36:39], v[160:163], v[210:213], v[36:39]
	v_mfma_f32_16x16x32_bf16 v[28:31], v[152:155], v[218:221], v[28:31]
	v_mfma_f32_16x16x32_bf16 v[20:23], v[160:163], v[218:221], v[20:23]
	v_mfma_f32_16x16x32_bf16 v[12:15], v[152:155], v[226:229], v[12:15]
	v_mfma_f32_16x16x32_bf16 v[4:7], v[160:163], v[226:229], v[4:7]
	s_setprio 0
	s_setprio 1
	v_mfma_f32_16x16x32_bf16 v[56:59], v[164:167], v[184:187], v[56:59]
	v_mfma_f32_16x16x32_bf16 v[48:51], v[172:175], v[184:187], v[48:51]
	v_mfma_f32_16x16x32_bf16 v[40:43], v[164:167], v[192:195], v[40:43]
	v_mfma_f32_16x16x32_bf16 v[32:35], v[172:175], v[192:195], v[32:35]
	v_mfma_f32_16x16x32_bf16 v[24:27], v[164:167], v[214:217], v[24:27]
	v_mfma_f32_16x16x32_bf16 v[16:19], v[172:175], v[214:217], v[16:19]
	v_mfma_f32_16x16x32_bf16 v[8:11], v[164:167], v[222:225], v[8:11]
	v_mfma_f32_16x16x32_bf16 v[0:3], v[172:175], v[222:225], v[0:3]
	v_mfma_f32_16x16x32_bf16 v[56:59], v[168:171], v[188:191], v[56:59]
	v_mfma_f32_16x16x32_bf16 v[48:51], v[180:183], v[188:191], v[48:51]
	v_mfma_f32_16x16x32_bf16 v[40:43], v[168:171], v[210:213], v[40:43]
	v_mfma_f32_16x16x32_bf16 v[32:35], v[180:183], v[210:213], v[32:35]
	v_mfma_f32_16x16x32_bf16 v[24:27], v[168:171], v[218:221], v[24:27]
	v_mfma_f32_16x16x32_bf16 v[16:19], v[180:183], v[218:221], v[16:19]
	v_mfma_f32_16x16x32_bf16 v[8:11], v[168:171], v[226:229], v[8:11]
	v_mfma_f32_16x16x32_bf16 v[0:3], v[180:183], v[226:229], v[0:3]
	s_setprio 0
	s_barrier
	s_add_i32 s35, 0, 0x18000
	v_add_u32_e32 v142, s35, v145
	s_add_i32 s36, 0, 0x1c000
	ds_read_b128 v[138:141], v142
	ds_read_b128 v[152:155], v142 offset:1024
	ds_read_b128 v[156:159], v142 offset:2048
	ds_read_b128 v[160:163], v142 offset:3072
	v_add_u32_e32 v142, s36, v145
	ds_read_b128 v[164:167], v142
	ds_read_b128 v[168:171], v142 offset:1024
	ds_read_b128 v[172:175], v142 offset:2048
	ds_read_b128 v[180:183], v142 offset:3072
	s_add_u32 s4, s4, 0x80000
	s_addc_u32 s5, s5, 0
	s_mov_b32 m0, s10
	v_lshl_add_u64 v[234:235], s[4:5], 0, v[132:133]
	ds_read_b128 v[184:187], v151 offset:32768
	ds_read_b128 v[188:191], v151 offset:33792
	ds_read_b128 v[192:195], v151 offset:34816
	ds_read_b128 v[210:213], v151 offset:35840
	ds_read_b128 v[214:217], v151 offset:36864
	ds_read_b128 v[218:221], v151 offset:37888
	ds_read_b128 v[222:225], v151 offset:38912
	ds_read_b128 v[226:229], v151 offset:39936
	global_load_lds_dwordx4 v[234:235], off
	v_lshl_add_u64 v[234:235], s[4:5], 0, v[130:131]
	s_mov_b32 m0, s11
	s_nop 0
	global_load_lds_dwordx4 v[234:235], off
	s_waitcnt vmcnt(8)
	s_waitcnt lgkmcnt(0)
	s_barrier
	s_setprio 1
	s_waitcnt lgkmcnt(0)
	v_mfma_f32_16x16x32_bf16 v[124:127], v[138:141], v[184:187], v[124:127]
	v_mfma_f32_16x16x32_bf16 v[116:119], v[156:159], v[184:187], v[116:119]
	v_mfma_f32_16x16x32_bf16 v[108:111], v[138:141], v[192:195], v[108:111]
	v_mfma_f32_16x16x32_bf16 v[100:103], v[156:159], v[192:195], v[100:103]
	v_mfma_f32_16x16x32_bf16 v[92:95], v[138:141], v[214:217], v[92:95]
	v_mfma_f32_16x16x32_bf16 v[84:87], v[156:159], v[214:217], v[84:87]
	v_mfma_f32_16x16x32_bf16 v[76:79], v[138:141], v[222:225], v[76:79]
	v_mfma_f32_16x16x32_bf16 v[68:71], v[156:159], v[222:225], v[68:71]
	v_mfma_f32_16x16x32_bf16 v[124:127], v[152:155], v[188:191], v[124:127]
	v_mfma_f32_16x16x32_bf16 v[116:119], v[160:163], v[188:191], v[116:119]
	v_mfma_f32_16x16x32_bf16 v[108:111], v[152:155], v[210:213], v[108:111]
	v_mfma_f32_16x16x32_bf16 v[100:103], v[160:163], v[210:213], v[100:103]
	v_mfma_f32_16x16x32_bf16 v[92:95], v[152:155], v[218:221], v[92:95]
	v_mfma_f32_16x16x32_bf16 v[84:87], v[160:163], v[218:221], v[84:87]
	v_mfma_f32_16x16x32_bf16 v[76:79], v[152:155], v[226:229], v[76:79]
	v_mfma_f32_16x16x32_bf16 v[68:71], v[160:163], v[226:229], v[68:71]
	s_setprio 0
	s_setprio 1
	v_mfma_f32_16x16x32_bf16 v[120:123], v[164:167], v[184:187], v[120:123]
	v_mfma_f32_16x16x32_bf16 v[112:115], v[172:175], v[184:187], v[112:115]
	v_mfma_f32_16x16x32_bf16 v[104:107], v[164:167], v[192:195], v[104:107]
	v_mfma_f32_16x16x32_bf16 v[96:99], v[172:175], v[192:195], v[96:99]
	v_mfma_f32_16x16x32_bf16 v[88:91], v[164:167], v[214:217], v[88:91]
	v_mfma_f32_16x16x32_bf16 v[80:83], v[172:175], v[214:217], v[80:83]
	v_mfma_f32_16x16x32_bf16 v[72:75], v[164:167], v[222:225], v[72:75]
	v_mfma_f32_16x16x32_bf16 v[64:67], v[172:175], v[222:225], v[64:67]
	v_mfma_f32_16x16x32_bf16 v[120:123], v[168:171], v[188:191], v[120:123]
	v_mfma_f32_16x16x32_bf16 v[112:115], v[180:183], v[188:191], v[112:115]
	v_mfma_f32_16x16x32_bf16 v[104:107], v[168:171], v[210:213], v[104:107]
	v_mfma_f32_16x16x32_bf16 v[96:99], v[180:183], v[210:213], v[96:99]
	v_mfma_f32_16x16x32_bf16 v[88:91], v[168:171], v[218:221], v[88:91]
	v_mfma_f32_16x16x32_bf16 v[80:83], v[180:183], v[218:221], v[80:83]
	v_mfma_f32_16x16x32_bf16 v[72:75], v[168:171], v[226:229], v[72:75]
	v_mfma_f32_16x16x32_bf16 v[64:67], v[180:183], v[226:229], v[64:67]
	s_setprio 0
	s_barrier
; #define PG8_STAGE(bufoff, gbase, voff) do { _Pragma("unroll") for (int _i = 0; _i < 2; ++_i) \
;         __builtin_amdgcn_global_load_lds((const unsigned*)((const char*)(gbase) + (voff)[_i]), (LAS unsigned*)(lds + (bufoff) + ldsw + _i * 8192), 16, 0, 0); } while (0)
; #define PG8_LDA(dst, b, h) do { _Pragma("unroll") for (int m = 0; m < 4; ++m) _Pragma("unroll") for (int k = 0; k < 2; ++k) dst[m][k] = *(const LAS bf16x8*)(lds + PG8_SA(b, h) + aoff + m * 2048 + k * 1024); } while (0)
; #define PG8_MMA(ai, bj, At, Bt) do { __builtin_amdgcn_s_setprio(1); _Pragma("unroll") for (int m = 0; m < 4; ++m) _Pragma("unroll") for (int n = 0; n < 2; ++n) _Pragma("unroll") for (int k = 0; k < 2; ++k) \
;         acc[ai][bj][m][n] = __builtin_amdgcn_mfma_f32_16x16x32_bf16(Bt[n][k], At[m][k], acc[ai][bj][m][n], 0, 0, 0); __builtin_amdgcn_s_setprio(0); } while (0)
; #define PG8_WAIT_V(n) asm volatile("s_waitcnt vmcnt(" #n ")" ::: "memory")
; #define PG8_WAIT_L(n) asm volatile("s_waitcnt lgkmcnt(" #n ")" ::: "memory")
; #define PG8_BAR __builtin_amdgcn_s_barrier()
; #define PG8_SCHED __builtin_amdgcn_sched_barrier(0)
; template <class Epi>
; __device__ __forceinline__ void gemm_phase(LAS unsigned char* lds, const GemmD g, const Epi& E, int G, int c) {
;     ...
;             PG8_LDA(At, 1, 1); PG8_STAGE(PG8_SB(1, 0), b3, voffB); PG8_STAGE(PG8_SB(1, 1), b3 + hstepB, voffB); PG8_STAGE(PG8_SA(1, 0), a3, voffA);
;             PG8_WAIT_V(8); PG8_WAIT_L(0); PG8_BAR; PG8_MMA(1, 0, At, B0); PG8_MMA(1, 1, At, B1); PG8_BAR; PG8_SCHED;
;         }
;         if (wr == 0) PG8_BAR;
	s_add_i32 s4, s35, s2
	v_lshl_add_u64 v[146:147], v[146:147], 0, s[48:49]
	s_mov_b32 m0, s4
	ds_read_b128 v[184:187], v151 offset:49152
	ds_read_b128 v[188:191], v151 offset:50176
	ds_read_b128 v[192:195], v151 offset:51200
	ds_read_b128 v[210:213], v151 offset:52224
	ds_read_b128 v[214:217], v151 offset:53248
	ds_read_b128 v[218:221], v151 offset:54272
	ds_read_b128 v[222:225], v151 offset:55296
	ds_read_b128 v[226:229], v151 offset:56320
	global_load_lds_dwordx4 v[146:147], off
	s_add_i32 m0, s4, 0x2000
	s_add_u32 s4, s86, 0x80080
	v_lshl_add_u64 v[146:147], v[198:199], 0, s[48:49]
	s_addc_u32 s5, s87, 0
	s_add_i32 s35, s36, s2
	global_load_lds_dwordx4 v[146:147], off
	v_lshl_add_u64 v[146:147], s[4:5], 0, v[178:179]
	s_mov_b32 m0, s35
	s_nop 0
	global_load_lds_dwordx4 v[146:147], off
	v_lshl_add_u64 v[146:147], s[4:5], 0, v[128:129]
	s_add_i32 m0, s35, 0x2000
	s_nop 0
	global_load_lds_dwordx4 v[146:147], off
	v_lshl_add_u64 v[146:147], v[230:231], 0, s[48:49]
	s_mov_b32 m0, s16
	s_nop 0
	global_load_lds_dwordx4 v[146:147], off
	v_lshl_add_u64 v[146:147], v[232:233], 0, s[48:49]
	s_mov_b32 m0, s17
	s_nop 0
	global_load_lds_dwordx4 v[146:147], off
	s_waitcnt vmcnt(8)
	s_waitcnt lgkmcnt(0)
	s_barrier
	s_setprio 1
	s_waitcnt lgkmcnt(0)
	v_mfma_f32_16x16x32_bf16 v[60:63], v[138:141], v[184:187], v[60:63]
	v_mfma_f32_16x16x32_bf16 v[52:55], v[156:159], v[184:187], v[52:55]
	v_mfma_f32_16x16x32_bf16 v[44:47], v[138:141], v[192:195], v[44:47]
	v_mfma_f32_16x16x32_bf16 v[36:39], v[156:159], v[192:195], v[36:39]
	v_mfma_f32_16x16x32_bf16 v[28:31], v[138:141], v[214:217], v[28:31]
	v_mfma_f32_16x16x32_bf16 v[20:23], v[156:159], v[214:217], v[20:23]
	v_mfma_f32_16x16x32_bf16 v[12:15], v[138:141], v[222:225], v[12:15]
	v_mfma_f32_16x16x32_bf16 v[4:7], v[156:159], v[222:225], v[4:7]
	v_mfma_f32_16x16x32_bf16 v[60:63], v[152:155], v[188:191], v[60:63]
	v_mfma_f32_16x16x32_bf16 v[52:55], v[160:163], v[188:191], v[52:55]
	v_mfma_f32_16x16x32_bf16 v[44:47], v[152:155], v[210:213], v[44:47]
	v_mfma_f32_16x16x32_bf16 v[36:39], v[160:163], v[210:213], v[36:39]
	v_mfma_f32_16x16x32_bf16 v[28:31], v[152:155], v[218:221], v[28:31]
	v_mfma_f32_16x16x32_bf16 v[20:23], v[160:163], v[218:221], v[20:23]
	v_mfma_f32_16x16x32_bf16 v[12:15], v[152:155], v[226:229], v[12:15]
	v_mfma_f32_16x16x32_bf16 v[4:7], v[160:163], v[226:229], v[4:7]
	s_setprio 0
	s_setprio 1
	v_mfma_f32_16x16x32_bf16 v[56:59], v[164:167], v[184:187], v[56:59]
	v_mfma_f32_16x16x32_bf16 v[48:51], v[172:175], v[184:187], v[48:51]
	v_mfma_f32_16x16x32_bf16 v[40:43], v[164:167], v[192:195], v[40:43]
	v_mfma_f32_16x16x32_bf16 v[32:35], v[172:175], v[192:195], v[32:35]
	v_mfma_f32_16x16x32_bf16 v[24:27], v[164:167], v[214:217], v[24:27]
	v_mfma_f32_16x16x32_bf16 v[16:19], v[172:175], v[214:217], v[16:19]
	v_mfma_f32_16x16x32_bf16 v[8:11], v[164:167], v[222:225], v[8:11]
	v_mfma_f32_16x16x32_bf16 v[0:3], v[172:175], v[222:225], v[0:3]
	v_mfma_f32_16x16x32_bf16 v[56:59], v[168:171], v[188:191], v[56:59]
	v_mfma_f32_16x16x32_bf16 v[48:51], v[180:183], v[188:191], v[48:51]
	v_mfma_f32_16x16x32_bf16 v[40:43], v[168:171], v[210:213], v[40:43]
	v_mfma_f32_16x16x32_bf16 v[32:35], v[180:183], v[210:213], v[32:35]
	v_mfma_f32_16x16x32_bf16 v[24:27], v[168:171], v[218:221], v[24:27]
	v_mfma_f32_16x16x32_bf16 v[16:19], v[180:183], v[218:221], v[16:19]
	v_mfma_f32_16x16x32_bf16 v[8:11], v[168:171], v[226:229], v[8:11]
	v_mfma_f32_16x16x32_bf16 v[0:3], v[180:183], v[226:229], v[0:3]
	s_setprio 0
	s_barrier
	s_add_i32 s33, s33, 2
	s_add_u32 s42, s42, 0x100
	s_addc_u32 s43, s43, 0
	s_add_u32 s30, s30, 0x100
	s_addc_u32 s31, s31, 0
	s_cmp_gt_u32 s33, 29
	s_cbranch_scc0 .LBB0_202
	s_and_b64 vcc, exec, s[46:47]
	s_cbranch_vccz .LBB0_205
	s_barrier

; #define PG8_WAIT_V(n) asm volatile("s_waitcnt vmcnt(" #n ")" ::: "memory")
; #define PG8_BAR __builtin_amdgcn_s_barrier()
; template <class Epi>
; __device__ __forceinline__ void gemm_phase(LAS unsigned char* lds, const GemmD g, const Epi& E, int G, int c) {
;     ...
;     PG8_WAIT_V(0);
;     PG8_BAR;
.LBB0_208:
	s_mov_b32 s99, 0
	s_waitcnt vmcnt(0)
	s_barrier

; #define PG8_BAR __builtin_amdgcn_s_barrier()
; #define PG8_PIN_ACC() do { _Pragma("unroll") for (int a = 0; a < 2; ++a) _Pragma("unroll") for (int b = 0; b < 2; ++b) _Pragma("unroll") for (int m = 0; m < 4; ++m) \
;         asm volatile("" : "+v"(acc[a][b][m][0]), "+v"(acc[a][b][m][1])); } while (0)
; template <class Epi>
; __device__ __forceinline__ void gemm_phase(LAS unsigned char* lds, const GemmD g, const Epi& E, int G, int c) {
;     ...
;         if (!has_next) break;
;         if constexpr (Epi::PRELOAD) { E.preload(acc, npm, npn, nz, wr, wc, fr, fq); PG8_PIN_ACC(); }
;         else {
; #pragma unroll
;         for (int a = 0; a < 2; ++a)
; #pragma unroll
;             for (int b = 0; b < 2; ++b)
; #pragma unroll
;                 for (int m = 0; m < 4; ++m)
; #pragma unroll
;                     for (int n = 0; n < 2; ++n) acc[a][b][m][n] = (f32x4){0.f, 0.f, 0.f, 0.f};
;         }
;         cpm = npm; cpn = npn; cz = nz; cA = nA; cB = nB; ++ui;
;         if (wr == 1) PG8_BAR;
.LBB0_263:
	s_mov_b32 s99, 1
	s_andn2_b64 vcc, exec, s[4:5]
	s_mov_b32 s2, s62
	s_mov_b32 s6, s82
	s_mov_b64 s[88:89], s[86:87]
	s_mov_b64 s[42:43], s[84:85]
	s_cbranch_vccz .LBB0_277

; #define PG8_STAGE(bufoff, gbase, voff) do { _Pragma("unroll") for (int _i = 0; _i < 2; ++_i) \
;         __builtin_amdgcn_global_load_lds((const unsigned*)((const char*)(gbase) + (voff)[_i]), (LAS unsigned*)(lds + (bufoff) + ldsw + _i * 8192), 16, 0, 0); } while (0)
; #define PG8_LDA(dst, b, h) do { _Pragma("unroll") for (int m = 0; m < 4; ++m) _Pragma("unroll") for (int k = 0; k < 2; ++k) dst[m][k] = *(const LAS bf16x8*)(lds + PG8_SA(b, h) + aoff + m * 2048 + k * 1024); } while (0)
; #define PG8_LDB(dst, b, h) do { _Pragma("unroll") for (int n = 0; n < 2; ++n) _Pragma("unroll") for (int k = 0; k < 2; ++k) dst[n][k] = *(const LAS bf16x8*)(lds + PG8_SB(b, h) + boff + n * 2048 + k * 1024); } while (0)
; #define PG8_MMA(ai, bj, At, Bt) do { __builtin_amdgcn_s_setprio(1); _Pragma("unroll") for (int m = 0; m < 4; ++m) _Pragma("unroll") for (int n = 0; n < 2; ++n) _Pragma("unroll") for (int k = 0; k < 2; ++k) \
;         acc[ai][bj][m][n] = __builtin_amdgcn_mfma_f32_16x16x32_bf16(Bt[n][k], At[m][k], acc[ai][bj][m][n], 0, 0, 0); __builtin_amdgcn_s_setprio(0); } while (0)
; #define PG8_WAIT_V(n) asm volatile("s_waitcnt vmcnt(" #n ")" ::: "memory")
; #define PG8_WAIT_L(n) asm volatile("s_waitcnt lgkmcnt(" #n ")" ::: "memory")
; #define PG8_BAR __builtin_amdgcn_s_barrier()
; #define PG8_SCHED __builtin_amdgcn_sched_barrier(0)
; template <class Epi>
; __device__ __forceinline__ void gemm_phase(LAS unsigned char* lds, const GemmD g, const Epi& E, int G, int c) {
;     ...
;         for (int t = 0; t < nt; t += 2) {
;             const bool last = (t == nt - 2);
;             const char* a1 = cA + (size_t)(t + 1) * kstep;
;             const char* a2 = last ? nA : cA + (size_t)(t + 2) * kstep; const char* b2 = last ? nB : cB + (size_t)(t + 2) * kstep;
;             const char* a3 = a2 + kstep; const char* b3 = b2 + kstep;
;             PG8_LDB(B0, 0, 0); PG8_LDB(B1, 0, 1); PG8_SCHED; PG8_LDA(At, 0, 0); PG8_STAGE(PG8_SA(1, 1), a1 + hstepA, voffA);
;             PG8_WAIT_V(8); PG8_WAIT_L(0); PG8_BAR; PG8_MMA(0, 0, At, B0); PG8_MMA(0, 1, At, B1); PG8_BAR; PG8_SCHED;
;             PG8_LDA(At, 0, 1); PG8_STAGE(PG8_SB(0, 0), b2, voffB); PG8_STAGE(PG8_SB(0, 1), b2 + hstepB, voffB); PG8_STAGE(PG8_SA(0, 0), a2, voffA);
;             PG8_WAIT_V(8); PG8_WAIT_L(0); PG8_BAR; PG8_MMA(1, 0, At, B0); PG8_MMA(1, 1, At, B1); PG8_BAR; PG8_SCHED;
.LBB0_271:
	s_add_u32 s4, s42, 0xfff80080
	s_addc_u32 s5, s43, -1
	s_add_i32 s28, 0, 0x10000
	s_cmp_eq_u32 s27, 28
	s_cselect_b32 s5, s9, s5
	s_cselect_b32 s4, s10, s4
	s_cselect_b32 s89, s11, s22
	s_cselect_b32 s88, s17, s19
	s_add_i32 s31, 0, 0x14000
	v_add_u32_e32 v44, s28, v210
	v_add_u32_e32 v156, s31, v210
	ds_read_b128 v[24:27], v44
	ds_read_b128 v[28:31], v44 offset:1024
	ds_read_b128 v[36:39], v44 offset:2048
	ds_read_b128 v[44:47], v44 offset:3072
	ds_read_b128 v[144:147], v156
	ds_read_b128 v[148:151], v156 offset:1024
	ds_read_b128 v[152:155], v156 offset:2048
	ds_read_b128 v[156:159], v156 offset:3072
	v_lshl_add_u64 v[194:195], s[42:43], 0, v[186:187]
	s_add_i32 m0, s23, 0xc000
	ds_read_b128 v[160:163], v212
	ds_read_b128 v[164:167], v212 offset:1024
	ds_read_b128 v[168:171], v212 offset:2048
	ds_read_b128 v[172:175], v212 offset:3072
	ds_read_b128 v[190:193], v212 offset:4096
	ds_read_b128 v[214:217], v212 offset:5120
	ds_read_b128 v[218:221], v212 offset:6144
	ds_read_b128 v[222:225], v212 offset:7168
	global_load_lds_dwordx4 v[194:195], off
	v_lshl_add_u64 v[194:195], s[42:43], 0, v[188:189]
	s_add_i32 m0, s23, 0xe000
	s_nop 0
	global_load_lds_dwordx4 v[194:195], off
	s_cmp_lg_u32 s99, 0
	s_cbranch_scc1 .Lrw_Glu_0_r
	s_waitcnt vmcnt(8)
	s_branch .Lrw_Glu_0_d
.Lrw_Glu_0_r:
	s_waitcnt vmcnt(24)
.Lrw_Glu_0_d:
	s_waitcnt lgkmcnt(0)
	s_barrier
	s_setprio 1
	s_waitcnt lgkmcnt(0)
	v_mfma_f32_16x16x32_bf16 v[140:143], v[24:27], v[160:163], v[140:143]
	v_mfma_f32_16x16x32_bf16 v[136:139], v[36:39], v[160:163], v[136:139]
	v_mfma_f32_16x16x32_bf16 v[124:127], v[24:27], v[168:171], v[124:127]
	v_mfma_f32_16x16x32_bf16 v[120:123], v[36:39], v[168:171], v[120:123]
	v_mfma_f32_16x16x32_bf16 v[108:111], v[24:27], v[190:193], v[108:111]
	v_mfma_f32_16x16x32_bf16 v[104:107], v[36:39], v[190:193], v[104:107]
	v_mfma_f32_16x16x32_bf16 v[92:95], v[24:27], v[218:221], v[92:95]
	v_mfma_f32_16x16x32_bf16 v[88:91], v[36:39], v[218:221], v[88:91]
	v_mfma_f32_16x16x32_bf16 v[140:143], v[28:31], v[164:167], v[140:143]
	v_mfma_f32_16x16x32_bf16 v[136:139], v[44:47], v[164:167], v[136:139]
	v_mfma_f32_16x16x32_bf16 v[124:127], v[28:31], v[172:175], v[124:127]
	v_mfma_f32_16x16x32_bf16 v[120:123], v[44:47], v[172:175], v[120:123]
	v_mfma_f32_16x16x32_bf16 v[108:111], v[28:31], v[214:217], v[108:111]
	v_mfma_f32_16x16x32_bf16 v[104:107], v[44:47], v[214:217], v[104:107]
	v_mfma_f32_16x16x32_bf16 v[92:95], v[28:31], v[222:225], v[92:95]
	v_mfma_f32_16x16x32_bf16 v[88:91], v[44:47], v[222:225], v[88:91]
	s_setprio 0
	s_setprio 1
	v_mfma_f32_16x16x32_bf16 v[132:135], v[144:147], v[160:163], v[132:135]
	v_mfma_f32_16x16x32_bf16 v[128:131], v[152:155], v[160:163], v[128:131]
	v_mfma_f32_16x16x32_bf16 v[116:119], v[144:147], v[168:171], v[116:119]
	v_mfma_f32_16x16x32_bf16 v[112:115], v[152:155], v[168:171], v[112:115]
	v_mfma_f32_16x16x32_bf16 v[100:103], v[144:147], v[190:193], v[100:103]
	v_mfma_f32_16x16x32_bf16 v[96:99], v[152:155], v[190:193], v[96:99]
	v_mfma_f32_16x16x32_bf16 v[84:87], v[144:147], v[218:221], v[84:87]
	v_mfma_f32_16x16x32_bf16 v[80:83], v[152:155], v[218:221], v[80:83]
	v_mfma_f32_16x16x32_bf16 v[132:135], v[148:151], v[164:167], v[132:135]
	v_mfma_f32_16x16x32_bf16 v[128:131], v[156:159], v[164:167], v[128:131]
	v_mfma_f32_16x16x32_bf16 v[116:119], v[148:151], v[172:175], v[116:119]
	v_mfma_f32_16x16x32_bf16 v[112:115], v[156:159], v[172:175], v[112:115]
	v_mfma_f32_16x16x32_bf16 v[100:103], v[148:151], v[214:217], v[100:103]
	v_mfma_f32_16x16x32_bf16 v[96:99], v[156:159], v[214:217], v[96:99]
	v_mfma_f32_16x16x32_bf16 v[84:87], v[148:151], v[222:225], v[84:87]
	v_mfma_f32_16x16x32_bf16 v[80:83], v[156:159], v[222:225], v[80:83]
	s_setprio 0
	s_barrier
	s_add_i32 s28, s28, s16
	v_lshl_add_u64 v[194:195], s[88:89], 0, v[178:179]
	s_mov_b32 m0, s28
	ds_read_b128 v[160:163], v212 offset:16384
	ds_read_b128 v[164:167], v212 offset:17408
	ds_read_b128 v[168:171], v212 offset:18432
	ds_read_b128 v[172:175], v212 offset:19456
	ds_read_b128 v[190:193], v212 offset:20480
	ds_read_b128 v[214:217], v212 offset:21504
	ds_read_b128 v[218:221], v212 offset:22528
	ds_read_b128 v[222:225], v212 offset:23552
	global_load_lds_dwordx4 v[194:195], off
	s_add_i32 m0, s28, 0x2000
	s_add_u32 s28, s88, 0x80000
	v_lshl_add_u64 v[198:199], s[88:89], 0, v[180:181]
	s_addc_u32 s29, s89, 0
	s_add_i32 s31, s31, s16
	global_load_lds_dwordx4 v[198:199], off
	v_lshl_add_u64 v[226:227], s[28:29], 0, v[178:179]
	s_mov_b32 m0, s31
	v_lshl_add_u64 v[228:229], s[4:5], 0, v[182:183]
	global_load_lds_dwordx4 v[226:227], off
	v_lshl_add_u64 v[226:227], s[28:29], 0, v[180:181]
	s_add_i32 m0, s31, 0x2000
	s_nop 0
	global_load_lds_dwordx4 v[226:227], off
	v_lshl_add_u64 v[226:227], s[4:5], 0, v[184:185]
	s_mov_b32 m0, s23
	s_nop 0
	global_load_lds_dwordx4 v[226:227], off
	s_mov_b32 m0, s26
	s_nop 0
	global_load_lds_dwordx4 v[228:229], off
	s_cmp_lg_u32 s99, 0
	s_cbranch_scc1 .Lrw_Glu_1_r
	s_waitcnt vmcnt(8)
	s_branch .Lrw_Glu_1_d
.Lrw_Glu_1_r:
	s_waitcnt vmcnt(24)
	s_mov_b32 s99, 0
; #define PG8_STAGE(bufoff, gbase, voff) do { _Pragma("unroll") for (int _i = 0; _i < 2; ++_i) \
;         __builtin_amdgcn_global_load_lds((const unsigned*)((const char*)(gbase) + (voff)[_i]), (LAS unsigned*)(lds + (bufoff) + ldsw + _i * 8192), 16, 0, 0); } while (0)
; #define PG8_LDA(dst, b, h) do { _Pragma("unroll") for (int m = 0; m < 4; ++m) _Pragma("unroll") for (int k = 0; k < 2; ++k) dst[m][k] = *(const LAS bf16x8*)(lds + PG8_SA(b, h) + aoff + m * 2048 + k * 1024); } while (0)
; #define PG8_LDB(dst, b, h) do { _Pragma("unroll") for (int n = 0; n < 2; ++n) _Pragma("unroll") for (int k = 0; k < 2; ++k) dst[n][k] = *(const LAS bf16x8*)(lds + PG8_SB(b, h) + boff + n * 2048 + k * 1024); } while (0)
; #define PG8_MMA(ai, bj, At, Bt) do { __builtin_amdgcn_s_setprio(1); _Pragma("unroll") for (int m = 0; m < 4; ++m) _Pragma("unroll") for (int n = 0; n < 2; ++n) _Pragma("unroll") for (int k = 0; k < 2; ++k) \
;         acc[ai][bj][m][n] = __builtin_amdgcn_mfma_f32_16x16x32_bf16(Bt[n][k], At[m][k], acc[ai][bj][m][n], 0, 0, 0); __builtin_amdgcn_s_setprio(0); } while (0)
; #define PG8_WAIT_V(n) asm volatile("s_waitcnt vmcnt(" #n ")" ::: "memory")
; #define PG8_WAIT_L(n) asm volatile("s_waitcnt lgkmcnt(" #n ")" ::: "memory")
; #define PG8_BAR __builtin_amdgcn_s_barrier()
; #define PG8_SCHED __builtin_amdgcn_sched_barrier(0)
; template <class Epi>
; __device__ __forceinline__ void gemm_phase(LAS unsigned char* lds, const GemmD g, const Epi& E, int G, int c) {
;     ...
;             PG8_WAIT_V(8); PG8_WAIT_L(0); PG8_BAR; PG8_MMA(1, 0, At, B0); PG8_MMA(1, 1, At, B1); PG8_BAR; PG8_SCHED;
;             PG8_LDB(B0, 1, 0); PG8_LDB(B1, 1, 1); PG8_SCHED; PG8_LDA(At, 1, 0); PG8_STAGE(PG8_SA(0, 1), a2 + hstepA, voffA);
;             PG8_WAIT_V(8); PG8_WAIT_L(0); PG8_BAR; PG8_MMA(0, 0, At, B0); PG8_MMA(0, 1, At, B1); PG8_BAR; PG8_SCHED;
.Lrw_Glu_1_d:
	s_waitcnt lgkmcnt(0)
	s_barrier
	s_setprio 1
	s_waitcnt lgkmcnt(0)
	v_mfma_f32_16x16x32_bf16 v[76:79], v[24:27], v[160:163], v[76:79]
	v_mfma_f32_16x16x32_bf16 v[72:75], v[36:39], v[160:163], v[72:75]
	v_mfma_f32_16x16x32_bf16 v[60:63], v[24:27], v[168:171], v[60:63]
	v_mfma_f32_16x16x32_bf16 v[56:59], v[36:39], v[168:171], v[56:59]
	v_mfma_f32_16x16x32_bf16 v[40:43], v[24:27], v[190:193], v[40:43]
	v_mfma_f32_16x16x32_bf16 v[32:35], v[36:39], v[190:193], v[32:35]
	v_mfma_f32_16x16x32_bf16 v[12:15], v[24:27], v[218:221], v[12:15]
	v_mfma_f32_16x16x32_bf16 v[8:11], v[36:39], v[218:221], v[8:11]
	v_mfma_f32_16x16x32_bf16 v[76:79], v[28:31], v[164:167], v[76:79]
	v_mfma_f32_16x16x32_bf16 v[72:75], v[44:47], v[164:167], v[72:75]
	v_mfma_f32_16x16x32_bf16 v[60:63], v[28:31], v[172:175], v[60:63]
	v_mfma_f32_16x16x32_bf16 v[56:59], v[44:47], v[172:175], v[56:59]
	v_mfma_f32_16x16x32_bf16 v[40:43], v[28:31], v[214:217], v[40:43]
	v_mfma_f32_16x16x32_bf16 v[32:35], v[44:47], v[214:217], v[32:35]
	v_mfma_f32_16x16x32_bf16 v[12:15], v[28:31], v[222:225], v[12:15]
	v_mfma_f32_16x16x32_bf16 v[8:11], v[44:47], v[222:225], v[8:11]
	s_setprio 0
	s_setprio 1
	v_mfma_f32_16x16x32_bf16 v[20:23], v[144:147], v[190:193], v[20:23]
	v_mfma_f32_16x16x32_bf16 v[16:19], v[152:155], v[190:193], v[16:19]
	v_mfma_f32_16x16x32_bf16 v[4:7], v[144:147], v[218:221], v[4:7]
	v_mfma_f32_16x16x32_bf16 v[0:3], v[152:155], v[218:221], v[0:3]
	v_mfma_f32_16x16x32_bf16 v[24:27], v[144:147], v[160:163], v[68:71]
	v_mfma_f32_16x16x32_bf16 v[28:31], v[152:155], v[160:163], v[64:67]
	v_mfma_f32_16x16x32_bf16 v[36:39], v[144:147], v[168:171], v[52:55]
	v_mfma_f32_16x16x32_bf16 v[44:47], v[152:155], v[168:171], v[48:51]
	v_mfma_f32_16x16x32_bf16 v[20:23], v[148:151], v[214:217], v[20:23]
	v_mfma_f32_16x16x32_bf16 v[16:19], v[156:159], v[214:217], v[16:19]
	v_mfma_f32_16x16x32_bf16 v[4:7], v[148:151], v[222:225], v[4:7]
	v_mfma_f32_16x16x32_bf16 v[0:3], v[156:159], v[222:225], v[0:3]
	v_mfma_f32_16x16x32_bf16 v[24:27], v[148:151], v[164:167], v[24:27]
	v_mfma_f32_16x16x32_bf16 v[28:31], v[156:159], v[164:167], v[28:31]
	v_mfma_f32_16x16x32_bf16 v[36:39], v[148:151], v[172:175], v[36:39]
	v_mfma_f32_16x16x32_bf16 v[44:47], v[156:159], v[172:175], v[44:47]
	s_setprio 0
	s_barrier
	s_add_i32 s28, 0, 0x18000
	s_add_i32 s29, 0, 0x1c000
	v_add_u32_e32 v68, s28, v210
	v_add_u32_e32 v156, s29, v210
	ds_read_b128 v[48:51], v68
	ds_read_b128 v[52:55], v68 offset:1024
	ds_read_b128 v[64:67], v68 offset:2048
	ds_read_b128 v[68:71], v68 offset:3072
	ds_read_b128 v[144:147], v156
	ds_read_b128 v[148:151], v156 offset:1024
	ds_read_b128 v[152:155], v156 offset:2048
	ds_read_b128 v[156:159], v156 offset:3072
	s_add_u32 s4, s4, 0x80000
	s_addc_u32 s5, s5, 0
	s_mov_b32 m0, s30
	v_lshl_add_u64 v[230:231], s[4:5], 0, v[184:185]
	ds_read_b128 v[160:163], v212 offset:32768
	ds_read_b128 v[164:167], v212 offset:33792
	ds_read_b128 v[168:171], v212 offset:34816
	ds_read_b128 v[172:175], v212 offset:35840
	ds_read_b128 v[190:193], v212 offset:36864
	ds_read_b128 v[214:217], v212 offset:37888
	ds_read_b128 v[218:221], v212 offset:38912
	ds_read_b128 v[222:225], v212 offset:39936
	global_load_lds_dwordx4 v[230:231], off
	v_lshl_add_u64 v[230:231], s[4:5], 0, v[182:183]
	s_mov_b32 m0, s35
	s_nop 0
	global_load_lds_dwordx4 v[230:231], off
	s_waitcnt vmcnt(8)
	s_waitcnt lgkmcnt(0)
	s_barrier
	s_setprio 1
	s_waitcnt lgkmcnt(0)
	v_mfma_f32_16x16x32_bf16 v[140:143], v[48:51], v[160:163], v[140:143]
	v_mfma_f32_16x16x32_bf16 v[136:139], v[64:67], v[160:163], v[136:139]
	v_mfma_f32_16x16x32_bf16 v[124:127], v[48:51], v[168:171], v[124:127]
	v_mfma_f32_16x16x32_bf16 v[120:123], v[64:67], v[168:171], v[120:123]
	v_mfma_f32_16x16x32_bf16 v[108:111], v[48:51], v[190:193], v[108:111]
	v_mfma_f32_16x16x32_bf16 v[104:107], v[64:67], v[190:193], v[104:107]
	v_mfma_f32_16x16x32_bf16 v[92:95], v[48:51], v[218:221], v[92:95]
	v_mfma_f32_16x16x32_bf16 v[88:91], v[64:67], v[218:221], v[88:91]
	v_mfma_f32_16x16x32_bf16 v[140:143], v[52:55], v[164:167], v[140:143]
	v_mfma_f32_16x16x32_bf16 v[136:139], v[68:71], v[164:167], v[136:139]
	v_mfma_f32_16x16x32_bf16 v[124:127], v[52:55], v[172:175], v[124:127]
	v_mfma_f32_16x16x32_bf16 v[120:123], v[68:71], v[172:175], v[120:123]
	v_mfma_f32_16x16x32_bf16 v[108:111], v[52:55], v[214:217], v[108:111]
	v_mfma_f32_16x16x32_bf16 v[104:107], v[68:71], v[214:217], v[104:107]
	v_mfma_f32_16x16x32_bf16 v[92:95], v[52:55], v[222:225], v[92:95]
	v_mfma_f32_16x16x32_bf16 v[88:91], v[68:71], v[222:225], v[88:91]
	s_setprio 0
	s_setprio 1
	v_mfma_f32_16x16x32_bf16 v[132:135], v[144:147], v[160:163], v[132:135]
	v_mfma_f32_16x16x32_bf16 v[128:131], v[152:155], v[160:163], v[128:131]
	v_mfma_f32_16x16x32_bf16 v[116:119], v[144:147], v[168:171], v[116:119]
	v_mfma_f32_16x16x32_bf16 v[112:115], v[152:155], v[168:171], v[112:115]
	v_mfma_f32_16x16x32_bf16 v[100:103], v[144:147], v[190:193], v[100:103]
	v_mfma_f32_16x16x32_bf16 v[96:99], v[152:155], v[190:193], v[96:99]
	v_mfma_f32_16x16x32_bf16 v[84:87], v[144:147], v[218:221], v[84:87]
	v_mfma_f32_16x16x32_bf16 v[80:83], v[152:155], v[218:221], v[80:83]
	v_mfma_f32_16x16x32_bf16 v[132:135], v[148:151], v[164:167], v[132:135]
	v_mfma_f32_16x16x32_bf16 v[128:131], v[156:159], v[164:167], v[128:131]
	v_mfma_f32_16x16x32_bf16 v[116:119], v[148:151], v[172:175], v[116:119]
	v_mfma_f32_16x16x32_bf16 v[112:115], v[156:159], v[172:175], v[112:115]
	v_mfma_f32_16x16x32_bf16 v[100:103], v[148:151], v[214:217], v[100:103]
	v_mfma_f32_16x16x32_bf16 v[96:99], v[156:159], v[214:217], v[96:99]
	v_mfma_f32_16x16x32_bf16 v[84:87], v[148:151], v[222:225], v[84:87]
	v_mfma_f32_16x16x32_bf16 v[80:83], v[156:159], v[222:225], v[80:83]
	s_setprio 0
	s_barrier
; #define PG8_STAGE(bufoff, gbase, voff) do { _Pragma("unroll") for (int _i = 0; _i < 2; ++_i) \
;         __builtin_amdgcn_global_load_lds((const unsigned*)((const char*)(gbase) + (voff)[_i]), (LAS unsigned*)(lds + (bufoff) + ldsw + _i * 8192), 16, 0, 0); } while (0)
; #define PG8_LDA(dst, b, h) do { _Pragma("unroll") for (int m = 0; m < 4; ++m) _Pragma("unroll") for (int k = 0; k < 2; ++k) dst[m][k] = *(const LAS bf16x8*)(lds + PG8_SA(b, h) + aoff + m * 2048 + k * 1024); } while (0)
; #define PG8_MMA(ai, bj, At, Bt) do { __builtin_amdgcn_s_setprio(1); _Pragma("unroll") for (int m = 0; m < 4; ++m) _Pragma("unroll") for (int n = 0; n < 2; ++n) _Pragma("unroll") for (int k = 0; k < 2; ++k) \
;         acc[ai][bj][m][n] = __builtin_amdgcn_mfma_f32_16x16x32_bf16(Bt[n][k], At[m][k], acc[ai][bj][m][n], 0, 0, 0); __builtin_amdgcn_s_setprio(0); } while (0)
; #define PG8_WAIT_V(n) asm volatile("s_waitcnt vmcnt(" #n ")" ::: "memory")
; #define PG8_WAIT_L(n) asm volatile("s_waitcnt lgkmcnt(" #n ")" ::: "memory")
; #define PG8_BAR __builtin_amdgcn_s_barrier()
; #define PG8_SCHED __builtin_amdgcn_sched_barrier(0)
; template <class Epi>
; __device__ __forceinline__ void gemm_phase(LAS unsigned char* lds, const GemmD g, const Epi& E, int G, int c) {
;     ...
;             PG8_LDA(At, 1, 1); PG8_STAGE(PG8_SB(1, 0), b3, voffB); PG8_STAGE(PG8_SB(1, 1), b3 + hstepB, voffB); PG8_STAGE(PG8_SA(1, 0), a3, voffA);
;             PG8_WAIT_V(8); PG8_WAIT_L(0); PG8_BAR; PG8_MMA(1, 0, At, B0); PG8_MMA(1, 1, At, B1); PG8_BAR; PG8_SCHED;
;         }
;         if (wr == 0) PG8_BAR;
	s_add_i32 s4, s28, s16
	v_lshl_add_u64 v[194:195], v[194:195], 0, s[48:49]
	s_mov_b32 m0, s4
	ds_read_b128 v[160:163], v212 offset:49152
	ds_read_b128 v[164:167], v212 offset:50176
	ds_read_b128 v[168:171], v212 offset:51200
	ds_read_b128 v[172:175], v212 offset:52224
	ds_read_b128 v[190:193], v212 offset:53248
	ds_read_b128 v[214:217], v212 offset:54272
	ds_read_b128 v[218:221], v212 offset:55296
	ds_read_b128 v[222:225], v212 offset:56320
	global_load_lds_dwordx4 v[194:195], off
	s_add_i32 m0, s4, 0x2000
	s_add_u32 s4, s88, 0x80080
	v_lshl_add_u64 v[194:195], v[198:199], 0, s[48:49]
	s_addc_u32 s5, s89, 0
	s_add_i32 s28, s29, s16
	global_load_lds_dwordx4 v[194:195], off
	v_lshl_add_u64 v[194:195], s[4:5], 0, v[178:179]
	s_mov_b32 m0, s28
	s_nop 0
	global_load_lds_dwordx4 v[194:195], off
	v_lshl_add_u64 v[194:195], s[4:5], 0, v[180:181]
	s_add_i32 m0, s28, 0x2000
	s_nop 0
	global_load_lds_dwordx4 v[194:195], off
	v_lshl_add_u64 v[194:195], v[226:227], 0, s[48:49]
	s_mov_b32 m0, s36
	s_nop 0
	global_load_lds_dwordx4 v[194:195], off
	v_lshl_add_u64 v[194:195], v[228:229], 0, s[48:49]
	s_mov_b32 m0, s90
	s_nop 0
	global_load_lds_dwordx4 v[194:195], off
	s_waitcnt vmcnt(8)
	s_waitcnt lgkmcnt(0)
	s_barrier
	s_setprio 1
	s_waitcnt lgkmcnt(0)
	v_mfma_f32_16x16x32_bf16 v[76:79], v[48:51], v[160:163], v[76:79]
	v_mfma_f32_16x16x32_bf16 v[72:75], v[64:67], v[160:163], v[72:75]
	v_mfma_f32_16x16x32_bf16 v[60:63], v[48:51], v[168:171], v[60:63]
	v_mfma_f32_16x16x32_bf16 v[56:59], v[64:67], v[168:171], v[56:59]
	v_mfma_f32_16x16x32_bf16 v[40:43], v[48:51], v[190:193], v[40:43]
	v_mfma_f32_16x16x32_bf16 v[32:35], v[64:67], v[190:193], v[32:35]
	v_mfma_f32_16x16x32_bf16 v[12:15], v[48:51], v[218:221], v[12:15]
	v_mfma_f32_16x16x32_bf16 v[8:11], v[64:67], v[218:221], v[8:11]
	v_mfma_f32_16x16x32_bf16 v[76:79], v[52:55], v[164:167], v[76:79]
	v_mfma_f32_16x16x32_bf16 v[72:75], v[68:71], v[164:167], v[72:75]
	v_mfma_f32_16x16x32_bf16 v[60:63], v[52:55], v[172:175], v[60:63]
	v_mfma_f32_16x16x32_bf16 v[56:59], v[68:71], v[172:175], v[56:59]
	v_mfma_f32_16x16x32_bf16 v[40:43], v[52:55], v[214:217], v[40:43]
	v_mfma_f32_16x16x32_bf16 v[32:35], v[68:71], v[214:217], v[32:35]
	v_mfma_f32_16x16x32_bf16 v[12:15], v[52:55], v[222:225], v[12:15]
	v_mfma_f32_16x16x32_bf16 v[8:11], v[68:71], v[222:225], v[8:11]
	s_setprio 0
	s_setprio 1
	v_mfma_f32_16x16x32_bf16 v[24:27], v[144:147], v[160:163], v[24:27]
	v_mfma_f32_16x16x32_bf16 v[68:71], v[148:151], v[164:167], v[24:27]
	v_mfma_f32_16x16x32_bf16 v[24:27], v[152:155], v[160:163], v[28:31]
	v_mfma_f32_16x16x32_bf16 v[64:67], v[156:159], v[164:167], v[24:27]
	v_mfma_f32_16x16x32_bf16 v[24:27], v[144:147], v[168:171], v[36:39]
	v_mfma_f32_16x16x32_bf16 v[52:55], v[148:151], v[172:175], v[24:27]
	v_mfma_f32_16x16x32_bf16 v[24:27], v[152:155], v[168:171], v[44:47]
	v_mfma_f32_16x16x32_bf16 v[20:23], v[144:147], v[190:193], v[20:23]
	v_mfma_f32_16x16x32_bf16 v[16:19], v[152:155], v[190:193], v[16:19]
	v_mfma_f32_16x16x32_bf16 v[4:7], v[144:147], v[218:221], v[4:7]
	v_mfma_f32_16x16x32_bf16 v[0:3], v[152:155], v[218:221], v[0:3]
	v_mfma_f32_16x16x32_bf16 v[48:51], v[156:159], v[172:175], v[24:27]
	v_mfma_f32_16x16x32_bf16 v[20:23], v[148:151], v[214:217], v[20:23]
	v_mfma_f32_16x16x32_bf16 v[16:19], v[156:159], v[214:217], v[16:19]
	v_mfma_f32_16x16x32_bf16 v[4:7], v[148:151], v[222:225], v[4:7]
	v_mfma_f32_16x16x32_bf16 v[0:3], v[156:159], v[222:225], v[0:3]
	s_setprio 0
	s_barrier
	s_add_i32 s27, s27, 2
	s_add_u32 s42, s42, 0x100
	s_addc_u32 s43, s43, 0
	s_add_u32 s19, s19, 0x100
	s_addc_u32 s22, s22, 0
	s_cmp_gt_u32 s27, 29
	s_cbranch_scc0 .LBB0_271
	s_and_b64 vcc, exec, s[66:67]
	s_cbranch_vccz .LBB0_274
	s_barrier

; #define PG8_BAR __builtin_amdgcn_s_barrier()
; #define PG8_PIN_ACC() do { _Pragma("unroll") for (int a = 0; a < 2; ++a) _Pragma("unroll") for (int b = 0; b < 2; ++b) _Pragma("unroll") for (int m = 0; m < 4; ++m) \
;         asm volatile("" : "+v"(acc[a][b][m][0]), "+v"(acc[a][b][m][1])); } while (0)
; template <class Epi>
; __device__ __forceinline__ void gemm_phase(LAS unsigned char* lds, const GemmD g, const Epi& E, int G, int c) {
;     ...
;         if (!has_next) break;
;         if constexpr (Epi::PRELOAD) { E.preload(acc, npm, npn, nz, wr, wc, fr, fq); PG8_PIN_ACC(); }
;         else {
; #pragma unroll
;         for (int a = 0; a < 2; ++a)
; #pragma unroll
;             for (int b = 0; b < 2; ++b)
; #pragma unroll
;                 for (int m = 0; m < 4; ++m)
; #pragma unroll
;                     for (int n = 0; n < 2; ++n) acc[a][b][m][n] = (f32x4){0.f, 0.f, 0.f, 0.f};
;         }
;         cpm = npm; cpn = npn; cz = nz; cA = nA; cB = nB; ++ui;
;         if (wr == 1) PG8_BAR;
.LBB0_285:
	s_mov_b32 s99, 1
	s_andn2_b64 vcc, exec, s[4:5]
	s_mov_b32 s26, s62
	s_mov_b32 s23, s64
	s_mov_b32 s27, s22
	s_mov_b64 s[84:85], s[80:81]
	s_mov_b64 s[82:83], s[66:67]
	s_cbranch_vccz .LBB0_307

; #define PG8_STAGE(bufoff, gbase, voff) do { _Pragma("unroll") for (int _i = 0; _i < 2; ++_i) \
;         __builtin_amdgcn_global_load_lds((const unsigned*)((const char*)(gbase) + (voff)[_i]), (LAS unsigned*)(lds + (bufoff) + ldsw + _i * 8192), 16, 0, 0); } while (0)
; #define PG8_LDA(dst, b, h) do { _Pragma("unroll") for (int m = 0; m < 4; ++m) _Pragma("unroll") for (int k = 0; k < 2; ++k) dst[m][k] = *(const LAS bf16x8*)(lds + PG8_SA(b, h) + aoff + m * 2048 + k * 1024); } while (0)
; #define PG8_LDB(dst, b, h) do { _Pragma("unroll") for (int n = 0; n < 2; ++n) _Pragma("unroll") for (int k = 0; k < 2; ++k) dst[n][k] = *(const LAS bf16x8*)(lds + PG8_SB(b, h) + boff + n * 2048 + k * 1024); } while (0)
; #define PG8_MMA(ai, bj, At, Bt) do { __builtin_amdgcn_s_setprio(1); _Pragma("unroll") for (int m = 0; m < 4; ++m) _Pragma("unroll") for (int n = 0; n < 2; ++n) _Pragma("unroll") for (int k = 0; k < 2; ++k) \
;         acc[ai][bj][m][n] = __builtin_amdgcn_mfma_f32_16x16x32_bf16(Bt[n][k], At[m][k], acc[ai][bj][m][n], 0, 0, 0); __builtin_amdgcn_s_setprio(0); } while (0)
; #define PG8_WAIT_V(n) asm volatile("s_waitcnt vmcnt(" #n ")" ::: "memory")
; #define PG8_WAIT_L(n) asm volatile("s_waitcnt lgkmcnt(" #n ")" ::: "memory")
; #define PG8_BAR __builtin_amdgcn_s_barrier()
; #define PG8_SCHED __builtin_amdgcn_sched_barrier(0)
; template <class Epi>
; __device__ __forceinline__ void gemm_phase(LAS unsigned char* lds, const GemmD g, const Epi& E, int G, int c) {
;     ...
;         for (int t = 0; t < nt; t += 2) {
;             const bool last = (t == nt - 2);
;             const char* a1 = cA + (size_t)(t + 1) * kstep;
;             const char* a2 = last ? nA : cA + (size_t)(t + 2) * kstep; const char* b2 = last ? nB : cB + (size_t)(t + 2) * kstep;
;             const char* a3 = a2 + kstep; const char* b3 = b2 + kstep;
;             PG8_LDB(B0, 0, 0); PG8_LDB(B1, 0, 1); PG8_SCHED; PG8_LDA(At, 0, 0); PG8_STAGE(PG8_SA(1, 1), a1 + hstepA, voffA);
;             PG8_WAIT_V(8); PG8_WAIT_L(0); PG8_BAR; PG8_MMA(0, 0, At, B0); PG8_MMA(0, 1, At, B1); PG8_BAR; PG8_SCHED;
;             PG8_LDA(At, 0, 1); PG8_STAGE(PG8_SB(0, 0), b2, voffB); PG8_STAGE(PG8_SB(0, 1), b2 + hstepB, voffB); PG8_STAGE(PG8_SA(0, 0), a2, voffA);
.LBB0_297:
	s_add_u32 s4, s82, 0xfff80080
	s_addc_u32 s5, s83, -1
	s_add_i32 s31, 0, 0x10000
	s_cmp_eq_u32 s30, 28
	s_cselect_b32 s5, s67, s5
	s_cselect_b32 s4, s66, s4
	v_add_u32_e32 v138, s31, v141
	s_cselect_b32 s85, s81, s29
	s_cselect_b32 s84, s80, s28
	s_add_i32 s33, 0, 0x14000
	ds_read_b128 v[146:149], v138
	ds_read_b128 v[150:153], v138 offset:1024
	ds_read_b128 v[154:157], v138 offset:2048
	ds_read_b128 v[158:161], v138 offset:3072
	v_add_u32_e32 v138, s33, v141
	ds_read_b128 v[162:165], v138
	ds_read_b128 v[166:169], v138 offset:1024
	ds_read_b128 v[170:173], v138 offset:2048
	ds_read_b128 v[180:183], v138 offset:3072
	v_lshl_add_u64 v[138:139], s[82:83], 0, v[134:135]
	s_add_i32 m0, s6, 0xc000
	ds_read_b128 v[184:187], v143
	ds_read_b128 v[188:191], v143 offset:1024
	ds_read_b128 v[192:195], v143 offset:2048
	ds_read_b128 v[210:213], v143 offset:3072
	ds_read_b128 v[214:217], v143 offset:4096
	ds_read_b128 v[218:221], v143 offset:5120
	ds_read_b128 v[222:225], v143 offset:6144
	ds_read_b128 v[226:229], v143 offset:7168
	global_load_lds_dwordx4 v[138:139], off
	v_lshl_add_u64 v[138:139], s[82:83], 0, v[136:137]
	s_add_i32 m0, s6, 0xe000
	s_nop 0
	global_load_lds_dwordx4 v[138:139], off
	s_cmp_lg_u32 s99, 0
	s_cbranch_scc1 .Lrw_PV_0_r
	s_waitcnt vmcnt(8)
	s_branch .Lrw_PV_0_d

; #define PG8_STAGE(bufoff, gbase, voff) do { _Pragma("unroll") for (int _i = 0; _i < 2; ++_i) \
;         __builtin_amdgcn_global_load_lds((const unsigned*)((const char*)(gbase) + (voff)[_i]), (LAS unsigned*)(lds + (bufoff) + ldsw + _i * 8192), 16, 0, 0); } while (0)
; #define PG8_LDA(dst, b, h) do { _Pragma("unroll") for (int m = 0; m < 4; ++m) _Pragma("unroll") for (int k = 0; k < 2; ++k) dst[m][k] = *(const LAS bf16x8*)(lds + PG8_SA(b, h) + aoff + m * 2048 + k * 1024); } while (0)
; #define PG8_MMA(ai, bj, At, Bt) do { __builtin_amdgcn_s_setprio(1); _Pragma("unroll") for (int m = 0; m < 4; ++m) _Pragma("unroll") for (int n = 0; n < 2; ++n) _Pragma("unroll") for (int k = 0; k < 2; ++k) \
;         acc[ai][bj][m][n] = __builtin_amdgcn_mfma_f32_16x16x32_bf16(Bt[n][k], At[m][k], acc[ai][bj][m][n], 0, 0, 0); __builtin_amdgcn_s_setprio(0); } while (0)
; #define PG8_WAIT_V(n) asm volatile("s_waitcnt vmcnt(" #n ")" ::: "memory")
; #define PG8_WAIT_L(n) asm volatile("s_waitcnt lgkmcnt(" #n ")" ::: "memory")
; #define PG8_BAR __builtin_amdgcn_s_barrier()
; #define PG8_SCHED __builtin_amdgcn_sched_barrier(0)
; template <class Epi>
; __device__ __forceinline__ void gemm_phase(LAS unsigned char* lds, const GemmD g, const Epi& E, int G, int c) {
;     ...
;             PG8_WAIT_V(8); PG8_WAIT_L(0); PG8_BAR; PG8_MMA(0, 0, At, B0); PG8_MMA(0, 1, At, B1); PG8_BAR; PG8_SCHED;
;             PG8_LDA(At, 0, 1); PG8_STAGE(PG8_SB(0, 0), b2, voffB); PG8_STAGE(PG8_SB(0, 1), b2 + hstepB, voffB); PG8_STAGE(PG8_SA(0, 0), a2, voffA);
;             PG8_WAIT_V(8); PG8_WAIT_L(0); PG8_BAR; PG8_MMA(1, 0, At, B0); PG8_MMA(1, 1, At, B1); PG8_BAR; PG8_SCHED;
.Lrw_PV_0_d:
	s_waitcnt lgkmcnt(0)
	s_barrier
	s_setprio 1
	s_waitcnt lgkmcnt(0)
	v_mfma_f32_16x16x32_bf16 v[124:127], v[146:149], v[184:187], v[124:127]
	v_mfma_f32_16x16x32_bf16 v[120:123], v[154:157], v[184:187], v[120:123]
	v_mfma_f32_16x16x32_bf16 v[112:115], v[146:149], v[192:195], v[112:115]
	v_mfma_f32_16x16x32_bf16 v[104:107], v[154:157], v[192:195], v[104:107]
	v_mfma_f32_16x16x32_bf16 v[96:99], v[146:149], v[214:217], v[96:99]
	v_mfma_f32_16x16x32_bf16 v[88:91], v[154:157], v[214:217], v[88:91]
	v_mfma_f32_16x16x32_bf16 v[80:83], v[146:149], v[222:225], v[80:83]
	v_mfma_f32_16x16x32_bf16 v[72:75], v[154:157], v[222:225], v[72:75]
	v_mfma_f32_16x16x32_bf16 v[124:127], v[150:153], v[188:191], v[124:127]
	v_mfma_f32_16x16x32_bf16 v[120:123], v[158:161], v[188:191], v[120:123]
	v_mfma_f32_16x16x32_bf16 v[112:115], v[150:153], v[210:213], v[112:115]
	v_mfma_f32_16x16x32_bf16 v[104:107], v[158:161], v[210:213], v[104:107]
	v_mfma_f32_16x16x32_bf16 v[96:99], v[150:153], v[218:221], v[96:99]
	v_mfma_f32_16x16x32_bf16 v[88:91], v[158:161], v[218:221], v[88:91]
	v_mfma_f32_16x16x32_bf16 v[80:83], v[150:153], v[226:229], v[80:83]
	v_mfma_f32_16x16x32_bf16 v[72:75], v[158:161], v[226:229], v[72:75]
	s_setprio 0
	s_setprio 1
	v_mfma_f32_16x16x32_bf16 v[116:119], v[162:165], v[184:187], v[116:119]
	v_mfma_f32_16x16x32_bf16 v[108:111], v[170:173], v[184:187], v[108:111]
	v_mfma_f32_16x16x32_bf16 v[100:103], v[162:165], v[192:195], v[100:103]
	v_mfma_f32_16x16x32_bf16 v[92:95], v[170:173], v[192:195], v[92:95]
	v_mfma_f32_16x16x32_bf16 v[84:87], v[162:165], v[214:217], v[84:87]
	v_mfma_f32_16x16x32_bf16 v[76:79], v[170:173], v[214:217], v[76:79]
	v_mfma_f32_16x16x32_bf16 v[68:71], v[162:165], v[222:225], v[68:71]
	v_mfma_f32_16x16x32_bf16 v[64:67], v[170:173], v[222:225], v[64:67]
	v_mfma_f32_16x16x32_bf16 v[116:119], v[166:169], v[188:191], v[116:119]
	v_mfma_f32_16x16x32_bf16 v[108:111], v[180:183], v[188:191], v[108:111]
	v_mfma_f32_16x16x32_bf16 v[100:103], v[166:169], v[210:213], v[100:103]
	v_mfma_f32_16x16x32_bf16 v[92:95], v[180:183], v[210:213], v[92:95]
	v_mfma_f32_16x16x32_bf16 v[84:87], v[166:169], v[218:221], v[84:87]
	v_mfma_f32_16x16x32_bf16 v[76:79], v[180:183], v[218:221], v[76:79]
	v_mfma_f32_16x16x32_bf16 v[68:71], v[166:169], v[226:229], v[68:71]
	v_mfma_f32_16x16x32_bf16 v[64:67], v[180:183], v[226:229], v[64:67]
	s_setprio 0
	s_barrier
	s_add_i32 s31, s31, s2
	v_lshl_add_u64 v[138:139], s[84:85], 0, v[178:179]
	s_mov_b32 m0, s31
	ds_read_b128 v[184:187], v143 offset:16384
	ds_read_b128 v[188:191], v143 offset:17408
	ds_read_b128 v[192:195], v143 offset:18432
	ds_read_b128 v[210:213], v143 offset:19456
	ds_read_b128 v[214:217], v143 offset:20480
	ds_read_b128 v[218:221], v143 offset:21504
	ds_read_b128 v[222:225], v143 offset:22528
	ds_read_b128 v[226:229], v143 offset:23552
	global_load_lds_dwordx4 v[138:139], off
	s_add_i32 m0, s31, 0x2000
	s_add_u32 s38, s84, 0x400000
	v_lshl_add_u64 v[174:175], s[84:85], 0, v[128:129]
	s_addc_u32 s39, s85, 0
	s_add_i32 s31, s33, s2
	global_load_lds_dwordx4 v[174:175], off
	v_lshl_add_u64 v[198:199], s[38:39], 0, v[178:179]
	s_mov_b32 m0, s31
	v_lshl_add_u64 v[230:231], s[4:5], 0, v[130:131]
	global_load_lds_dwordx4 v[198:199], off
	v_lshl_add_u64 v[198:199], s[38:39], 0, v[128:129]
	s_add_i32 m0, s31, 0x2000
	s_nop 0
	global_load_lds_dwordx4 v[198:199], off
	v_lshl_add_u64 v[198:199], s[4:5], 0, v[132:133]
	s_mov_b32 m0, s6
	s_nop 0
	global_load_lds_dwordx4 v[198:199], off
	s_mov_b32 m0, s9
	s_nop 0
	global_load_lds_dwordx4 v[230:231], off
	s_cmp_lg_u32 s99, 0
	s_cbranch_scc1 .Lrw_PV_1_r
	s_waitcnt vmcnt(8)
	s_branch .Lrw_PV_1_d

; #define PG8_STAGE(bufoff, gbase, voff) do { _Pragma("unroll") for (int _i = 0; _i < 2; ++_i) \
;         __builtin_amdgcn_global_load_lds((const unsigned*)((const char*)(gbase) + (voff)[_i]), (LAS unsigned*)(lds + (bufoff) + ldsw + _i * 8192), 16, 0, 0); } while (0)
; #define PG8_LDA(dst, b, h) do { _Pragma("unroll") for (int m = 0; m < 4; ++m) _Pragma("unroll") for (int k = 0; k < 2; ++k) dst[m][k] = *(const LAS bf16x8*)(lds + PG8_SA(b, h) + aoff + m * 2048 + k * 1024); } while (0)
; #define PG8_LDB(dst, b, h) do { _Pragma("unroll") for (int n = 0; n < 2; ++n) _Pragma("unroll") for (int k = 0; k < 2; ++k) dst[n][k] = *(const LAS bf16x8*)(lds + PG8_SB(b, h) + boff + n * 2048 + k * 1024); } while (0)
; #define PG8_MMA(ai, bj, At, Bt) do { __builtin_amdgcn_s_setprio(1); _Pragma("unroll") for (int m = 0; m < 4; ++m) _Pragma("unroll") for (int n = 0; n < 2; ++n) _Pragma("unroll") for (int k = 0; k < 2; ++k) \
;         acc[ai][bj][m][n] = __builtin_amdgcn_mfma_f32_16x16x32_bf16(Bt[n][k], At[m][k], acc[ai][bj][m][n], 0, 0, 0); __builtin_amdgcn_s_setprio(0); } while (0)
; #define PG8_WAIT_V(n) asm volatile("s_waitcnt vmcnt(" #n ")" ::: "memory")
; #define PG8_WAIT_L(n) asm volatile("s_waitcnt lgkmcnt(" #n ")" ::: "memory")
; #define PG8_BAR __builtin_amdgcn_s_barrier()
; #define PG8_SCHED __builtin_amdgcn_sched_barrier(0)
; template <class Epi>
; __device__ __forceinline__ void gemm_phase(LAS unsigned char* lds, const GemmD g, const Epi& E, int G, int c) {
;     ...
;             PG8_WAIT_V(8); PG8_WAIT_L(0); PG8_BAR; PG8_MMA(1, 0, At, B0); PG8_MMA(1, 1, At, B1); PG8_BAR; PG8_SCHED;
;             PG8_LDB(B0, 1, 0); PG8_LDB(B1, 1, 1); PG8_SCHED; PG8_LDA(At, 1, 0); PG8_STAGE(PG8_SA(0, 1), a2 + hstepA, voffA);
;             PG8_WAIT_V(8); PG8_WAIT_L(0); PG8_BAR; PG8_MMA(0, 0, At, B0); PG8_MMA(0, 1, At, B1); PG8_BAR; PG8_SCHED;
.Lrw_PV_1_d:
	s_waitcnt lgkmcnt(0)
	s_barrier
	s_setprio 1
	s_waitcnt lgkmcnt(0)
	v_mfma_f32_16x16x32_bf16 v[60:63], v[146:149], v[184:187], v[60:63]
	v_mfma_f32_16x16x32_bf16 v[56:59], v[154:157], v[184:187], v[56:59]
	v_mfma_f32_16x16x32_bf16 v[52:55], v[146:149], v[192:195], v[52:55]
	v_mfma_f32_16x16x32_bf16 v[44:47], v[154:157], v[192:195], v[44:47]
	v_mfma_f32_16x16x32_bf16 v[36:39], v[146:149], v[214:217], v[36:39]
	v_mfma_f32_16x16x32_bf16 v[28:31], v[154:157], v[214:217], v[28:31]
	v_mfma_f32_16x16x32_bf16 v[20:23], v[146:149], v[222:225], v[20:23]
	v_mfma_f32_16x16x32_bf16 v[12:15], v[154:157], v[222:225], v[12:15]
	v_mfma_f32_16x16x32_bf16 v[60:63], v[150:153], v[188:191], v[60:63]
	v_mfma_f32_16x16x32_bf16 v[56:59], v[158:161], v[188:191], v[56:59]
	v_mfma_f32_16x16x32_bf16 v[52:55], v[150:153], v[210:213], v[52:55]
	v_mfma_f32_16x16x32_bf16 v[44:47], v[158:161], v[210:213], v[44:47]
	v_mfma_f32_16x16x32_bf16 v[36:39], v[150:153], v[218:221], v[36:39]
	v_mfma_f32_16x16x32_bf16 v[28:31], v[158:161], v[218:221], v[28:31]
	v_mfma_f32_16x16x32_bf16 v[20:23], v[150:153], v[226:229], v[20:23]
	v_mfma_f32_16x16x32_bf16 v[12:15], v[158:161], v[226:229], v[12:15]
	s_setprio 0
	s_setprio 1
	v_mfma_f32_16x16x32_bf16 v[48:51], v[162:165], v[184:187], v[48:51]
	v_mfma_f32_16x16x32_bf16 v[40:43], v[170:173], v[184:187], v[40:43]
	v_mfma_f32_16x16x32_bf16 v[32:35], v[162:165], v[192:195], v[32:35]
	v_mfma_f32_16x16x32_bf16 v[24:27], v[170:173], v[192:195], v[24:27]
	v_mfma_f32_16x16x32_bf16 v[16:19], v[162:165], v[214:217], v[16:19]
	v_mfma_f32_16x16x32_bf16 v[8:11], v[170:173], v[214:217], v[8:11]
	v_mfma_f32_16x16x32_bf16 v[4:7], v[162:165], v[222:225], v[4:7]
	v_mfma_f32_16x16x32_bf16 v[0:3], v[170:173], v[222:225], v[0:3]
	v_mfma_f32_16x16x32_bf16 v[48:51], v[166:169], v[188:191], v[48:51]
	v_mfma_f32_16x16x32_bf16 v[40:43], v[180:183], v[188:191], v[40:43]
	v_mfma_f32_16x16x32_bf16 v[32:35], v[166:169], v[210:213], v[32:35]
	v_mfma_f32_16x16x32_bf16 v[24:27], v[180:183], v[210:213], v[24:27]
	v_mfma_f32_16x16x32_bf16 v[16:19], v[166:169], v[218:221], v[16:19]
	v_mfma_f32_16x16x32_bf16 v[8:11], v[180:183], v[218:221], v[8:11]
	v_mfma_f32_16x16x32_bf16 v[4:7], v[166:169], v[226:229], v[4:7]
	v_mfma_f32_16x16x32_bf16 v[0:3], v[180:183], v[226:229], v[0:3]
	s_setprio 0
	s_barrier
	s_add_i32 s31, 0, 0x18000
	v_add_u32_e32 v145, s31, v141
	s_add_i32 s33, 0, 0x1c000
	ds_read_b128 v[146:149], v145
	ds_read_b128 v[150:153], v145 offset:1024
	ds_read_b128 v[154:157], v145 offset:2048
	ds_read_b128 v[158:161], v145 offset:3072
	v_add_u32_e32 v145, s33, v141
	ds_read_b128 v[162:165], v145
	ds_read_b128 v[166:169], v145 offset:1024
	ds_read_b128 v[170:173], v145 offset:2048
	ds_read_b128 v[180:183], v145 offset:3072
	s_add_u32 s4, s4, 0x80000
	s_addc_u32 s5, s5, 0
	s_mov_b32 m0, s10
	v_lshl_add_u64 v[232:233], s[4:5], 0, v[132:133]
	ds_read_b128 v[184:187], v143 offset:32768
	ds_read_b128 v[188:191], v143 offset:33792
	ds_read_b128 v[192:195], v143 offset:34816
	ds_read_b128 v[210:213], v143 offset:35840
	ds_read_b128 v[214:217], v143 offset:36864
	ds_read_b128 v[218:221], v143 offset:37888
	ds_read_b128 v[222:225], v143 offset:38912
	ds_read_b128 v[226:229], v143 offset:39936
	global_load_lds_dwordx4 v[232:233], off
	v_lshl_add_u64 v[232:233], s[4:5], 0, v[130:131]
	s_mov_b32 m0, s11
	s_nop 0
	global_load_lds_dwordx4 v[232:233], off
	s_waitcnt vmcnt(8)
	s_waitcnt lgkmcnt(0)
	s_barrier
	s_setprio 1
	s_waitcnt lgkmcnt(0)
	v_mfma_f32_16x16x32_bf16 v[124:127], v[146:149], v[184:187], v[124:127]
	v_mfma_f32_16x16x32_bf16 v[120:123], v[154:157], v[184:187], v[120:123]
	v_mfma_f32_16x16x32_bf16 v[112:115], v[146:149], v[192:195], v[112:115]
	v_mfma_f32_16x16x32_bf16 v[104:107], v[154:157], v[192:195], v[104:107]
	v_mfma_f32_16x16x32_bf16 v[96:99], v[146:149], v[214:217], v[96:99]
	v_mfma_f32_16x16x32_bf16 v[88:91], v[154:157], v[214:217], v[88:91]
	v_mfma_f32_16x16x32_bf16 v[80:83], v[146:149], v[222:225], v[80:83]
	v_mfma_f32_16x16x32_bf16 v[72:75], v[154:157], v[222:225], v[72:75]
	v_mfma_f32_16x16x32_bf16 v[124:127], v[150:153], v[188:191], v[124:127]
	v_mfma_f32_16x16x32_bf16 v[120:123], v[158:161], v[188:191], v[120:123]
	v_mfma_f32_16x16x32_bf16 v[112:115], v[150:153], v[210:213], v[112:115]
	v_mfma_f32_16x16x32_bf16 v[104:107], v[158:161], v[210:213], v[104:107]
	v_mfma_f32_16x16x32_bf16 v[96:99], v[150:153], v[218:221], v[96:99]
	v_mfma_f32_16x16x32_bf16 v[88:91], v[158:161], v[218:221], v[88:91]
	v_mfma_f32_16x16x32_bf16 v[80:83], v[150:153], v[226:229], v[80:83]
	v_mfma_f32_16x16x32_bf16 v[72:75], v[158:161], v[226:229], v[72:75]
	s_setprio 0
	s_setprio 1
	v_mfma_f32_16x16x32_bf16 v[116:119], v[162:165], v[184:187], v[116:119]
	v_mfma_f32_16x16x32_bf16 v[108:111], v[170:173], v[184:187], v[108:111]
	v_mfma_f32_16x16x32_bf16 v[100:103], v[162:165], v[192:195], v[100:103]
	v_mfma_f32_16x16x32_bf16 v[92:95], v[170:173], v[192:195], v[92:95]
	v_mfma_f32_16x16x32_bf16 v[84:87], v[162:165], v[214:217], v[84:87]
	v_mfma_f32_16x16x32_bf16 v[76:79], v[170:173], v[214:217], v[76:79]
	v_mfma_f32_16x16x32_bf16 v[68:71], v[162:165], v[222:225], v[68:71]
	v_mfma_f32_16x16x32_bf16 v[64:67], v[170:173], v[222:225], v[64:67]
	v_mfma_f32_16x16x32_bf16 v[116:119], v[166:169], v[188:191], v[116:119]
	v_mfma_f32_16x16x32_bf16 v[108:111], v[180:183], v[188:191], v[108:111]
	v_mfma_f32_16x16x32_bf16 v[100:103], v[166:169], v[210:213], v[100:103]
	v_mfma_f32_16x16x32_bf16 v[92:95], v[180:183], v[210:213], v[92:95]
	v_mfma_f32_16x16x32_bf16 v[84:87], v[166:169], v[218:221], v[84:87]
	v_mfma_f32_16x16x32_bf16 v[76:79], v[180:183], v[218:221], v[76:79]
	v_mfma_f32_16x16x32_bf16 v[68:71], v[166:169], v[226:229], v[68:71]
	v_mfma_f32_16x16x32_bf16 v[64:67], v[180:183], v[226:229], v[64:67]
	s_setprio 0
	s_barrier
; #define PG8_STAGE(bufoff, gbase, voff) do { _Pragma("unroll") for (int _i = 0; _i < 2; ++_i) \
;         __builtin_amdgcn_global_load_lds((const unsigned*)((const char*)(gbase) + (voff)[_i]), (LAS unsigned*)(lds + (bufoff) + ldsw + _i * 8192), 16, 0, 0); } while (0)
; #define PG8_LDA(dst, b, h) do { _Pragma("unroll") for (int m = 0; m < 4; ++m) _Pragma("unroll") for (int k = 0; k < 2; ++k) dst[m][k] = *(const LAS bf16x8*)(lds + PG8_SA(b, h) + aoff + m * 2048 + k * 1024); } while (0)
; #define PG8_MMA(ai, bj, At, Bt) do { __builtin_amdgcn_s_setprio(1); _Pragma("unroll") for (int m = 0; m < 4; ++m) _Pragma("unroll") for (int n = 0; n < 2; ++n) _Pragma("unroll") for (int k = 0; k < 2; ++k) \
;         acc[ai][bj][m][n] = __builtin_amdgcn_mfma_f32_16x16x32_bf16(Bt[n][k], At[m][k], acc[ai][bj][m][n], 0, 0, 0); __builtin_amdgcn_s_setprio(0); } while (0)
; #define PG8_WAIT_V(n) asm volatile("s_waitcnt vmcnt(" #n ")" ::: "memory")
; #define PG8_WAIT_L(n) asm volatile("s_waitcnt lgkmcnt(" #n ")" ::: "memory")
; #define PG8_BAR __builtin_amdgcn_s_barrier()
; #define PG8_SCHED __builtin_amdgcn_sched_barrier(0)
; template <class Epi>
; __device__ __forceinline__ void gemm_phase(LAS unsigned char* lds, const GemmD g, const Epi& E, int G, int c) {
;     ...
;             PG8_LDA(At, 1, 1); PG8_STAGE(PG8_SB(1, 0), b3, voffB); PG8_STAGE(PG8_SB(1, 1), b3 + hstepB, voffB); PG8_STAGE(PG8_SA(1, 0), a3, voffA);
;             PG8_WAIT_V(8); PG8_WAIT_L(0); PG8_BAR; PG8_MMA(1, 0, At, B0); PG8_MMA(1, 1, At, B1); PG8_BAR; PG8_SCHED;
;         }
;         if (wr == 0) PG8_BAR;
	s_add_i32 s4, s31, s2
	v_lshl_add_u64 v[138:139], v[138:139], 0, s[48:49]
	s_mov_b32 m0, s4
	ds_read_b128 v[184:187], v143 offset:49152
	ds_read_b128 v[188:191], v143 offset:50176
	ds_read_b128 v[192:195], v143 offset:51200
	ds_read_b128 v[210:213], v143 offset:52224
	ds_read_b128 v[214:217], v143 offset:53248
	ds_read_b128 v[218:221], v143 offset:54272
	ds_read_b128 v[222:225], v143 offset:55296
	ds_read_b128 v[226:229], v143 offset:56320
	global_load_lds_dwordx4 v[138:139], off
	s_add_i32 m0, s4, 0x2000
	s_add_u32 s4, s84, 0x400080
	v_lshl_add_u64 v[138:139], v[174:175], 0, s[48:49]
	s_addc_u32 s5, s85, 0
	s_add_i32 s31, s33, s2
	global_load_lds_dwordx4 v[138:139], off
	v_lshl_add_u64 v[138:139], s[4:5], 0, v[178:179]
	s_mov_b32 m0, s31
	s_nop 0
	global_load_lds_dwordx4 v[138:139], off
	v_lshl_add_u64 v[138:139], s[4:5], 0, v[128:129]
	s_add_i32 m0, s31, 0x2000
	s_nop 0
	global_load_lds_dwordx4 v[138:139], off
	v_lshl_add_u64 v[138:139], v[198:199], 0, s[48:49]
	s_mov_b32 m0, s16
	s_nop 0
	global_load_lds_dwordx4 v[138:139], off
	v_lshl_add_u64 v[138:139], v[230:231], 0, s[48:49]
	s_mov_b32 m0, s17
	s_nop 0
	global_load_lds_dwordx4 v[138:139], off
	s_waitcnt vmcnt(8)
	s_waitcnt lgkmcnt(0)
	s_barrier
	s_setprio 1
	s_waitcnt lgkmcnt(0)
	v_mfma_f32_16x16x32_bf16 v[60:63], v[146:149], v[184:187], v[60:63]
	v_mfma_f32_16x16x32_bf16 v[56:59], v[154:157], v[184:187], v[56:59]
	v_mfma_f32_16x16x32_bf16 v[52:55], v[146:149], v[192:195], v[52:55]
	v_mfma_f32_16x16x32_bf16 v[44:47], v[154:157], v[192:195], v[44:47]
	v_mfma_f32_16x16x32_bf16 v[36:39], v[146:149], v[214:217], v[36:39]
	v_mfma_f32_16x16x32_bf16 v[28:31], v[154:157], v[214:217], v[28:31]
	v_mfma_f32_16x16x32_bf16 v[20:23], v[146:149], v[222:225], v[20:23]
	v_mfma_f32_16x16x32_bf16 v[12:15], v[154:157], v[222:225], v[12:15]
	v_mfma_f32_16x16x32_bf16 v[60:63], v[150:153], v[188:191], v[60:63]
	v_mfma_f32_16x16x32_bf16 v[56:59], v[158:161], v[188:191], v[56:59]
	v_mfma_f32_16x16x32_bf16 v[52:55], v[150:153], v[210:213], v[52:55]
	v_mfma_f32_16x16x32_bf16 v[44:47], v[158:161], v[210:213], v[44:47]
	v_mfma_f32_16x16x32_bf16 v[36:39], v[150:153], v[218:221], v[36:39]
	v_mfma_f32_16x16x32_bf16 v[28:31], v[158:161], v[218:221], v[28:31]
	v_mfma_f32_16x16x32_bf16 v[20:23], v[150:153], v[226:229], v[20:23]
	v_mfma_f32_16x16x32_bf16 v[12:15], v[158:161], v[226:229], v[12:15]
	s_setprio 0
	s_setprio 1
	v_mfma_f32_16x16x32_bf16 v[48:51], v[162:165], v[184:187], v[48:51]
	v_mfma_f32_16x16x32_bf16 v[40:43], v[170:173], v[184:187], v[40:43]
	v_mfma_f32_16x16x32_bf16 v[32:35], v[162:165], v[192:195], v[32:35]
	v_mfma_f32_16x16x32_bf16 v[24:27], v[170:173], v[192:195], v[24:27]
	v_mfma_f32_16x16x32_bf16 v[16:19], v[162:165], v[214:217], v[16:19]
	v_mfma_f32_16x16x32_bf16 v[8:11], v[170:173], v[214:217], v[8:11]
	v_mfma_f32_16x16x32_bf16 v[4:7], v[162:165], v[222:225], v[4:7]
	v_mfma_f32_16x16x32_bf16 v[0:3], v[170:173], v[222:225], v[0:3]
	v_mfma_f32_16x16x32_bf16 v[48:51], v[166:169], v[188:191], v[48:51]
	v_mfma_f32_16x16x32_bf16 v[40:43], v[180:183], v[188:191], v[40:43]
	v_mfma_f32_16x16x32_bf16 v[32:35], v[166:169], v[210:213], v[32:35]
	v_mfma_f32_16x16x32_bf16 v[24:27], v[180:183], v[210:213], v[24:27]
	v_mfma_f32_16x16x32_bf16 v[16:19], v[166:169], v[218:221], v[16:19]
	v_mfma_f32_16x16x32_bf16 v[8:11], v[180:183], v[218:221], v[8:11]
	v_mfma_f32_16x16x32_bf16 v[4:7], v[166:169], v[226:229], v[4:7]
	v_mfma_f32_16x16x32_bf16 v[0:3], v[180:183], v[226:229], v[0:3]
	s_setprio 0
	s_barrier
	s_add_i32 s30, s30, 2
	s_add_u32 s82, s82, 0x100
	s_addc_u32 s83, s83, 0
	s_add_u32 s28, s28, 0x100
	s_addc_u32 s29, s29, 0
	s_cmp_gt_u32 s30, 29
	s_cbranch_scc0 .LBB0_297
	s_and_b64 vcc, exec, s[60:61]
	s_cbranch_vccz .LBB0_300
	s_barrier

; #define PG8_BAR __builtin_amdgcn_s_barrier()
; #define PG8_PIN_ACC() do { _Pragma("unroll") for (int a = 0; a < 2; ++a) _Pragma("unroll") for (int b = 0; b < 2; ++b) _Pragma("unroll") for (int m = 0; m < 4; ++m) \
;         asm volatile("" : "+v"(acc[a][b][m][0]), "+v"(acc[a][b][m][1])); } while (0)
; template <class Epi>
; __device__ __forceinline__ void gemm_phase(LAS unsigned char* lds, const GemmD g, const Epi& E, int G, int c) {
;     ...
;         if (!has_next) break;
;         if constexpr (Epi::PRELOAD) { E.preload(acc, npm, npn, nz, wr, wc, fr, fq); PG8_PIN_ACC(); }
;         else {
; #pragma unroll
;         for (int a = 0; a < 2; ++a)
; #pragma unroll
;             for (int b = 0; b < 2; ++b)
; #pragma unroll
;                 for (int m = 0; m < 4; ++m)
; #pragma unroll
;                     for (int n = 0; n < 2; ++n) acc[a][b][m][n] = (f32x4){0.f, 0.f, 0.f, 0.f};
;         }
;         cpm = npm; cpn = npn; cz = nz; cA = nA; cB = nB; ++ui;
;         if (wr == 1) PG8_BAR;
.LBB0_317:
	s_mov_b32 s99, 1
	s_andn2_b64 vcc, exec, s[4:5]
	s_mov_b32 s2, s60
	s_mov_b32 s6, s64
	s_mov_b32 s86, s54
	s_mov_b64 s[82:83], s[80:81]
	s_mov_b64 s[84:85], s[66:67]
	s_cbranch_vccz .LBB0_339

; #define PG8_STAGE(bufoff, gbase, voff) do { _Pragma("unroll") for (int _i = 0; _i < 2; ++_i) \
;         __builtin_amdgcn_global_load_lds((const unsigned*)((const char*)(gbase) + (voff)[_i]), (LAS unsigned*)(lds + (bufoff) + ldsw + _i * 8192), 16, 0, 0); } while (0)
; #define PG8_LDA(dst, b, h) do { _Pragma("unroll") for (int m = 0; m < 4; ++m) _Pragma("unroll") for (int k = 0; k < 2; ++k) dst[m][k] = *(const LAS bf16x8*)(lds + PG8_SA(b, h) + aoff + m * 2048 + k * 1024); } while (0)
; #define PG8_LDB(dst, b, h) do { _Pragma("unroll") for (int n = 0; n < 2; ++n) _Pragma("unroll") for (int k = 0; k < 2; ++k) dst[n][k] = *(const LAS bf16x8*)(lds + PG8_SB(b, h) + boff + n * 2048 + k * 1024); } while (0)
; #define PG8_MMA(ai, bj, At, Bt) do { __builtin_amdgcn_s_setprio(1); _Pragma("unroll") for (int m = 0; m < 4; ++m) _Pragma("unroll") for (int n = 0; n < 2; ++n) _Pragma("unroll") for (int k = 0; k < 2; ++k) \
;         acc[ai][bj][m][n] = __builtin_amdgcn_mfma_f32_16x16x32_bf16(Bt[n][k], At[m][k], acc[ai][bj][m][n], 0, 0, 0); __builtin_amdgcn_s_setprio(0); } while (0)
; #define PG8_WAIT_V(n) asm volatile("s_waitcnt vmcnt(" #n ")" ::: "memory")
; #define PG8_WAIT_L(n) asm volatile("s_waitcnt lgkmcnt(" #n ")" ::: "memory")
; #define PG8_BAR __builtin_amdgcn_s_barrier()
; #define PG8_SCHED __builtin_amdgcn_sched_barrier(0)
; template <class Epi>
; __device__ __forceinline__ void gemm_phase(LAS unsigned char* lds, const GemmD g, const Epi& E, int G, int c) {
;     ...
;         for (int t = 0; t < nt; t += 2) {
;             const bool last = (t == nt - 2);
;             const char* a1 = cA + (size_t)(t + 1) * kstep;
;             const char* a2 = last ? nA : cA + (size_t)(t + 2) * kstep; const char* b2 = last ? nB : cB + (size_t)(t + 2) * kstep;
;             const char* a3 = a2 + kstep; const char* b3 = b2 + kstep;
;             PG8_LDB(B0, 0, 0); PG8_LDB(B1, 0, 1); PG8_SCHED; PG8_LDA(At, 0, 0); PG8_STAGE(PG8_SA(1, 1), a1 + hstepA, voffA);
;             PG8_WAIT_V(8); PG8_WAIT_L(0); PG8_BAR; PG8_MMA(0, 0, At, B0); PG8_MMA(0, 1, At, B1); PG8_BAR; PG8_SCHED;
;             PG8_LDA(At, 0, 1); PG8_STAGE(PG8_SB(0, 0), b2, voffB); PG8_STAGE(PG8_SB(0, 1), b2 + hstepB, voffB); PG8_STAGE(PG8_SA(0, 0), a2, voffA);
.LBB0_329:
	s_add_u32 s17, s84, s4
	s_addc_u32 s19, s85, 0
	s_add_u32 s5, s17, 0x100
	s_addc_u32 s27, s19, 0
	s_and_b64 s[28:29], s[90:91], exec
	s_cselect_b32 s93, s67, s27
	s_cselect_b32 s92, s66, s5
	s_add_u32 s4, s82, s4
	s_addc_u32 s5, s83, 0
	s_add_u32 s27, s4, 0x100
	s_addc_u32 s28, s5, 0
	s_add_i32 s39, 0, 0x10000
	s_and_b64 s[4:5], s[90:91], exec
	s_cselect_b32 s95, s81, s28
	s_cselect_b32 s94, s80, s27
	s_add_i32 s50, 0, 0x14000
	s_add_u32 s4, s17, 0x40080
	s_addc_u32 s5, s19, 0
	s_add_i32 s38, s39, s16
	s_add_i32 m0, s30, 0xc000
	s_add_i32 s52, s30, 0xe000
	s_add_i32 s29, s38, 0x2000
	s_add_u32 s96, s94, 0x40000
	v_add_u32_e32 v146, s39, v171
	v_add_u32_e32 v162, s50, v171
	s_addc_u32 s97, s95, 0
	s_add_i32 s33, s50, s16
	ds_read_b128 v[128:131], v146
	ds_read_b128 v[138:141], v146 offset:1024
	ds_read_b128 v[142:145], v146 offset:2048
	ds_read_b128 v[146:149], v146 offset:3072
	ds_read_b128 v[150:153], v162
	ds_read_b128 v[154:157], v162 offset:1024
	ds_read_b128 v[158:161], v162 offset:2048
	ds_read_b128 v[162:165], v162 offset:3072
	s_add_i32 s31, s33, 0x2000
	s_add_i32 s28, 0, 0x18000
	s_add_i32 s27, 0, 0x1c000
	s_add_u32 vcc_lo, s92, 0x40000
	s_addc_u32 vcc_hi, s93, 0
	s_add_i32 s19, s28, s16
	s_add_i32 s17, s19, 0x2000
	s_add_u32 s90, s94, 0x40080
	s_addc_u32 s91, s95, 0
	s_add_i32 s50, s27, s16
	s_add_i32 s39, s50, 0x2000
	v_lshl_add_u64 v[174:175], s[4:5], 0, v[136:137]
	ds_read_b128 v[166:169], v173
	ds_read_b128 v[180:183], v173 offset:1024
	ds_read_b128 v[184:187], v173 offset:2048
	ds_read_b128 v[188:191], v173 offset:3072
	ds_read_b128 v[192:195], v173 offset:4096
	ds_read_b128 v[210:213], v173 offset:5120
	ds_read_b128 v[214:217], v173 offset:6144
	ds_read_b128 v[218:221], v173 offset:7168
	global_load_lds_dwordx4 v[174:175], off
	v_lshl_add_u64 v[174:175], s[4:5], 0, v[134:135]
	s_mov_b32 m0, s52
	s_nop 0
	global_load_lds_dwordx4 v[174:175], off
	s_cmp_lg_u32 s99, 0
	s_cbranch_scc1 .Lrw_S_0_r
	s_waitcnt vmcnt(8)
	s_branch .Lrw_S_0_d

; #define PG8_STAGE(bufoff, gbase, voff) do { _Pragma("unroll") for (int _i = 0; _i < 2; ++_i) \
;         __builtin_amdgcn_global_load_lds((const unsigned*)((const char*)(gbase) + (voff)[_i]), (LAS unsigned*)(lds + (bufoff) + ldsw + _i * 8192), 16, 0, 0); } while (0)
; #define PG8_LDA(dst, b, h) do { _Pragma("unroll") for (int m = 0; m < 4; ++m) _Pragma("unroll") for (int k = 0; k < 2; ++k) dst[m][k] = *(const LAS bf16x8*)(lds + PG8_SA(b, h) + aoff + m * 2048 + k * 1024); } while (0)
; #define PG8_MMA(ai, bj, At, Bt) do { __builtin_amdgcn_s_setprio(1); _Pragma("unroll") for (int m = 0; m < 4; ++m) _Pragma("unroll") for (int n = 0; n < 2; ++n) _Pragma("unroll") for (int k = 0; k < 2; ++k) \
;         acc[ai][bj][m][n] = __builtin_amdgcn_mfma_f32_16x16x32_bf16(Bt[n][k], At[m][k], acc[ai][bj][m][n], 0, 0, 0); __builtin_amdgcn_s_setprio(0); } while (0)
; #define PG8_WAIT_V(n) asm volatile("s_waitcnt vmcnt(" #n ")" ::: "memory")
; #define PG8_WAIT_L(n) asm volatile("s_waitcnt lgkmcnt(" #n ")" ::: "memory")
; #define PG8_BAR __builtin_amdgcn_s_barrier()
; #define PG8_SCHED __builtin_amdgcn_sched_barrier(0)
; template <class Epi>
; __device__ __forceinline__ void gemm_phase(LAS unsigned char* lds, const GemmD g, const Epi& E, int G, int c) {
;     ...
;             PG8_WAIT_V(8); PG8_WAIT_L(0); PG8_BAR; PG8_MMA(0, 0, At, B0); PG8_MMA(0, 1, At, B1); PG8_BAR; PG8_SCHED;
;             PG8_LDA(At, 0, 1); PG8_STAGE(PG8_SB(0, 0), b2, voffB); PG8_STAGE(PG8_SB(0, 1), b2 + hstepB, voffB); PG8_STAGE(PG8_SA(0, 0), a2, voffA);
;             PG8_WAIT_V(8); PG8_WAIT_L(0); PG8_BAR; PG8_MMA(1, 0, At, B0); PG8_MMA(1, 1, At, B1); PG8_BAR; PG8_SCHED;
.Lrw_S_0_d:
	s_waitcnt lgkmcnt(0)
	s_barrier
	s_setprio 1
	s_waitcnt lgkmcnt(0)
	v_mfma_f32_16x16x32_bf16 v[124:127], v[128:131], v[166:169], v[124:127]
	v_mfma_f32_16x16x32_bf16 v[120:123], v[142:145], v[166:169], v[120:123]
	v_mfma_f32_16x16x32_bf16 v[108:111], v[128:131], v[184:187], v[108:111]
	v_mfma_f32_16x16x32_bf16 v[104:107], v[142:145], v[184:187], v[104:107]
	v_mfma_f32_16x16x32_bf16 v[92:95], v[128:131], v[192:195], v[92:95]
	v_mfma_f32_16x16x32_bf16 v[88:91], v[142:145], v[192:195], v[88:91]
	v_mfma_f32_16x16x32_bf16 v[76:79], v[128:131], v[214:217], v[76:79]
	v_mfma_f32_16x16x32_bf16 v[72:75], v[142:145], v[214:217], v[72:75]
	v_mfma_f32_16x16x32_bf16 v[124:127], v[138:141], v[180:183], v[124:127]
	v_mfma_f32_16x16x32_bf16 v[120:123], v[146:149], v[180:183], v[120:123]
	v_mfma_f32_16x16x32_bf16 v[108:111], v[138:141], v[188:191], v[108:111]
	v_mfma_f32_16x16x32_bf16 v[104:107], v[146:149], v[188:191], v[104:107]
	v_mfma_f32_16x16x32_bf16 v[92:95], v[138:141], v[210:213], v[92:95]
	v_mfma_f32_16x16x32_bf16 v[88:91], v[146:149], v[210:213], v[88:91]
	v_mfma_f32_16x16x32_bf16 v[76:79], v[138:141], v[218:221], v[76:79]
	v_mfma_f32_16x16x32_bf16 v[72:75], v[146:149], v[218:221], v[72:75]
	s_setprio 0
	s_setprio 1
	v_mfma_f32_16x16x32_bf16 v[116:119], v[150:153], v[166:169], v[116:119]
	v_mfma_f32_16x16x32_bf16 v[112:115], v[158:161], v[166:169], v[112:115]
	v_mfma_f32_16x16x32_bf16 v[100:103], v[150:153], v[184:187], v[100:103]
	v_mfma_f32_16x16x32_bf16 v[96:99], v[158:161], v[184:187], v[96:99]
	v_mfma_f32_16x16x32_bf16 v[84:87], v[150:153], v[192:195], v[84:87]
	v_mfma_f32_16x16x32_bf16 v[80:83], v[158:161], v[192:195], v[80:83]
	v_mfma_f32_16x16x32_bf16 v[68:71], v[150:153], v[214:217], v[68:71]
	v_mfma_f32_16x16x32_bf16 v[64:67], v[158:161], v[214:217], v[64:67]
	v_mfma_f32_16x16x32_bf16 v[116:119], v[154:157], v[180:183], v[116:119]
	v_mfma_f32_16x16x32_bf16 v[112:115], v[162:165], v[180:183], v[112:115]
	v_mfma_f32_16x16x32_bf16 v[100:103], v[154:157], v[188:191], v[100:103]
	v_mfma_f32_16x16x32_bf16 v[96:99], v[162:165], v[188:191], v[96:99]
	v_mfma_f32_16x16x32_bf16 v[84:87], v[154:157], v[210:213], v[84:87]
	v_mfma_f32_16x16x32_bf16 v[80:83], v[162:165], v[210:213], v[80:83]
	v_mfma_f32_16x16x32_bf16 v[68:71], v[154:157], v[218:221], v[68:71]
	v_mfma_f32_16x16x32_bf16 v[64:67], v[162:165], v[218:221], v[64:67]
	s_setprio 0
	s_barrier
	s_mov_b32 m0, s38
	v_lshl_add_u64 v[174:175], s[94:95], 0, v[178:179]
	ds_read_b128 v[166:169], v173 offset:16384
	ds_read_b128 v[180:183], v173 offset:17408
	ds_read_b128 v[184:187], v173 offset:18432
	ds_read_b128 v[188:191], v173 offset:19456
	ds_read_b128 v[192:195], v173 offset:20480
	ds_read_b128 v[210:213], v173 offset:21504
	ds_read_b128 v[214:217], v173 offset:22528
	ds_read_b128 v[218:221], v173 offset:23552
	global_load_lds_dwordx4 v[174:175], off
	v_lshl_add_u64 v[198:199], s[94:95], 0, v[132:133]
	s_mov_b32 m0, s29
	v_lshl_add_u64 v[222:223], s[96:97], 0, v[178:179]
	global_load_lds_dwordx4 v[198:199], off
	s_mov_b32 m0, s33
	v_lshl_add_u64 v[224:225], s[92:93], 0, v[134:135]
	global_load_lds_dwordx4 v[222:223], off
	v_lshl_add_u64 v[222:223], s[96:97], 0, v[132:133]
	s_mov_b32 m0, s31
	s_nop 0
	global_load_lds_dwordx4 v[222:223], off
	v_lshl_add_u64 v[222:223], s[92:93], 0, v[136:137]
	s_mov_b32 m0, s30
	s_nop 0
	global_load_lds_dwordx4 v[222:223], off
	s_mov_b32 m0, s35
	s_nop 0
	global_load_lds_dwordx4 v[224:225], off
	s_cmp_lg_u32 s99, 0
	s_cbranch_scc1 .Lrw_S_1_r
	s_waitcnt vmcnt(8)
	s_branch .Lrw_S_1_d

; #define PG8_STAGE(bufoff, gbase, voff) do { _Pragma("unroll") for (int _i = 0; _i < 2; ++_i) \
;         __builtin_amdgcn_global_load_lds((const unsigned*)((const char*)(gbase) + (voff)[_i]), (LAS unsigned*)(lds + (bufoff) + ldsw + _i * 8192), 16, 0, 0); } while (0)
; #define PG8_LDA(dst, b, h) do { _Pragma("unroll") for (int m = 0; m < 4; ++m) _Pragma("unroll") for (int k = 0; k < 2; ++k) dst[m][k] = *(const LAS bf16x8*)(lds + PG8_SA(b, h) + aoff + m * 2048 + k * 1024); } while (0)
; #define PG8_LDB(dst, b, h) do { _Pragma("unroll") for (int n = 0; n < 2; ++n) _Pragma("unroll") for (int k = 0; k < 2; ++k) dst[n][k] = *(const LAS bf16x8*)(lds + PG8_SB(b, h) + boff + n * 2048 + k * 1024); } while (0)
; #define PG8_MMA(ai, bj, At, Bt) do { __builtin_amdgcn_s_setprio(1); _Pragma("unroll") for (int m = 0; m < 4; ++m) _Pragma("unroll") for (int n = 0; n < 2; ++n) _Pragma("unroll") for (int k = 0; k < 2; ++k) \
;         acc[ai][bj][m][n] = __builtin_amdgcn_mfma_f32_16x16x32_bf16(Bt[n][k], At[m][k], acc[ai][bj][m][n], 0, 0, 0); __builtin_amdgcn_s_setprio(0); } while (0)
; #define PG8_WAIT_V(n) asm volatile("s_waitcnt vmcnt(" #n ")" ::: "memory")
; #define PG8_WAIT_L(n) asm volatile("s_waitcnt lgkmcnt(" #n ")" ::: "memory")
; #define PG8_BAR __builtin_amdgcn_s_barrier()
; #define PG8_SCHED __builtin_amdgcn_sched_barrier(0)
; template <class Epi>
; __device__ __forceinline__ void gemm_phase(LAS unsigned char* lds, const GemmD g, const Epi& E, int G, int c) {
;     ...
;             PG8_WAIT_V(8); PG8_WAIT_L(0); PG8_BAR; PG8_MMA(1, 0, At, B0); PG8_MMA(1, 1, At, B1); PG8_BAR; PG8_SCHED;
;             PG8_LDB(B0, 1, 0); PG8_LDB(B1, 1, 1); PG8_SCHED; PG8_LDA(At, 1, 0); PG8_STAGE(PG8_SA(0, 1), a2 + hstepA, voffA);
;             PG8_WAIT_V(8); PG8_WAIT_L(0); PG8_BAR; PG8_MMA(0, 0, At, B0); PG8_MMA(0, 1, At, B1); PG8_BAR; PG8_SCHED;
.Lrw_S_1_d:
	s_waitcnt lgkmcnt(0)
	s_barrier
	s_setprio 1
	s_waitcnt lgkmcnt(0)
	v_mfma_f32_16x16x32_bf16 v[60:63], v[128:131], v[166:169], v[60:63]
	v_mfma_f32_16x16x32_bf16 v[56:59], v[142:145], v[166:169], v[56:59]
	v_mfma_f32_16x16x32_bf16 v[44:47], v[128:131], v[184:187], v[44:47]
	v_mfma_f32_16x16x32_bf16 v[40:43], v[142:145], v[184:187], v[40:43]
	v_mfma_f32_16x16x32_bf16 v[28:31], v[128:131], v[192:195], v[28:31]
	v_mfma_f32_16x16x32_bf16 v[24:27], v[142:145], v[192:195], v[24:27]
	v_mfma_f32_16x16x32_bf16 v[12:15], v[128:131], v[214:217], v[12:15]
	v_mfma_f32_16x16x32_bf16 v[8:11], v[142:145], v[214:217], v[8:11]
	v_mfma_f32_16x16x32_bf16 v[60:63], v[138:141], v[180:183], v[60:63]
	v_mfma_f32_16x16x32_bf16 v[56:59], v[146:149], v[180:183], v[56:59]
	v_mfma_f32_16x16x32_bf16 v[44:47], v[138:141], v[188:191], v[44:47]
	v_mfma_f32_16x16x32_bf16 v[40:43], v[146:149], v[188:191], v[40:43]
	v_mfma_f32_16x16x32_bf16 v[28:31], v[138:141], v[210:213], v[28:31]
	v_mfma_f32_16x16x32_bf16 v[24:27], v[146:149], v[210:213], v[24:27]
	v_mfma_f32_16x16x32_bf16 v[12:15], v[138:141], v[218:221], v[12:15]
	v_mfma_f32_16x16x32_bf16 v[8:11], v[146:149], v[218:221], v[8:11]
	s_setprio 0
	s_setprio 1
	v_mfma_f32_16x16x32_bf16 v[52:55], v[150:153], v[166:169], v[52:55]
	v_mfma_f32_16x16x32_bf16 v[48:51], v[158:161], v[166:169], v[48:51]
	v_mfma_f32_16x16x32_bf16 v[36:39], v[150:153], v[184:187], v[36:39]
	v_mfma_f32_16x16x32_bf16 v[32:35], v[158:161], v[184:187], v[32:35]
	v_mfma_f32_16x16x32_bf16 v[20:23], v[150:153], v[192:195], v[20:23]
	v_mfma_f32_16x16x32_bf16 v[16:19], v[158:161], v[192:195], v[16:19]
	v_mfma_f32_16x16x32_bf16 v[4:7], v[150:153], v[214:217], v[4:7]
	v_mfma_f32_16x16x32_bf16 v[0:3], v[158:161], v[214:217], v[0:3]
	v_mfma_f32_16x16x32_bf16 v[52:55], v[154:157], v[180:183], v[52:55]
	v_mfma_f32_16x16x32_bf16 v[48:51], v[162:165], v[180:183], v[48:51]
	v_mfma_f32_16x16x32_bf16 v[36:39], v[154:157], v[188:191], v[36:39]
	v_mfma_f32_16x16x32_bf16 v[32:35], v[162:165], v[188:191], v[32:35]
	v_mfma_f32_16x16x32_bf16 v[20:23], v[154:157], v[210:213], v[20:23]
	v_mfma_f32_16x16x32_bf16 v[16:19], v[162:165], v[210:213], v[16:19]
	v_mfma_f32_16x16x32_bf16 v[4:7], v[154:157], v[218:221], v[4:7]
	v_mfma_f32_16x16x32_bf16 v[0:3], v[162:165], v[218:221], v[0:3]
	s_setprio 0
	s_barrier
	v_add_u32_e32 v146, s28, v171
	v_add_u32_e32 v162, s27, v171
	ds_read_b128 v[128:131], v146
	ds_read_b128 v[138:141], v146 offset:1024
	ds_read_b128 v[142:145], v146 offset:2048
	ds_read_b128 v[146:149], v146 offset:3072
	ds_read_b128 v[150:153], v162
	ds_read_b128 v[154:157], v162 offset:1024
	ds_read_b128 v[158:161], v162 offset:2048
	ds_read_b128 v[162:165], v162 offset:3072
	s_mov_b32 m0, s36
	v_lshl_add_u64 v[226:227], vcc, 0, v[136:137]
	ds_read_b128 v[166:169], v173 offset:32768
	ds_read_b128 v[180:183], v173 offset:33792
	ds_read_b128 v[184:187], v173 offset:34816
	ds_read_b128 v[188:191], v173 offset:35840
	ds_read_b128 v[192:195], v173 offset:36864
	ds_read_b128 v[210:213], v173 offset:37888
	ds_read_b128 v[214:217], v173 offset:38912
	ds_read_b128 v[218:221], v173 offset:39936
	global_load_lds_dwordx4 v[226:227], off
	v_lshl_add_u64 v[226:227], vcc, 0, v[134:135]
	s_mov_b32 m0, s9
	s_nop 0
	global_load_lds_dwordx4 v[226:227], off
	s_waitcnt vmcnt(8)
	s_waitcnt lgkmcnt(0)
	s_barrier
	s_setprio 1
	s_waitcnt lgkmcnt(0)
	v_mfma_f32_16x16x32_bf16 v[124:127], v[128:131], v[166:169], v[124:127]
	v_mfma_f32_16x16x32_bf16 v[120:123], v[142:145], v[166:169], v[120:123]
	v_mfma_f32_16x16x32_bf16 v[108:111], v[128:131], v[184:187], v[108:111]
	v_mfma_f32_16x16x32_bf16 v[104:107], v[142:145], v[184:187], v[104:107]
	v_mfma_f32_16x16x32_bf16 v[92:95], v[128:131], v[192:195], v[92:95]
	v_mfma_f32_16x16x32_bf16 v[88:91], v[142:145], v[192:195], v[88:91]
	v_mfma_f32_16x16x32_bf16 v[76:79], v[128:131], v[214:217], v[76:79]
	v_mfma_f32_16x16x32_bf16 v[72:75], v[142:145], v[214:217], v[72:75]
	v_mfma_f32_16x16x32_bf16 v[124:127], v[138:141], v[180:183], v[124:127]
	v_mfma_f32_16x16x32_bf16 v[120:123], v[146:149], v[180:183], v[120:123]
	v_mfma_f32_16x16x32_bf16 v[108:111], v[138:141], v[188:191], v[108:111]
	v_mfma_f32_16x16x32_bf16 v[104:107], v[146:149], v[188:191], v[104:107]
	v_mfma_f32_16x16x32_bf16 v[92:95], v[138:141], v[210:213], v[92:95]
	v_mfma_f32_16x16x32_bf16 v[88:91], v[146:149], v[210:213], v[88:91]
	v_mfma_f32_16x16x32_bf16 v[76:79], v[138:141], v[218:221], v[76:79]
	v_mfma_f32_16x16x32_bf16 v[72:75], v[146:149], v[218:221], v[72:75]
	s_setprio 0
	s_setprio 1
	v_mfma_f32_16x16x32_bf16 v[116:119], v[150:153], v[166:169], v[116:119]
	v_mfma_f32_16x16x32_bf16 v[112:115], v[158:161], v[166:169], v[112:115]
	v_mfma_f32_16x16x32_bf16 v[100:103], v[150:153], v[184:187], v[100:103]
	v_mfma_f32_16x16x32_bf16 v[96:99], v[158:161], v[184:187], v[96:99]
	v_mfma_f32_16x16x32_bf16 v[84:87], v[150:153], v[192:195], v[84:87]
	v_mfma_f32_16x16x32_bf16 v[80:83], v[158:161], v[192:195], v[80:83]
	v_mfma_f32_16x16x32_bf16 v[68:71], v[150:153], v[214:217], v[68:71]
	v_mfma_f32_16x16x32_bf16 v[64:67], v[158:161], v[214:217], v[64:67]
	v_mfma_f32_16x16x32_bf16 v[116:119], v[154:157], v[180:183], v[116:119]
	v_mfma_f32_16x16x32_bf16 v[112:115], v[162:165], v[180:183], v[112:115]
	v_mfma_f32_16x16x32_bf16 v[100:103], v[154:157], v[188:191], v[100:103]
	v_mfma_f32_16x16x32_bf16 v[96:99], v[162:165], v[188:191], v[96:99]
	v_mfma_f32_16x16x32_bf16 v[84:87], v[154:157], v[210:213], v[84:87]
	v_mfma_f32_16x16x32_bf16 v[80:83], v[162:165], v[210:213], v[80:83]
	v_mfma_f32_16x16x32_bf16 v[68:71], v[154:157], v[218:221], v[68:71]
	v_mfma_f32_16x16x32_bf16 v[64:67], v[162:165], v[218:221], v[64:67]
	s_setprio 0
	s_barrier
; #define PG8_STAGE(bufoff, gbase, voff) do { _Pragma("unroll") for (int _i = 0; _i < 2; ++_i) \
;         __builtin_amdgcn_global_load_lds((const unsigned*)((const char*)(gbase) + (voff)[_i]), (LAS unsigned*)(lds + (bufoff) + ldsw + _i * 8192), 16, 0, 0); } while (0)
; #define PG8_LDA(dst, b, h) do { _Pragma("unroll") for (int m = 0; m < 4; ++m) _Pragma("unroll") for (int k = 0; k < 2; ++k) dst[m][k] = *(const LAS bf16x8*)(lds + PG8_SA(b, h) + aoff + m * 2048 + k * 1024); } while (0)
; #define PG8_MMA(ai, bj, At, Bt) do { __builtin_amdgcn_s_setprio(1); _Pragma("unroll") for (int m = 0; m < 4; ++m) _Pragma("unroll") for (int n = 0; n < 2; ++n) _Pragma("unroll") for (int k = 0; k < 2; ++k) \
;         acc[ai][bj][m][n] = __builtin_amdgcn_mfma_f32_16x16x32_bf16(Bt[n][k], At[m][k], acc[ai][bj][m][n], 0, 0, 0); __builtin_amdgcn_s_setprio(0); } while (0)
; #define PG8_WAIT_V(n) asm volatile("s_waitcnt vmcnt(" #n ")" ::: "memory")
; #define PG8_WAIT_L(n) asm volatile("s_waitcnt lgkmcnt(" #n ")" ::: "memory")
; #define PG8_BAR __builtin_amdgcn_s_barrier()
; #define PG8_SCHED __builtin_amdgcn_sched_barrier(0)
; template <class Epi>
; __device__ __forceinline__ void gemm_phase(LAS unsigned char* lds, const GemmD g, const Epi& E, int G, int c) {
;     ...
;             PG8_LDA(At, 1, 1); PG8_STAGE(PG8_SB(1, 0), b3, voffB); PG8_STAGE(PG8_SB(1, 1), b3 + hstepB, voffB); PG8_STAGE(PG8_SA(1, 0), a3, voffA);
;             PG8_WAIT_V(8); PG8_WAIT_L(0); PG8_BAR; PG8_MMA(1, 0, At, B0); PG8_MMA(1, 1, At, B1); PG8_BAR; PG8_SCHED;
;         }
;         if (wr == 0) PG8_BAR;
	s_mov_b32 m0, s19
	v_lshl_add_u64 v[174:175], v[174:175], 0, s[48:49]
	ds_read_b128 v[166:169], v173 offset:49152
	ds_read_b128 v[180:183], v173 offset:50176
	ds_read_b128 v[184:187], v173 offset:51200
	ds_read_b128 v[188:191], v173 offset:52224
	ds_read_b128 v[192:195], v173 offset:53248
	ds_read_b128 v[210:213], v173 offset:54272
	ds_read_b128 v[214:217], v173 offset:55296
	ds_read_b128 v[218:221], v173 offset:56320
	global_load_lds_dwordx4 v[174:175], off
	v_lshl_add_u64 v[174:175], v[198:199], 0, s[48:49]
	s_mov_b32 m0, s17
	s_nop 0
	global_load_lds_dwordx4 v[174:175], off
	v_lshl_add_u64 v[174:175], s[90:91], 0, v[178:179]
	s_mov_b32 m0, s50
	s_nop 0
	global_load_lds_dwordx4 v[174:175], off
	v_lshl_add_u64 v[174:175], s[90:91], 0, v[132:133]
	s_mov_b32 m0, s39
	s_nop 0
	global_load_lds_dwordx4 v[174:175], off
	v_lshl_add_u64 v[174:175], v[222:223], 0, s[48:49]
	s_mov_b32 m0, s10
	s_nop 0
	global_load_lds_dwordx4 v[174:175], off
	v_lshl_add_u64 v[174:175], v[224:225], 0, s[48:49]
	s_mov_b32 m0, s11
	s_nop 0
	global_load_lds_dwordx4 v[174:175], off
	s_waitcnt vmcnt(8)
	s_waitcnt lgkmcnt(0)
	s_barrier
	s_setprio 1
	s_waitcnt lgkmcnt(0)
	v_mfma_f32_16x16x32_bf16 v[60:63], v[128:131], v[166:169], v[60:63]
	v_mfma_f32_16x16x32_bf16 v[56:59], v[142:145], v[166:169], v[56:59]
	v_mfma_f32_16x16x32_bf16 v[44:47], v[128:131], v[184:187], v[44:47]
	v_mfma_f32_16x16x32_bf16 v[40:43], v[142:145], v[184:187], v[40:43]
	v_mfma_f32_16x16x32_bf16 v[28:31], v[128:131], v[192:195], v[28:31]
	v_mfma_f32_16x16x32_bf16 v[24:27], v[142:145], v[192:195], v[24:27]
	v_mfma_f32_16x16x32_bf16 v[12:15], v[128:131], v[214:217], v[12:15]
	v_mfma_f32_16x16x32_bf16 v[8:11], v[142:145], v[214:217], v[8:11]
	v_mfma_f32_16x16x32_bf16 v[60:63], v[138:141], v[180:183], v[60:63]
	v_mfma_f32_16x16x32_bf16 v[56:59], v[146:149], v[180:183], v[56:59]
	v_mfma_f32_16x16x32_bf16 v[44:47], v[138:141], v[188:191], v[44:47]
	v_mfma_f32_16x16x32_bf16 v[40:43], v[146:149], v[188:191], v[40:43]
	v_mfma_f32_16x16x32_bf16 v[28:31], v[138:141], v[210:213], v[28:31]
	v_mfma_f32_16x16x32_bf16 v[24:27], v[146:149], v[210:213], v[24:27]
	v_mfma_f32_16x16x32_bf16 v[12:15], v[138:141], v[218:221], v[12:15]
	v_mfma_f32_16x16x32_bf16 v[8:11], v[146:149], v[218:221], v[8:11]
	s_setprio 0
	s_setprio 1
	v_mfma_f32_16x16x32_bf16 v[52:55], v[150:153], v[166:169], v[52:55]
	v_mfma_f32_16x16x32_bf16 v[48:51], v[158:161], v[166:169], v[48:51]
	v_mfma_f32_16x16x32_bf16 v[36:39], v[150:153], v[184:187], v[36:39]
	v_mfma_f32_16x16x32_bf16 v[32:35], v[158:161], v[184:187], v[32:35]
	v_mfma_f32_16x16x32_bf16 v[20:23], v[150:153], v[192:195], v[20:23]
	v_mfma_f32_16x16x32_bf16 v[16:19], v[158:161], v[192:195], v[16:19]
	v_mfma_f32_16x16x32_bf16 v[4:7], v[150:153], v[214:217], v[4:7]
	v_mfma_f32_16x16x32_bf16 v[0:3], v[158:161], v[214:217], v[0:3]
	v_mfma_f32_16x16x32_bf16 v[52:55], v[154:157], v[180:183], v[52:55]
	v_mfma_f32_16x16x32_bf16 v[48:51], v[162:165], v[180:183], v[48:51]
	v_mfma_f32_16x16x32_bf16 v[36:39], v[154:157], v[188:191], v[36:39]
	v_mfma_f32_16x16x32_bf16 v[32:35], v[162:165], v[188:191], v[32:35]
	v_mfma_f32_16x16x32_bf16 v[20:23], v[154:157], v[210:213], v[20:23]
	v_mfma_f32_16x16x32_bf16 v[16:19], v[162:165], v[210:213], v[16:19]
	v_mfma_f32_16x16x32_bf16 v[4:7], v[154:157], v[218:221], v[4:7]
	v_mfma_f32_16x16x32_bf16 v[0:3], v[162:165], v[218:221], v[0:3]
	s_setprio 0
	s_barrier
	s_movk_i32 s4, 0x100
	s_andn2_b64 vcc, exec, s[88:89]
	s_mov_b64 s[90:91], -1
	s_mov_b64 s[88:89], 0
	s_cbranch_vccz .LBB0_329
	s_and_b64 vcc, exec, s[62:63]
	s_cbranch_vccz .LBB0_332
	s_barrier

; #define PG8_BAR __builtin_amdgcn_s_barrier()
; #define PG8_PIN_ACC() do { _Pragma("unroll") for (int a = 0; a < 2; ++a) _Pragma("unroll") for (int b = 0; b < 2; ++b) _Pragma("unroll") for (int m = 0; m < 4; ++m) \
;         asm volatile("" : "+v"(acc[a][b][m][0]), "+v"(acc[a][b][m][1])); } while (0)
; template <class Epi>
; __device__ __forceinline__ void gemm_phase(LAS unsigned char* lds, const GemmD g, const Epi& E, int G, int c) {
;     ...
;         if (!has_next) break;
;         if constexpr (Epi::PRELOAD) { E.preload(acc, npm, npn, nz, wr, wc, fr, fq); PG8_PIN_ACC(); }
;         else {
; #pragma unroll
;         for (int a = 0; a < 2; ++a)
; #pragma unroll
;             for (int b = 0; b < 2; ++b)
; #pragma unroll
;                 for (int m = 0; m < 4; ++m)
; #pragma unroll
;                     for (int n = 0; n < 2; ++n) acc[a][b][m][n] = (f32x4){0.f, 0.f, 0.f, 0.f};
;         }
;         cpm = npm; cpn = npn; cz = nz; cA = nA; cB = nB; ++ui;
;         if (wr == 1) PG8_BAR;
.LBB0_390:
	s_mov_b32 s99, 1
	s_andn2_b64 vcc, exec, s[4:5]
	s_mov_b32 s2, s60
	s_mov_b32 s9, s62
	s_mov_b64 s[80:81], s[78:79]
	s_mov_b64 s[42:43], s[66:67]
	s_cbranch_vccz .LBB0_472

; #define PG8_STAGE(bufoff, gbase, voff) do { _Pragma("unroll") for (int _i = 0; _i < 2; ++_i) \
;         __builtin_amdgcn_global_load_lds((const unsigned*)((const char*)(gbase) + (voff)[_i]), (LAS unsigned*)(lds + (bufoff) + ldsw + _i * 8192), 16, 0, 0); } while (0)
; #define PG8_LDA(dst, b, h) do { _Pragma("unroll") for (int m = 0; m < 4; ++m) _Pragma("unroll") for (int k = 0; k < 2; ++k) dst[m][k] = *(const LAS bf16x8*)(lds + PG8_SA(b, h) + aoff + m * 2048 + k * 1024); } while (0)
; #define PG8_LDB(dst, b, h) do { _Pragma("unroll") for (int n = 0; n < 2; ++n) _Pragma("unroll") for (int k = 0; k < 2; ++k) dst[n][k] = *(const LAS bf16x8*)(lds + PG8_SB(b, h) + boff + n * 2048 + k * 1024); } while (0)
; #define PG8_MMA(ai, bj, At, Bt) do { __builtin_amdgcn_s_setprio(1); _Pragma("unroll") for (int m = 0; m < 4; ++m) _Pragma("unroll") for (int n = 0; n < 2; ++n) _Pragma("unroll") for (int k = 0; k < 2; ++k) \
;         acc[ai][bj][m][n] = __builtin_amdgcn_mfma_f32_16x16x32_bf16(Bt[n][k], At[m][k], acc[ai][bj][m][n], 0, 0, 0); __builtin_amdgcn_s_setprio(0); } while (0)
; #define PG8_WAIT_V(n) asm volatile("s_waitcnt vmcnt(" #n ")" ::: "memory")
; #define PG8_WAIT_L(n) asm volatile("s_waitcnt lgkmcnt(" #n ")" ::: "memory")
; #define PG8_BAR __builtin_amdgcn_s_barrier()
; #define PG8_SCHED __builtin_amdgcn_sched_barrier(0)
; template <class Epi>
; __device__ __forceinline__ void gemm_phase(LAS unsigned char* lds, const GemmD g, const Epi& E, int G, int c) {
;     ...
;         for (int t = 0; t < nt; t += 2) {
;             const bool last = (t == nt - 2);
;             const char* a1 = cA + (size_t)(t + 1) * kstep;
;             const char* a2 = last ? nA : cA + (size_t)(t + 2) * kstep; const char* b2 = last ? nB : cB + (size_t)(t + 2) * kstep;
;             const char* a3 = a2 + kstep; const char* b3 = b2 + kstep;
;             PG8_LDB(B0, 0, 0); PG8_LDB(B1, 0, 1); PG8_SCHED; PG8_LDA(At, 0, 0); PG8_STAGE(PG8_SA(1, 1), a1 + hstepA, voffA);
;             PG8_WAIT_V(8); PG8_WAIT_L(0); PG8_BAR; PG8_MMA(0, 0, At, B0); PG8_MMA(0, 1, At, B1); PG8_BAR; PG8_SCHED;
;             PG8_LDA(At, 0, 1); PG8_STAGE(PG8_SB(0, 0), b2, voffB); PG8_STAGE(PG8_SB(0, 1), b2 + hstepB, voffB); PG8_STAGE(PG8_SA(0, 0), a2, voffA);
.LBB0_394:
	s_add_u32 s4, s42, 0xfff80080
	s_addc_u32 s5, s43, -1
	s_add_i32 s28, 0, 0x10000
	s_cmp_eq_u32 s27, 28
	s_cselect_b32 s5, s6, s5
	s_cselect_b32 s4, s10, s4
	s_cselect_b32 s81, s11, s22
	s_cselect_b32 s80, s17, s19
	s_add_i32 s31, 0, 0x14000
	v_add_u32_e32 v140, s28, v194
	v_add_u32_e32 v174, s31, v194
	ds_read_b128 v[128:131], v140
	ds_read_b128 v[132:135], v140 offset:1024
	ds_read_b128 v[136:139], v140 offset:2048
	ds_read_b128 v[140:143], v140 offset:3072
	ds_read_b128 v[162:165], v174
	ds_read_b128 v[166:169], v174 offset:1024
	ds_read_b128 v[170:173], v174 offset:2048
	ds_read_b128 v[180:183], v174 offset:3072
	v_lshl_add_u64 v[174:175], s[42:43], 0, v[158:159]
	s_add_i32 m0, s23, 0xc000
	ds_read_b128 v[184:187], v196
	ds_read_b128 v[188:191], v196 offset:1024
	ds_read_b128 v[210:213], v196 offset:2048
	ds_read_b128 v[214:217], v196 offset:3072
	ds_read_b128 v[218:221], v196 offset:4096
	ds_read_b128 v[222:225], v196 offset:5120
	ds_read_b128 v[226:229], v196 offset:6144
	ds_read_b128 v[230:233], v196 offset:7168
	global_load_lds_dwordx4 v[174:175], off
	v_lshl_add_u64 v[174:175], s[42:43], 0, v[160:161]
	s_add_i32 m0, s23, 0xe000
	s_nop 0
	global_load_lds_dwordx4 v[174:175], off
	s_cmp_lg_u32 s99, 0
	s_cbranch_scc1 .Lrw_In_0_r
	s_waitcnt vmcnt(8)
	s_branch .Lrw_In_0_d

; #define PG8_STAGE(bufoff, gbase, voff) do { _Pragma("unroll") for (int _i = 0; _i < 2; ++_i) \
;         __builtin_amdgcn_global_load_lds((const unsigned*)((const char*)(gbase) + (voff)[_i]), (LAS unsigned*)(lds + (bufoff) + ldsw + _i * 8192), 16, 0, 0); } while (0)
; #define PG8_LDA(dst, b, h) do { _Pragma("unroll") for (int m = 0; m < 4; ++m) _Pragma("unroll") for (int k = 0; k < 2; ++k) dst[m][k] = *(const LAS bf16x8*)(lds + PG8_SA(b, h) + aoff + m * 2048 + k * 1024); } while (0)
; #define PG8_MMA(ai, bj, At, Bt) do { __builtin_amdgcn_s_setprio(1); _Pragma("unroll") for (int m = 0; m < 4; ++m) _Pragma("unroll") for (int n = 0; n < 2; ++n) _Pragma("unroll") for (int k = 0; k < 2; ++k) \
;         acc[ai][bj][m][n] = __builtin_amdgcn_mfma_f32_16x16x32_bf16(Bt[n][k], At[m][k], acc[ai][bj][m][n], 0, 0, 0); __builtin_amdgcn_s_setprio(0); } while (0)
; #define PG8_WAIT_V(n) asm volatile("s_waitcnt vmcnt(" #n ")" ::: "memory")
; #define PG8_WAIT_L(n) asm volatile("s_waitcnt lgkmcnt(" #n ")" ::: "memory")
; #define PG8_BAR __builtin_amdgcn_s_barrier()
; #define PG8_SCHED __builtin_amdgcn_sched_barrier(0)
; template <class Epi>
; __device__ __forceinline__ void gemm_phase(LAS unsigned char* lds, const GemmD g, const Epi& E, int G, int c) {
;     ...
;             PG8_WAIT_V(8); PG8_WAIT_L(0); PG8_BAR; PG8_MMA(0, 0, At, B0); PG8_MMA(0, 1, At, B1); PG8_BAR; PG8_SCHED;
;             PG8_LDA(At, 0, 1); PG8_STAGE(PG8_SB(0, 0), b2, voffB); PG8_STAGE(PG8_SB(0, 1), b2 + hstepB, voffB); PG8_STAGE(PG8_SA(0, 0), a2, voffA);
;             PG8_WAIT_V(8); PG8_WAIT_L(0); PG8_BAR; PG8_MMA(1, 0, At, B0); PG8_MMA(1, 1, At, B1); PG8_BAR; PG8_SCHED;
.Lrw_In_0_d:
	s_waitcnt lgkmcnt(0)
	s_barrier
	s_setprio 1
	s_waitcnt lgkmcnt(0)
	v_mfma_f32_16x16x32_bf16 v[124:127], v[128:131], v[184:187], v[124:127]
	v_mfma_f32_16x16x32_bf16 v[120:123], v[136:139], v[184:187], v[120:123]
	v_mfma_f32_16x16x32_bf16 v[108:111], v[128:131], v[210:213], v[108:111]
	v_mfma_f32_16x16x32_bf16 v[104:107], v[136:139], v[210:213], v[104:107]
	v_mfma_f32_16x16x32_bf16 v[92:95], v[128:131], v[218:221], v[92:95]
	v_mfma_f32_16x16x32_bf16 v[88:91], v[136:139], v[218:221], v[88:91]
	v_mfma_f32_16x16x32_bf16 v[76:79], v[128:131], v[226:229], v[76:79]
	v_mfma_f32_16x16x32_bf16 v[72:75], v[136:139], v[226:229], v[72:75]
	v_mfma_f32_16x16x32_bf16 v[124:127], v[132:135], v[188:191], v[124:127]
	v_mfma_f32_16x16x32_bf16 v[120:123], v[140:143], v[188:191], v[120:123]
	v_mfma_f32_16x16x32_bf16 v[108:111], v[132:135], v[214:217], v[108:111]
	v_mfma_f32_16x16x32_bf16 v[104:107], v[140:143], v[214:217], v[104:107]
	v_mfma_f32_16x16x32_bf16 v[92:95], v[132:135], v[222:225], v[92:95]
	v_mfma_f32_16x16x32_bf16 v[88:91], v[140:143], v[222:225], v[88:91]
	v_mfma_f32_16x16x32_bf16 v[76:79], v[132:135], v[230:233], v[76:79]
	v_mfma_f32_16x16x32_bf16 v[72:75], v[140:143], v[230:233], v[72:75]
	s_setprio 0
	s_setprio 1
	v_mfma_f32_16x16x32_bf16 v[116:119], v[162:165], v[184:187], v[116:119]
	v_mfma_f32_16x16x32_bf16 v[112:115], v[170:173], v[184:187], v[112:115]
	v_mfma_f32_16x16x32_bf16 v[100:103], v[162:165], v[210:213], v[100:103]
	v_mfma_f32_16x16x32_bf16 v[96:99], v[170:173], v[210:213], v[96:99]
	v_mfma_f32_16x16x32_bf16 v[84:87], v[162:165], v[218:221], v[84:87]
	v_mfma_f32_16x16x32_bf16 v[80:83], v[170:173], v[218:221], v[80:83]
	v_mfma_f32_16x16x32_bf16 v[68:71], v[162:165], v[226:229], v[68:71]
	v_mfma_f32_16x16x32_bf16 v[64:67], v[170:173], v[226:229], v[64:67]
	v_mfma_f32_16x16x32_bf16 v[116:119], v[166:169], v[188:191], v[116:119]
	v_mfma_f32_16x16x32_bf16 v[112:115], v[180:183], v[188:191], v[112:115]
	v_mfma_f32_16x16x32_bf16 v[100:103], v[166:169], v[214:217], v[100:103]
	v_mfma_f32_16x16x32_bf16 v[96:99], v[180:183], v[214:217], v[96:99]
	v_mfma_f32_16x16x32_bf16 v[84:87], v[166:169], v[222:225], v[84:87]
	v_mfma_f32_16x16x32_bf16 v[80:83], v[180:183], v[222:225], v[80:83]
	v_mfma_f32_16x16x32_bf16 v[68:71], v[166:169], v[230:233], v[68:71]
	v_mfma_f32_16x16x32_bf16 v[64:67], v[180:183], v[230:233], v[64:67]
	s_setprio 0
	s_barrier
	s_add_i32 s28, s28, s16
	v_lshl_add_u64 v[174:175], s[80:81], 0, v[148:149]
	s_mov_b32 m0, s28
	ds_read_b128 v[184:187], v196 offset:16384
	ds_read_b128 v[188:191], v196 offset:17408
	ds_read_b128 v[210:213], v196 offset:18432
	ds_read_b128 v[214:217], v196 offset:19456
	ds_read_b128 v[218:221], v196 offset:20480
	ds_read_b128 v[222:225], v196 offset:21504
	ds_read_b128 v[226:229], v196 offset:22528
	ds_read_b128 v[230:233], v196 offset:23552
	global_load_lds_dwordx4 v[174:175], off
	s_add_i32 m0, s28, 0x2000
	s_add_u32 s28, s80, 0x80000
	v_lshl_add_u64 v[192:193], s[80:81], 0, v[144:145]
	s_addc_u32 s29, s81, 0
	s_add_i32 s31, s31, s16
	global_load_lds_dwordx4 v[192:193], off
	v_lshl_add_u64 v[198:199], s[28:29], 0, v[148:149]
	s_mov_b32 m0, s31
	v_lshl_add_u64 v[234:235], s[4:5], 0, v[146:147]
	global_load_lds_dwordx4 v[198:199], off
	v_lshl_add_u64 v[198:199], s[28:29], 0, v[144:145]
	s_add_i32 m0, s31, 0x2000
	s_nop 0
	global_load_lds_dwordx4 v[198:199], off
	v_lshl_add_u64 v[198:199], s[4:5], 0, v[150:151]
	s_mov_b32 m0, s23
	s_nop 0
	global_load_lds_dwordx4 v[198:199], off
	s_mov_b32 m0, s26
	s_nop 0
	global_load_lds_dwordx4 v[234:235], off
	s_cmp_lg_u32 s99, 0
	s_cbranch_scc1 .Lrw_In_1_r
	s_waitcnt vmcnt(8)
	s_branch .Lrw_In_1_d

; #define PG8_STAGE(bufoff, gbase, voff) do { _Pragma("unroll") for (int _i = 0; _i < 2; ++_i) \
;         __builtin_amdgcn_global_load_lds((const unsigned*)((const char*)(gbase) + (voff)[_i]), (LAS unsigned*)(lds + (bufoff) + ldsw + _i * 8192), 16, 0, 0); } while (0)
; #define PG8_LDA(dst, b, h) do { _Pragma("unroll") for (int m = 0; m < 4; ++m) _Pragma("unroll") for (int k = 0; k < 2; ++k) dst[m][k] = *(const LAS bf16x8*)(lds + PG8_SA(b, h) + aoff + m * 2048 + k * 1024); } while (0)
; #define PG8_LDB(dst, b, h) do { _Pragma("unroll") for (int n = 0; n < 2; ++n) _Pragma("unroll") for (int k = 0; k < 2; ++k) dst[n][k] = *(const LAS bf16x8*)(lds + PG8_SB(b, h) + boff + n * 2048 + k * 1024); } while (0)
; #define PG8_MMA(ai, bj, At, Bt) do { __builtin_amdgcn_s_setprio(1); _Pragma("unroll") for (int m = 0; m < 4; ++m) _Pragma("unroll") for (int n = 0; n < 2; ++n) _Pragma("unroll") for (int k = 0; k < 2; ++k) \
;         acc[ai][bj][m][n] = __builtin_amdgcn_mfma_f32_16x16x32_bf16(Bt[n][k], At[m][k], acc[ai][bj][m][n], 0, 0, 0); __builtin_amdgcn_s_setprio(0); } while (0)
; #define PG8_WAIT_V(n) asm volatile("s_waitcnt vmcnt(" #n ")" ::: "memory")
; #define PG8_WAIT_L(n) asm volatile("s_waitcnt lgkmcnt(" #n ")" ::: "memory")
; #define PG8_BAR __builtin_amdgcn_s_barrier()
; #define PG8_SCHED __builtin_amdgcn_sched_barrier(0)
; template <class Epi>
; __device__ __forceinline__ void gemm_phase(LAS unsigned char* lds, const GemmD g, const Epi& E, int G, int c) {
;     ...
;             PG8_WAIT_V(8); PG8_WAIT_L(0); PG8_BAR; PG8_MMA(1, 0, At, B0); PG8_MMA(1, 1, At, B1); PG8_BAR; PG8_SCHED;
;             PG8_LDB(B0, 1, 0); PG8_LDB(B1, 1, 1); PG8_SCHED; PG8_LDA(At, 1, 0); PG8_STAGE(PG8_SA(0, 1), a2 + hstepA, voffA);
;             PG8_WAIT_V(8); PG8_WAIT_L(0); PG8_BAR; PG8_MMA(0, 0, At, B0); PG8_MMA(0, 1, At, B1); PG8_BAR; PG8_SCHED;
.Lrw_In_1_d:
	s_waitcnt lgkmcnt(0)
	s_barrier
	s_setprio 1
	s_waitcnt lgkmcnt(0)
	v_mfma_f32_16x16x32_bf16 v[60:63], v[128:131], v[184:187], v[60:63]
	v_mfma_f32_16x16x32_bf16 v[56:59], v[136:139], v[184:187], v[56:59]
	v_mfma_f32_16x16x32_bf16 v[44:47], v[128:131], v[210:213], v[44:47]
	v_mfma_f32_16x16x32_bf16 v[40:43], v[136:139], v[210:213], v[40:43]
	v_mfma_f32_16x16x32_bf16 v[28:31], v[128:131], v[218:221], v[28:31]
	v_mfma_f32_16x16x32_bf16 v[24:27], v[136:139], v[218:221], v[24:27]
	v_mfma_f32_16x16x32_bf16 v[12:15], v[128:131], v[226:229], v[12:15]
	v_mfma_f32_16x16x32_bf16 v[8:11], v[136:139], v[226:229], v[8:11]
	v_mfma_f32_16x16x32_bf16 v[60:63], v[132:135], v[188:191], v[60:63]
	v_mfma_f32_16x16x32_bf16 v[56:59], v[140:143], v[188:191], v[56:59]
	v_mfma_f32_16x16x32_bf16 v[44:47], v[132:135], v[214:217], v[44:47]
	v_mfma_f32_16x16x32_bf16 v[40:43], v[140:143], v[214:217], v[40:43]
	v_mfma_f32_16x16x32_bf16 v[28:31], v[132:135], v[222:225], v[28:31]
	v_mfma_f32_16x16x32_bf16 v[24:27], v[140:143], v[222:225], v[24:27]
	v_mfma_f32_16x16x32_bf16 v[12:15], v[132:135], v[230:233], v[12:15]
	v_mfma_f32_16x16x32_bf16 v[8:11], v[140:143], v[230:233], v[8:11]
	s_setprio 0
	s_setprio 1
	v_mfma_f32_16x16x32_bf16 v[52:55], v[162:165], v[184:187], v[52:55]
	v_mfma_f32_16x16x32_bf16 v[48:51], v[170:173], v[184:187], v[48:51]
	v_mfma_f32_16x16x32_bf16 v[36:39], v[162:165], v[210:213], v[36:39]
	v_mfma_f32_16x16x32_bf16 v[32:35], v[170:173], v[210:213], v[32:35]
	v_mfma_f32_16x16x32_bf16 v[20:23], v[162:165], v[218:221], v[20:23]
	v_mfma_f32_16x16x32_bf16 v[16:19], v[170:173], v[218:221], v[16:19]
	v_mfma_f32_16x16x32_bf16 v[4:7], v[162:165], v[226:229], v[4:7]
	v_mfma_f32_16x16x32_bf16 v[0:3], v[170:173], v[226:229], v[0:3]
	v_mfma_f32_16x16x32_bf16 v[52:55], v[166:169], v[188:191], v[52:55]
	v_mfma_f32_16x16x32_bf16 v[48:51], v[180:183], v[188:191], v[48:51]
	v_mfma_f32_16x16x32_bf16 v[36:39], v[166:169], v[214:217], v[36:39]
	v_mfma_f32_16x16x32_bf16 v[32:35], v[180:183], v[214:217], v[32:35]
	v_mfma_f32_16x16x32_bf16 v[20:23], v[166:169], v[222:225], v[20:23]
	v_mfma_f32_16x16x32_bf16 v[16:19], v[180:183], v[222:225], v[16:19]
	v_mfma_f32_16x16x32_bf16 v[4:7], v[166:169], v[230:233], v[4:7]
	v_mfma_f32_16x16x32_bf16 v[0:3], v[180:183], v[230:233], v[0:3]
	s_setprio 0
	s_barrier
	s_add_i32 s28, 0, 0x18000
	s_add_i32 s29, 0, 0x1c000
	v_add_u32_e32 v140, s28, v194
	v_add_u32_e32 v178, s29, v194
	ds_read_b128 v[128:131], v140
	ds_read_b128 v[132:135], v140 offset:1024
	ds_read_b128 v[136:139], v140 offset:2048
	ds_read_b128 v[140:143], v140 offset:3072
	ds_read_b128 v[162:165], v178
	ds_read_b128 v[166:169], v178 offset:1024
	ds_read_b128 v[170:173], v178 offset:2048
	ds_read_b128 v[180:183], v178 offset:3072
	s_add_u32 s4, s4, 0x80000
	s_addc_u32 s5, s5, 0
	s_mov_b32 m0, s30
	v_lshl_add_u64 v[236:237], s[4:5], 0, v[150:151]
	ds_read_b128 v[184:187], v196 offset:32768
	ds_read_b128 v[188:191], v196 offset:33792
	ds_read_b128 v[210:213], v196 offset:34816
	ds_read_b128 v[214:217], v196 offset:35840
	ds_read_b128 v[218:221], v196 offset:36864
	ds_read_b128 v[222:225], v196 offset:37888
	ds_read_b128 v[226:229], v196 offset:38912
	ds_read_b128 v[230:233], v196 offset:39936
	global_load_lds_dwordx4 v[236:237], off
	v_lshl_add_u64 v[236:237], s[4:5], 0, v[146:147]
	s_mov_b32 m0, s35
	s_nop 0
	global_load_lds_dwordx4 v[236:237], off
	s_waitcnt vmcnt(8)
	s_waitcnt lgkmcnt(0)
	s_barrier
	s_setprio 1
	s_waitcnt lgkmcnt(0)
	v_mfma_f32_16x16x32_bf16 v[124:127], v[128:131], v[184:187], v[124:127]
	v_mfma_f32_16x16x32_bf16 v[120:123], v[136:139], v[184:187], v[120:123]
	v_mfma_f32_16x16x32_bf16 v[108:111], v[128:131], v[210:213], v[108:111]
	v_mfma_f32_16x16x32_bf16 v[104:107], v[136:139], v[210:213], v[104:107]
	v_mfma_f32_16x16x32_bf16 v[92:95], v[128:131], v[218:221], v[92:95]
	v_mfma_f32_16x16x32_bf16 v[88:91], v[136:139], v[218:221], v[88:91]
	v_mfma_f32_16x16x32_bf16 v[76:79], v[128:131], v[226:229], v[76:79]
	v_mfma_f32_16x16x32_bf16 v[72:75], v[136:139], v[226:229], v[72:75]
	v_mfma_f32_16x16x32_bf16 v[124:127], v[132:135], v[188:191], v[124:127]
	v_mfma_f32_16x16x32_bf16 v[120:123], v[140:143], v[188:191], v[120:123]
	v_mfma_f32_16x16x32_bf16 v[108:111], v[132:135], v[214:217], v[108:111]
	v_mfma_f32_16x16x32_bf16 v[104:107], v[140:143], v[214:217], v[104:107]
	v_mfma_f32_16x16x32_bf16 v[92:95], v[132:135], v[222:225], v[92:95]
	v_mfma_f32_16x16x32_bf16 v[88:91], v[140:143], v[222:225], v[88:91]
	v_mfma_f32_16x16x32_bf16 v[76:79], v[132:135], v[230:233], v[76:79]
	v_mfma_f32_16x16x32_bf16 v[72:75], v[140:143], v[230:233], v[72:75]
	s_setprio 0
	s_setprio 1
	v_mfma_f32_16x16x32_bf16 v[116:119], v[162:165], v[184:187], v[116:119]
	v_mfma_f32_16x16x32_bf16 v[112:115], v[170:173], v[184:187], v[112:115]
	v_mfma_f32_16x16x32_bf16 v[100:103], v[162:165], v[210:213], v[100:103]
	v_mfma_f32_16x16x32_bf16 v[96:99], v[170:173], v[210:213], v[96:99]
	v_mfma_f32_16x16x32_bf16 v[84:87], v[162:165], v[218:221], v[84:87]
	v_mfma_f32_16x16x32_bf16 v[80:83], v[170:173], v[218:221], v[80:83]
	v_mfma_f32_16x16x32_bf16 v[68:71], v[162:165], v[226:229], v[68:71]
	v_mfma_f32_16x16x32_bf16 v[64:67], v[170:173], v[226:229], v[64:67]
	v_mfma_f32_16x16x32_bf16 v[116:119], v[166:169], v[188:191], v[116:119]
	v_mfma_f32_16x16x32_bf16 v[112:115], v[180:183], v[188:191], v[112:115]
	v_mfma_f32_16x16x32_bf16 v[100:103], v[166:169], v[214:217], v[100:103]
	v_mfma_f32_16x16x32_bf16 v[96:99], v[180:183], v[214:217], v[96:99]
	v_mfma_f32_16x16x32_bf16 v[84:87], v[166:169], v[222:225], v[84:87]
	v_mfma_f32_16x16x32_bf16 v[80:83], v[180:183], v[222:225], v[80:83]
	v_mfma_f32_16x16x32_bf16 v[68:71], v[166:169], v[230:233], v[68:71]
	v_mfma_f32_16x16x32_bf16 v[64:67], v[180:183], v[230:233], v[64:67]
	s_setprio 0
	s_barrier
; #define PG8_STAGE(bufoff, gbase, voff) do { _Pragma("unroll") for (int _i = 0; _i < 2; ++_i) \
;         __builtin_amdgcn_global_load_lds((const unsigned*)((const char*)(gbase) + (voff)[_i]), (LAS unsigned*)(lds + (bufoff) + ldsw + _i * 8192), 16, 0, 0); } while (0)
; #define PG8_LDA(dst, b, h) do { _Pragma("unroll") for (int m = 0; m < 4; ++m) _Pragma("unroll") for (int k = 0; k < 2; ++k) dst[m][k] = *(const LAS bf16x8*)(lds + PG8_SA(b, h) + aoff + m * 2048 + k * 1024); } while (0)
; #define PG8_MMA(ai, bj, At, Bt) do { __builtin_amdgcn_s_setprio(1); _Pragma("unroll") for (int m = 0; m < 4; ++m) _Pragma("unroll") for (int n = 0; n < 2; ++n) _Pragma("unroll") for (int k = 0; k < 2; ++k) \
;         acc[ai][bj][m][n] = __builtin_amdgcn_mfma_f32_16x16x32_bf16(Bt[n][k], At[m][k], acc[ai][bj][m][n], 0, 0, 0); __builtin_amdgcn_s_setprio(0); } while (0)
; #define PG8_WAIT_V(n) asm volatile("s_waitcnt vmcnt(" #n ")" ::: "memory")
; #define PG8_WAIT_L(n) asm volatile("s_waitcnt lgkmcnt(" #n ")" ::: "memory")
; #define PG8_BAR __builtin_amdgcn_s_barrier()
; #define PG8_SCHED __builtin_amdgcn_sched_barrier(0)
; template <class Epi>
; __device__ __forceinline__ void gemm_phase(LAS unsigned char* lds, const GemmD g, const Epi& E, int G, int c) {
;     ...
;             PG8_LDA(At, 1, 1); PG8_STAGE(PG8_SB(1, 0), b3, voffB); PG8_STAGE(PG8_SB(1, 1), b3 + hstepB, voffB); PG8_STAGE(PG8_SA(1, 0), a3, voffA);
;             PG8_WAIT_V(8); PG8_WAIT_L(0); PG8_BAR; PG8_MMA(1, 0, At, B0); PG8_MMA(1, 1, At, B1); PG8_BAR; PG8_SCHED;
;         }
;         if (wr == 0) PG8_BAR;
	s_add_i32 s4, s28, s16
	v_lshl_add_u64 v[174:175], v[174:175], 0, s[48:49]
	s_mov_b32 m0, s4
	ds_read_b128 v[184:187], v196 offset:49152
	ds_read_b128 v[188:191], v196 offset:50176
	ds_read_b128 v[210:213], v196 offset:51200
	ds_read_b128 v[214:217], v196 offset:52224
	ds_read_b128 v[218:221], v196 offset:53248
	ds_read_b128 v[222:225], v196 offset:54272
	ds_read_b128 v[226:229], v196 offset:55296
	ds_read_b128 v[230:233], v196 offset:56320
	global_load_lds_dwordx4 v[174:175], off
	s_add_i32 m0, s4, 0x2000
	s_add_u32 s4, s80, 0x80080
	v_lshl_add_u64 v[174:175], v[192:193], 0, s[48:49]
	s_addc_u32 s5, s81, 0
	s_add_i32 s28, s29, s16
	global_load_lds_dwordx4 v[174:175], off
	v_lshl_add_u64 v[174:175], s[4:5], 0, v[148:149]
	s_mov_b32 m0, s28
	s_nop 0
	global_load_lds_dwordx4 v[174:175], off
	v_lshl_add_u64 v[174:175], s[4:5], 0, v[144:145]
	s_add_i32 m0, s28, 0x2000
	s_nop 0
	global_load_lds_dwordx4 v[174:175], off
	v_lshl_add_u64 v[174:175], v[198:199], 0, s[48:49]
	s_mov_b32 m0, s36
	s_nop 0
	global_load_lds_dwordx4 v[174:175], off
	v_lshl_add_u64 v[174:175], v[234:235], 0, s[48:49]
	s_mov_b32 m0, s82
	s_nop 0
	global_load_lds_dwordx4 v[174:175], off
	s_waitcnt vmcnt(8)
	s_waitcnt lgkmcnt(0)
	s_barrier
	s_setprio 1
	s_waitcnt lgkmcnt(0)
	v_mfma_f32_16x16x32_bf16 v[60:63], v[128:131], v[184:187], v[60:63]
	v_mfma_f32_16x16x32_bf16 v[56:59], v[136:139], v[184:187], v[56:59]
	v_mfma_f32_16x16x32_bf16 v[44:47], v[128:131], v[210:213], v[44:47]
	v_mfma_f32_16x16x32_bf16 v[40:43], v[136:139], v[210:213], v[40:43]
	v_mfma_f32_16x16x32_bf16 v[28:31], v[128:131], v[218:221], v[28:31]
	v_mfma_f32_16x16x32_bf16 v[24:27], v[136:139], v[218:221], v[24:27]
	v_mfma_f32_16x16x32_bf16 v[12:15], v[128:131], v[226:229], v[12:15]
	v_mfma_f32_16x16x32_bf16 v[8:11], v[136:139], v[226:229], v[8:11]
	v_mfma_f32_16x16x32_bf16 v[60:63], v[132:135], v[188:191], v[60:63]
	v_mfma_f32_16x16x32_bf16 v[56:59], v[140:143], v[188:191], v[56:59]
	v_mfma_f32_16x16x32_bf16 v[44:47], v[132:135], v[214:217], v[44:47]
	v_mfma_f32_16x16x32_bf16 v[40:43], v[140:143], v[214:217], v[40:43]
	v_mfma_f32_16x16x32_bf16 v[28:31], v[132:135], v[222:225], v[28:31]
	v_mfma_f32_16x16x32_bf16 v[24:27], v[140:143], v[222:225], v[24:27]
	v_mfma_f32_16x16x32_bf16 v[12:15], v[132:135], v[230:233], v[12:15]
	v_mfma_f32_16x16x32_bf16 v[8:11], v[140:143], v[230:233], v[8:11]
	s_setprio 0
	s_setprio 1
	v_mfma_f32_16x16x32_bf16 v[52:55], v[162:165], v[184:187], v[52:55]
	v_mfma_f32_16x16x32_bf16 v[48:51], v[170:173], v[184:187], v[48:51]
	v_mfma_f32_16x16x32_bf16 v[36:39], v[162:165], v[210:213], v[36:39]
	v_mfma_f32_16x16x32_bf16 v[32:35], v[170:173], v[210:213], v[32:35]
	v_mfma_f32_16x16x32_bf16 v[20:23], v[162:165], v[218:221], v[20:23]
	v_mfma_f32_16x16x32_bf16 v[16:19], v[170:173], v[218:221], v[16:19]
	v_mfma_f32_16x16x32_bf16 v[4:7], v[162:165], v[226:229], v[4:7]
	v_mfma_f32_16x16x32_bf16 v[0:3], v[170:173], v[226:229], v[0:3]
	v_mfma_f32_16x16x32_bf16 v[52:55], v[166:169], v[188:191], v[52:55]
	v_mfma_f32_16x16x32_bf16 v[48:51], v[180:183], v[188:191], v[48:51]
	v_mfma_f32_16x16x32_bf16 v[36:39], v[166:169], v[214:217], v[36:39]
	v_mfma_f32_16x16x32_bf16 v[32:35], v[180:183], v[214:217], v[32:35]
	v_mfma_f32_16x16x32_bf16 v[20:23], v[166:169], v[222:225], v[20:23]
	v_mfma_f32_16x16x32_bf16 v[16:19], v[180:183], v[222:225], v[16:19]
	v_mfma_f32_16x16x32_bf16 v[4:7], v[166:169], v[230:233], v[4:7]
	v_mfma_f32_16x16x32_bf16 v[0:3], v[180:183], v[230:233], v[0:3]
	s_setprio 0
	s_barrier
	s_add_i32 s27, s27, 2
	s_add_u32 s42, s42, 0x100
	s_addc_u32 s43, s43, 0
	s_add_u32 s19, s19, 0x100
	s_addc_u32 s22, s22, 0
	s_cmp_gt_u32 s27, 29
	s_cbranch_scc0 .LBB0_394
	s_and_b64 vcc, exec, s[46:47]
	s_cbranch_vccz .LBB0_397
	s_barrier

; #define PG8_BAR __builtin_amdgcn_s_barrier()
; #define PG8_PIN_ACC() do { _Pragma("unroll") for (int a = 0; a < 2; ++a) _Pragma("unroll") for (int b = 0; b < 2; ++b) _Pragma("unroll") for (int m = 0; m < 4; ++m) \
;         asm volatile("" : "+v"(acc[a][b][m][0]), "+v"(acc[a][b][m][1])); } while (0)
; template <class Epi>
; __device__ __forceinline__ void gemm_phase(LAS unsigned char* lds, const GemmD g, const Epi& E, int G, int c) {
;     ...
;         if (!has_next) break;
;         if constexpr (Epi::PRELOAD) { E.preload(acc, npm, npn, nz, wr, wc, fr, fq); PG8_PIN_ACC(); }
;         else {
; #pragma unroll
;         for (int a = 0; a < 2; ++a)
; #pragma unroll
;             for (int b = 0; b < 2; ++b)
; #pragma unroll
;                 for (int m = 0; m < 4; ++m)
; #pragma unroll
;                     for (int n = 0; n < 2; ++n) acc[a][b][m][n] = (f32x4){0.f, 0.f, 0.f, 0.f};
;         }
;         cpm = npm; cpn = npn; cz = nz; cA = nA; cB = nB; ++ui;
;         if (wr == 1) PG8_BAR;
.LBB0_478:
	s_mov_b32 s99, 1
	s_andn2_b64 vcc, exec, s[4:5]
	s_mov_b32 s26, s62
	s_mov_b32 s27, s64
	s_mov_b64 s[76:77], s[74:75]
	s_mov_b64 s[42:43], s[66:67]
	s_cbranch_vccz .LBB0_492

; #define PG8_STAGE(bufoff, gbase, voff) do { _Pragma("unroll") for (int _i = 0; _i < 2; ++_i) \
;         __builtin_amdgcn_global_load_lds((const unsigned*)((const char*)(gbase) + (voff)[_i]), (LAS unsigned*)(lds + (bufoff) + ldsw + _i * 8192), 16, 0, 0); } while (0)
; #define PG8_LDA(dst, b, h) do { _Pragma("unroll") for (int m = 0; m < 4; ++m) _Pragma("unroll") for (int k = 0; k < 2; ++k) dst[m][k] = *(const LAS bf16x8*)(lds + PG8_SA(b, h) + aoff + m * 2048 + k * 1024); } while (0)
; #define PG8_LDB(dst, b, h) do { _Pragma("unroll") for (int n = 0; n < 2; ++n) _Pragma("unroll") for (int k = 0; k < 2; ++k) dst[n][k] = *(const LAS bf16x8*)(lds + PG8_SB(b, h) + boff + n * 2048 + k * 1024); } while (0)
; #define PG8_MMA(ai, bj, At, Bt) do { __builtin_amdgcn_s_setprio(1); _Pragma("unroll") for (int m = 0; m < 4; ++m) _Pragma("unroll") for (int n = 0; n < 2; ++n) _Pragma("unroll") for (int k = 0; k < 2; ++k) \
;         acc[ai][bj][m][n] = __builtin_amdgcn_mfma_f32_16x16x32_bf16(Bt[n][k], At[m][k], acc[ai][bj][m][n], 0, 0, 0); __builtin_amdgcn_s_setprio(0); } while (0)
; #define PG8_WAIT_V(n) asm volatile("s_waitcnt vmcnt(" #n ")" ::: "memory")
; #define PG8_WAIT_L(n) asm volatile("s_waitcnt lgkmcnt(" #n ")" ::: "memory")
; #define PG8_BAR __builtin_amdgcn_s_barrier()
; #define PG8_SCHED __builtin_amdgcn_sched_barrier(0)
; template <class Epi>
; __device__ __forceinline__ void gemm_phase(LAS unsigned char* lds, const GemmD g, const Epi& E, int G, int c) {
;     ...
;         for (int t = 0; t < nt; t += 2) {
;             const bool last = (t == nt - 2);
;             const char* a1 = cA + (size_t)(t + 1) * kstep;
;             const char* a2 = last ? nA : cA + (size_t)(t + 2) * kstep; const char* b2 = last ? nB : cB + (size_t)(t + 2) * kstep;
;             const char* a3 = a2 + kstep; const char* b3 = b2 + kstep;
;             PG8_LDB(B0, 0, 0); PG8_LDB(B1, 0, 1); PG8_SCHED; PG8_LDA(At, 0, 0); PG8_STAGE(PG8_SA(1, 1), a1 + hstepA, voffA);
;             PG8_WAIT_V(8); PG8_WAIT_L(0); PG8_BAR; PG8_MMA(0, 0, At, B0); PG8_MMA(0, 1, At, B1); PG8_BAR; PG8_SCHED;
;             PG8_LDA(At, 0, 1); PG8_STAGE(PG8_SB(0, 0), b2, voffB); PG8_STAGE(PG8_SB(0, 1), b2 + hstepB, voffB); PG8_STAGE(PG8_SA(0, 0), a2, voffA);
.LBB0_486:
	s_add_u32 s4, s42, 0xfff80080
	s_addc_u32 s5, s43, -1
	s_add_i32 s38, 0, 0x10000
	s_cmp_eq_u32 s36, 28
	s_cselect_b32 s5, s28, s5
	s_cselect_b32 s4, s29, s4
	s_cselect_b32 s77, s30, s35
	s_cselect_b32 s76, s31, s33
	s_add_i32 s50, 0, 0x14000
	v_add_u32_e32 v150, s38, v159
	v_add_u32_e32 v170, s50, v159
	ds_read_b128 v[128:131], v150
	ds_read_b128 v[132:135], v150 offset:1024
	ds_read_b128 v[146:149], v150 offset:2048
	ds_read_b128 v[150:153], v150 offset:3072
	ds_read_b128 v[154:157], v170
	ds_read_b128 v[162:165], v170 offset:1024
	ds_read_b128 v[166:169], v170 offset:2048
	ds_read_b128 v[170:173], v170 offset:3072
	v_lshl_add_u64 v[174:175], s[42:43], 0, v[142:143]
	s_add_i32 m0, s10, 0xc000
	ds_read_b128 v[180:183], v161
	ds_read_b128 v[184:187], v161 offset:1024
	ds_read_b128 v[188:191], v161 offset:2048
	ds_read_b128 v[192:195], v161 offset:3072
	ds_read_b128 v[210:213], v161 offset:4096
	ds_read_b128 v[214:217], v161 offset:5120
	ds_read_b128 v[218:221], v161 offset:6144
	ds_read_b128 v[222:225], v161 offset:7168
	global_load_lds_dwordx4 v[174:175], off
	v_lshl_add_u64 v[174:175], s[42:43], 0, v[144:145]
	s_add_i32 m0, s10, 0xe000
	s_nop 0
	global_load_lds_dwordx4 v[174:175], off
	s_cmp_lg_u32 s99, 0
	s_cbranch_scc1 .Lrw_Bf16_0_r
	s_waitcnt vmcnt(8)
	s_branch .Lrw_Bf16_0_d

; #define PG8_STAGE(bufoff, gbase, voff) do { _Pragma("unroll") for (int _i = 0; _i < 2; ++_i) \
;         __builtin_amdgcn_global_load_lds((const unsigned*)((const char*)(gbase) + (voff)[_i]), (LAS unsigned*)(lds + (bufoff) + ldsw + _i * 8192), 16, 0, 0); } while (0)
; #define PG8_LDA(dst, b, h) do { _Pragma("unroll") for (int m = 0; m < 4; ++m) _Pragma("unroll") for (int k = 0; k < 2; ++k) dst[m][k] = *(const LAS bf16x8*)(lds + PG8_SA(b, h) + aoff + m * 2048 + k * 1024); } while (0)
; #define PG8_LDB(dst, b, h) do { _Pragma("unroll") for (int n = 0; n < 2; ++n) _Pragma("unroll") for (int k = 0; k < 2; ++k) dst[n][k] = *(const LAS bf16x8*)(lds + PG8_SB(b, h) + boff + n * 2048 + k * 1024); } while (0)
; #define PG8_MMA(ai, bj, At, Bt) do { __builtin_amdgcn_s_setprio(1); _Pragma("unroll") for (int m = 0; m < 4; ++m) _Pragma("unroll") for (int n = 0; n < 2; ++n) _Pragma("unroll") for (int k = 0; k < 2; ++k) \
;         acc[ai][bj][m][n] = __builtin_amdgcn_mfma_f32_16x16x32_bf16(Bt[n][k], At[m][k], acc[ai][bj][m][n], 0, 0, 0); __builtin_amdgcn_s_setprio(0); } while (0)
; #define PG8_WAIT_V(n) asm volatile("s_waitcnt vmcnt(" #n ")" ::: "memory")
; #define PG8_WAIT_L(n) asm volatile("s_waitcnt lgkmcnt(" #n ")" ::: "memory")
; #define PG8_BAR __builtin_amdgcn_s_barrier()
; #define PG8_SCHED __builtin_amdgcn_sched_barrier(0)
; template <class Epi>
; __device__ __forceinline__ void gemm_phase(LAS unsigned char* lds, const GemmD g, const Epi& E, int G, int c) {
;     ...
;             PG8_LDB(B0, 0, 0); PG8_LDB(B1, 0, 1); PG8_SCHED; PG8_LDA(At, 0, 0); PG8_STAGE(PG8_SA(1, 1), a1 + hstepA, voffA);
;             PG8_WAIT_V(8); PG8_WAIT_L(0); PG8_BAR; PG8_MMA(0, 0, At, B0); PG8_MMA(0, 1, At, B1); PG8_BAR; PG8_SCHED;
;             PG8_LDA(At, 0, 1); PG8_STAGE(PG8_SB(0, 0), b2, voffB); PG8_STAGE(PG8_SB(0, 1), b2 + hstepB, voffB); PG8_STAGE(PG8_SA(0, 0), a2, voffA);
;             PG8_WAIT_V(8); PG8_WAIT_L(0); PG8_BAR; PG8_MMA(1, 0, At, B0); PG8_MMA(1, 1, At, B1); PG8_BAR; PG8_SCHED;
.Lrw_Bf16_0_d:
	s_waitcnt lgkmcnt(0)
	s_barrier
	s_setprio 1
	s_waitcnt lgkmcnt(0)
	v_mfma_f32_16x16x32_bf16 v[124:127], v[128:131], v[180:183], v[124:127]
	v_mfma_f32_16x16x32_bf16 v[120:123], v[146:149], v[180:183], v[120:123]
	v_mfma_f32_16x16x32_bf16 v[112:115], v[128:131], v[188:191], v[112:115]
	v_mfma_f32_16x16x32_bf16 v[108:111], v[146:149], v[188:191], v[108:111]
	v_mfma_f32_16x16x32_bf16 v[100:103], v[128:131], v[210:213], v[100:103]
	v_mfma_f32_16x16x32_bf16 v[92:95], v[146:149], v[210:213], v[92:95]
	v_mfma_f32_16x16x32_bf16 v[84:87], v[128:131], v[218:221], v[84:87]
	v_mfma_f32_16x16x32_bf16 v[76:79], v[146:149], v[218:221], v[76:79]
	v_mfma_f32_16x16x32_bf16 v[124:127], v[132:135], v[184:187], v[124:127]
	v_mfma_f32_16x16x32_bf16 v[120:123], v[150:153], v[184:187], v[120:123]
	v_mfma_f32_16x16x32_bf16 v[112:115], v[132:135], v[192:195], v[112:115]
	v_mfma_f32_16x16x32_bf16 v[108:111], v[150:153], v[192:195], v[108:111]
	v_mfma_f32_16x16x32_bf16 v[100:103], v[132:135], v[214:217], v[100:103]
	v_mfma_f32_16x16x32_bf16 v[92:95], v[150:153], v[214:217], v[92:95]
	v_mfma_f32_16x16x32_bf16 v[84:87], v[132:135], v[222:225], v[84:87]
	v_mfma_f32_16x16x32_bf16 v[76:79], v[150:153], v[222:225], v[76:79]
	s_setprio 0
	s_setprio 1
	v_mfma_f32_16x16x32_bf16 v[116:119], v[154:157], v[180:183], v[116:119]
	v_mfma_f32_16x16x32_bf16 v[104:107], v[166:169], v[180:183], v[104:107]
	v_mfma_f32_16x16x32_bf16 v[96:99], v[154:157], v[188:191], v[96:99]
	v_mfma_f32_16x16x32_bf16 v[88:91], v[166:169], v[188:191], v[88:91]
	v_mfma_f32_16x16x32_bf16 v[80:83], v[154:157], v[210:213], v[80:83]
	v_mfma_f32_16x16x32_bf16 v[72:75], v[166:169], v[210:213], v[72:75]
	v_mfma_f32_16x16x32_bf16 v[68:71], v[154:157], v[218:221], v[68:71]
	v_mfma_f32_16x16x32_bf16 v[64:67], v[166:169], v[218:221], v[64:67]
	v_mfma_f32_16x16x32_bf16 v[116:119], v[162:165], v[184:187], v[116:119]
	v_mfma_f32_16x16x32_bf16 v[104:107], v[170:173], v[184:187], v[104:107]
	v_mfma_f32_16x16x32_bf16 v[96:99], v[162:165], v[192:195], v[96:99]
	v_mfma_f32_16x16x32_bf16 v[88:91], v[170:173], v[192:195], v[88:91]
	v_mfma_f32_16x16x32_bf16 v[80:83], v[162:165], v[214:217], v[80:83]
	v_mfma_f32_16x16x32_bf16 v[72:75], v[170:173], v[214:217], v[72:75]
	v_mfma_f32_16x16x32_bf16 v[68:71], v[162:165], v[222:225], v[68:71]
	v_mfma_f32_16x16x32_bf16 v[64:67], v[170:173], v[222:225], v[64:67]
	s_setprio 0
	s_barrier
	s_add_i32 s38, s38, s9
	v_lshl_add_u64 v[174:175], s[76:77], 0, v[178:179]
	s_mov_b32 m0, s38
	ds_read_b128 v[180:183], v161 offset:16384
	ds_read_b128 v[184:187], v161 offset:17408
	ds_read_b128 v[188:191], v161 offset:18432
	ds_read_b128 v[192:195], v161 offset:19456
	ds_read_b128 v[210:213], v161 offset:20480
	ds_read_b128 v[214:217], v161 offset:21504
	ds_read_b128 v[218:221], v161 offset:22528
	ds_read_b128 v[222:225], v161 offset:23552
	global_load_lds_dwordx4 v[174:175], off
	s_add_i32 m0, s38, 0x2000
	s_add_u32 s38, s76, 0x80000
	v_lshl_add_u64 v[198:199], s[76:77], 0, v[136:137]
	s_addc_u32 s39, s77, 0
	s_add_i32 s50, s50, s9
	global_load_lds_dwordx4 v[198:199], off
	v_lshl_add_u64 v[226:227], s[38:39], 0, v[178:179]
	s_mov_b32 m0, s50
	v_lshl_add_u64 v[228:229], s[4:5], 0, v[138:139]
	global_load_lds_dwordx4 v[226:227], off
	v_lshl_add_u64 v[226:227], s[38:39], 0, v[136:137]
	s_add_i32 m0, s50, 0x2000
	s_nop 0
	global_load_lds_dwordx4 v[226:227], off
	v_lshl_add_u64 v[226:227], s[4:5], 0, v[140:141]
	s_mov_b32 m0, s10
	s_nop 0
	global_load_lds_dwordx4 v[226:227], off
	s_mov_b32 m0, s11
	s_nop 0
	global_load_lds_dwordx4 v[228:229], off
	s_cmp_lg_u32 s99, 0
	s_cbranch_scc1 .Lrw_Bf16_1_r
	s_waitcnt vmcnt(8)
	s_branch .Lrw_Bf16_1_d

; #define PG8_STAGE(bufoff, gbase, voff) do { _Pragma("unroll") for (int _i = 0; _i < 2; ++_i) \
;         __builtin_amdgcn_global_load_lds((const unsigned*)((const char*)(gbase) + (voff)[_i]), (LAS unsigned*)(lds + (bufoff) + ldsw + _i * 8192), 16, 0, 0); } while (0)
; #define PG8_LDA(dst, b, h) do { _Pragma("unroll") for (int m = 0; m < 4; ++m) _Pragma("unroll") for (int k = 0; k < 2; ++k) dst[m][k] = *(const LAS bf16x8*)(lds + PG8_SA(b, h) + aoff + m * 2048 + k * 1024); } while (0)
; #define PG8_LDB(dst, b, h) do { _Pragma("unroll") for (int n = 0; n < 2; ++n) _Pragma("unroll") for (int k = 0; k < 2; ++k) dst[n][k] = *(const LAS bf16x8*)(lds + PG8_SB(b, h) + boff + n * 2048 + k * 1024); } while (0)
; #define PG8_MMA(ai, bj, At, Bt) do { __builtin_amdgcn_s_setprio(1); _Pragma("unroll") for (int m = 0; m < 4; ++m) _Pragma("unroll") for (int n = 0; n < 2; ++n) _Pragma("unroll") for (int k = 0; k < 2; ++k) \
;         acc[ai][bj][m][n] = __builtin_amdgcn_mfma_f32_16x16x32_bf16(Bt[n][k], At[m][k], acc[ai][bj][m][n], 0, 0, 0); __builtin_amdgcn_s_setprio(0); } while (0)
; #define PG8_WAIT_V(n) asm volatile("s_waitcnt vmcnt(" #n ")" ::: "memory")
; #define PG8_WAIT_L(n) asm volatile("s_waitcnt lgkmcnt(" #n ")" ::: "memory")
; #define PG8_BAR __builtin_amdgcn_s_barrier()
; #define PG8_SCHED __builtin_amdgcn_sched_barrier(0)
; template <class Epi>
; __device__ __forceinline__ void gemm_phase(LAS unsigned char* lds, const GemmD g, const Epi& E, int G, int c) {
;     ...
;             PG8_WAIT_V(8); PG8_WAIT_L(0); PG8_BAR; PG8_MMA(1, 0, At, B0); PG8_MMA(1, 1, At, B1); PG8_BAR; PG8_SCHED;
;             PG8_LDB(B0, 1, 0); PG8_LDB(B1, 1, 1); PG8_SCHED; PG8_LDA(At, 1, 0); PG8_STAGE(PG8_SA(0, 1), a2 + hstepA, voffA);
;             PG8_WAIT_V(8); PG8_WAIT_L(0); PG8_BAR; PG8_MMA(0, 0, At, B0); PG8_MMA(0, 1, At, B1); PG8_BAR; PG8_SCHED;
.Lrw_Bf16_1_d:
	s_waitcnt lgkmcnt(0)
	s_barrier
	s_setprio 1
	s_waitcnt lgkmcnt(0)
	v_mfma_f32_16x16x32_bf16 v[60:63], v[128:131], v[180:183], v[60:63]
	v_mfma_f32_16x16x32_bf16 v[56:59], v[146:149], v[180:183], v[56:59]
	v_mfma_f32_16x16x32_bf16 v[52:55], v[128:131], v[188:191], v[52:55]
	v_mfma_f32_16x16x32_bf16 v[44:47], v[146:149], v[188:191], v[44:47]
	v_mfma_f32_16x16x32_bf16 v[36:39], v[128:131], v[210:213], v[36:39]
	v_mfma_f32_16x16x32_bf16 v[28:31], v[146:149], v[210:213], v[28:31]
	v_mfma_f32_16x16x32_bf16 v[20:23], v[128:131], v[218:221], v[20:23]
	v_mfma_f32_16x16x32_bf16 v[12:15], v[146:149], v[218:221], v[12:15]
	v_mfma_f32_16x16x32_bf16 v[60:63], v[132:135], v[184:187], v[60:63]
	v_mfma_f32_16x16x32_bf16 v[56:59], v[150:153], v[184:187], v[56:59]
	v_mfma_f32_16x16x32_bf16 v[52:55], v[132:135], v[192:195], v[52:55]
	v_mfma_f32_16x16x32_bf16 v[44:47], v[150:153], v[192:195], v[44:47]
	v_mfma_f32_16x16x32_bf16 v[36:39], v[132:135], v[214:217], v[36:39]
	v_mfma_f32_16x16x32_bf16 v[28:31], v[150:153], v[214:217], v[28:31]
	v_mfma_f32_16x16x32_bf16 v[20:23], v[132:135], v[222:225], v[20:23]
	v_mfma_f32_16x16x32_bf16 v[12:15], v[150:153], v[222:225], v[12:15]
	s_setprio 0
	s_setprio 1
	v_mfma_f32_16x16x32_bf16 v[48:51], v[154:157], v[180:183], v[48:51]
	v_mfma_f32_16x16x32_bf16 v[40:43], v[166:169], v[180:183], v[40:43]
	v_mfma_f32_16x16x32_bf16 v[32:35], v[154:157], v[188:191], v[32:35]
	v_mfma_f32_16x16x32_bf16 v[24:27], v[166:169], v[188:191], v[24:27]
	v_mfma_f32_16x16x32_bf16 v[16:19], v[154:157], v[210:213], v[16:19]
	v_mfma_f32_16x16x32_bf16 v[8:11], v[166:169], v[210:213], v[8:11]
	v_mfma_f32_16x16x32_bf16 v[4:7], v[154:157], v[218:221], v[4:7]
	v_mfma_f32_16x16x32_bf16 v[0:3], v[166:169], v[218:221], v[0:3]
	v_mfma_f32_16x16x32_bf16 v[48:51], v[162:165], v[184:187], v[48:51]
	v_mfma_f32_16x16x32_bf16 v[40:43], v[170:173], v[184:187], v[40:43]
	v_mfma_f32_16x16x32_bf16 v[32:35], v[162:165], v[192:195], v[32:35]
	v_mfma_f32_16x16x32_bf16 v[24:27], v[170:173], v[192:195], v[24:27]
	v_mfma_f32_16x16x32_bf16 v[16:19], v[162:165], v[214:217], v[16:19]
	v_mfma_f32_16x16x32_bf16 v[8:11], v[170:173], v[214:217], v[8:11]
	v_mfma_f32_16x16x32_bf16 v[4:7], v[162:165], v[222:225], v[4:7]
	v_mfma_f32_16x16x32_bf16 v[0:3], v[170:173], v[222:225], v[0:3]
	s_setprio 0
	s_barrier
	s_add_i32 s38, 0, 0x18000
	s_add_i32 s39, 0, 0x1c000
	v_add_u32_e32 v150, s38, v159
	v_add_u32_e32 v170, s39, v159
	ds_read_b128 v[128:131], v150
	ds_read_b128 v[132:135], v150 offset:1024
	ds_read_b128 v[146:149], v150 offset:2048
	ds_read_b128 v[150:153], v150 offset:3072
	ds_read_b128 v[154:157], v170
	ds_read_b128 v[162:165], v170 offset:1024
	ds_read_b128 v[166:169], v170 offset:2048
	ds_read_b128 v[170:173], v170 offset:3072
	s_add_u32 s4, s4, 0x80000
	s_addc_u32 s5, s5, 0
	s_mov_b32 m0, s16
	v_lshl_add_u64 v[230:231], s[4:5], 0, v[140:141]
	ds_read_b128 v[180:183], v161 offset:32768
	ds_read_b128 v[184:187], v161 offset:33792
	ds_read_b128 v[188:191], v161 offset:34816
	ds_read_b128 v[192:195], v161 offset:35840
	ds_read_b128 v[210:213], v161 offset:36864
	ds_read_b128 v[214:217], v161 offset:37888
	ds_read_b128 v[218:221], v161 offset:38912
	ds_read_b128 v[222:225], v161 offset:39936
	global_load_lds_dwordx4 v[230:231], off
	v_lshl_add_u64 v[230:231], s[4:5], 0, v[138:139]
	s_mov_b32 m0, s17
	s_nop 0
	global_load_lds_dwordx4 v[230:231], off
	s_waitcnt vmcnt(8)
	s_waitcnt lgkmcnt(0)
	s_barrier
	s_setprio 1
	s_waitcnt lgkmcnt(0)
	v_mfma_f32_16x16x32_bf16 v[124:127], v[128:131], v[180:183], v[124:127]
	v_mfma_f32_16x16x32_bf16 v[120:123], v[146:149], v[180:183], v[120:123]
	v_mfma_f32_16x16x32_bf16 v[112:115], v[128:131], v[188:191], v[112:115]
	v_mfma_f32_16x16x32_bf16 v[108:111], v[146:149], v[188:191], v[108:111]
	v_mfma_f32_16x16x32_bf16 v[100:103], v[128:131], v[210:213], v[100:103]
	v_mfma_f32_16x16x32_bf16 v[92:95], v[146:149], v[210:213], v[92:95]
	v_mfma_f32_16x16x32_bf16 v[84:87], v[128:131], v[218:221], v[84:87]
	v_mfma_f32_16x16x32_bf16 v[76:79], v[146:149], v[218:221], v[76:79]
	v_mfma_f32_16x16x32_bf16 v[124:127], v[132:135], v[184:187], v[124:127]
	v_mfma_f32_16x16x32_bf16 v[120:123], v[150:153], v[184:187], v[120:123]
	v_mfma_f32_16x16x32_bf16 v[112:115], v[132:135], v[192:195], v[112:115]
	v_mfma_f32_16x16x32_bf16 v[108:111], v[150:153], v[192:195], v[108:111]
	v_mfma_f32_16x16x32_bf16 v[100:103], v[132:135], v[214:217], v[100:103]
	v_mfma_f32_16x16x32_bf16 v[92:95], v[150:153], v[214:217], v[92:95]
	v_mfma_f32_16x16x32_bf16 v[84:87], v[132:135], v[222:225], v[84:87]
	v_mfma_f32_16x16x32_bf16 v[76:79], v[150:153], v[222:225], v[76:79]
	s_setprio 0
	s_setprio 1
	v_mfma_f32_16x16x32_bf16 v[116:119], v[154:157], v[180:183], v[116:119]
	v_mfma_f32_16x16x32_bf16 v[104:107], v[166:169], v[180:183], v[104:107]
	v_mfma_f32_16x16x32_bf16 v[96:99], v[154:157], v[188:191], v[96:99]
	v_mfma_f32_16x16x32_bf16 v[88:91], v[166:169], v[188:191], v[88:91]
	v_mfma_f32_16x16x32_bf16 v[80:83], v[154:157], v[210:213], v[80:83]
	v_mfma_f32_16x16x32_bf16 v[72:75], v[166:169], v[210:213], v[72:75]
	v_mfma_f32_16x16x32_bf16 v[68:71], v[154:157], v[218:221], v[68:71]
	v_mfma_f32_16x16x32_bf16 v[64:67], v[166:169], v[218:221], v[64:67]
	v_mfma_f32_16x16x32_bf16 v[116:119], v[162:165], v[184:187], v[116:119]
	v_mfma_f32_16x16x32_bf16 v[104:107], v[170:173], v[184:187], v[104:107]
	v_mfma_f32_16x16x32_bf16 v[96:99], v[162:165], v[192:195], v[96:99]
	v_mfma_f32_16x16x32_bf16 v[88:91], v[170:173], v[192:195], v[88:91]
	v_mfma_f32_16x16x32_bf16 v[80:83], v[162:165], v[214:217], v[80:83]
	v_mfma_f32_16x16x32_bf16 v[72:75], v[170:173], v[214:217], v[72:75]
	v_mfma_f32_16x16x32_bf16 v[68:71], v[162:165], v[222:225], v[68:71]
	v_mfma_f32_16x16x32_bf16 v[64:67], v[170:173], v[222:225], v[64:67]
	s_setprio 0
	s_barrier
; #define PG8_STAGE(bufoff, gbase, voff) do { _Pragma("unroll") for (int _i = 0; _i < 2; ++_i) \
;         __builtin_amdgcn_global_load_lds((const unsigned*)((const char*)(gbase) + (voff)[_i]), (LAS unsigned*)(lds + (bufoff) + ldsw + _i * 8192), 16, 0, 0); } while (0)
; #define PG8_LDA(dst, b, h) do { _Pragma("unroll") for (int m = 0; m < 4; ++m) _Pragma("unroll") for (int k = 0; k < 2; ++k) dst[m][k] = *(const LAS bf16x8*)(lds + PG8_SA(b, h) + aoff + m * 2048 + k * 1024); } while (0)
; #define PG8_MMA(ai, bj, At, Bt) do { __builtin_amdgcn_s_setprio(1); _Pragma("unroll") for (int m = 0; m < 4; ++m) _Pragma("unroll") for (int n = 0; n < 2; ++n) _Pragma("unroll") for (int k = 0; k < 2; ++k) \
;         acc[ai][bj][m][n] = __builtin_amdgcn_mfma_f32_16x16x32_bf16(Bt[n][k], At[m][k], acc[ai][bj][m][n], 0, 0, 0); __builtin_amdgcn_s_setprio(0); } while (0)
; #define PG8_WAIT_V(n) asm volatile("s_waitcnt vmcnt(" #n ")" ::: "memory")
; #define PG8_WAIT_L(n) asm volatile("s_waitcnt lgkmcnt(" #n ")" ::: "memory")
; #define PG8_BAR __builtin_amdgcn_s_barrier()
; #define PG8_SCHED __builtin_amdgcn_sched_barrier(0)
; template <class Epi>
; __device__ __forceinline__ void gemm_phase(LAS unsigned char* lds, const GemmD g, const Epi& E, int G, int c) {
;     ...
;             PG8_LDA(At, 1, 1); PG8_STAGE(PG8_SB(1, 0), b3, voffB); PG8_STAGE(PG8_SB(1, 1), b3 + hstepB, voffB); PG8_STAGE(PG8_SA(1, 0), a3, voffA);
;             PG8_WAIT_V(8); PG8_WAIT_L(0); PG8_BAR; PG8_MMA(1, 0, At, B0); PG8_MMA(1, 1, At, B1); PG8_BAR; PG8_SCHED;
;         }
;         if (wr == 0) PG8_BAR;
	s_add_i32 s4, s38, s9
	v_lshl_add_u64 v[174:175], v[174:175], 0, s[48:49]
	s_mov_b32 m0, s4
	ds_read_b128 v[180:183], v161 offset:49152
	ds_read_b128 v[184:187], v161 offset:50176
	ds_read_b128 v[188:191], v161 offset:51200
	ds_read_b128 v[192:195], v161 offset:52224
	ds_read_b128 v[210:213], v161 offset:53248
	ds_read_b128 v[214:217], v161 offset:54272
	ds_read_b128 v[218:221], v161 offset:55296
	ds_read_b128 v[222:225], v161 offset:56320
	global_load_lds_dwordx4 v[174:175], off
	s_add_i32 m0, s4, 0x2000
	s_add_u32 s4, s76, 0x80080
	v_lshl_add_u64 v[174:175], v[198:199], 0, s[48:49]
	s_addc_u32 s5, s77, 0
	s_add_i32 s38, s39, s9
	global_load_lds_dwordx4 v[174:175], off
	v_lshl_add_u64 v[174:175], s[4:5], 0, v[178:179]
	s_mov_b32 m0, s38
	s_nop 0
	global_load_lds_dwordx4 v[174:175], off
	v_lshl_add_u64 v[174:175], s[4:5], 0, v[136:137]
	s_add_i32 m0, s38, 0x2000
	s_nop 0
	global_load_lds_dwordx4 v[174:175], off
	v_lshl_add_u64 v[174:175], v[226:227], 0, s[48:49]
	s_mov_b32 m0, s19
	s_nop 0
	global_load_lds_dwordx4 v[174:175], off
	v_lshl_add_u64 v[174:175], v[228:229], 0, s[48:49]
	s_mov_b32 m0, s22
	s_nop 0
	global_load_lds_dwordx4 v[174:175], off
	s_waitcnt vmcnt(8)
	s_waitcnt lgkmcnt(0)
	s_barrier
	s_setprio 1
	s_waitcnt lgkmcnt(0)
	v_mfma_f32_16x16x32_bf16 v[60:63], v[128:131], v[180:183], v[60:63]
	v_mfma_f32_16x16x32_bf16 v[56:59], v[146:149], v[180:183], v[56:59]
	v_mfma_f32_16x16x32_bf16 v[52:55], v[128:131], v[188:191], v[52:55]
	v_mfma_f32_16x16x32_bf16 v[44:47], v[146:149], v[188:191], v[44:47]
	v_mfma_f32_16x16x32_bf16 v[36:39], v[128:131], v[210:213], v[36:39]
	v_mfma_f32_16x16x32_bf16 v[28:31], v[146:149], v[210:213], v[28:31]
	v_mfma_f32_16x16x32_bf16 v[20:23], v[128:131], v[218:221], v[20:23]
	v_mfma_f32_16x16x32_bf16 v[12:15], v[146:149], v[218:221], v[12:15]
	v_mfma_f32_16x16x32_bf16 v[60:63], v[132:135], v[184:187], v[60:63]
	v_mfma_f32_16x16x32_bf16 v[56:59], v[150:153], v[184:187], v[56:59]
	v_mfma_f32_16x16x32_bf16 v[52:55], v[132:135], v[192:195], v[52:55]
	v_mfma_f32_16x16x32_bf16 v[44:47], v[150:153], v[192:195], v[44:47]
	v_mfma_f32_16x16x32_bf16 v[36:39], v[132:135], v[214:217], v[36:39]
	v_mfma_f32_16x16x32_bf16 v[28:31], v[150:153], v[214:217], v[28:31]
	v_mfma_f32_16x16x32_bf16 v[20:23], v[132:135], v[222:225], v[20:23]
	v_mfma_f32_16x16x32_bf16 v[12:15], v[150:153], v[222:225], v[12:15]
	s_setprio 0
	s_setprio 1
	v_mfma_f32_16x16x32_bf16 v[48:51], v[154:157], v[180:183], v[48:51]
	v_mfma_f32_16x16x32_bf16 v[40:43], v[166:169], v[180:183], v[40:43]
	v_mfma_f32_16x16x32_bf16 v[32:35], v[154:157], v[188:191], v[32:35]
	v_mfma_f32_16x16x32_bf16 v[24:27], v[166:169], v[188:191], v[24:27]
	v_mfma_f32_16x16x32_bf16 v[16:19], v[154:157], v[210:213], v[16:19]
	v_mfma_f32_16x16x32_bf16 v[8:11], v[166:169], v[210:213], v[8:11]
	v_mfma_f32_16x16x32_bf16 v[4:7], v[154:157], v[218:221], v[4:7]
	v_mfma_f32_16x16x32_bf16 v[0:3], v[166:169], v[218:221], v[0:3]
	v_mfma_f32_16x16x32_bf16 v[48:51], v[162:165], v[184:187], v[48:51]
	v_mfma_f32_16x16x32_bf16 v[40:43], v[170:173], v[184:187], v[40:43]
	v_mfma_f32_16x16x32_bf16 v[32:35], v[162:165], v[192:195], v[32:35]
	v_mfma_f32_16x16x32_bf16 v[24:27], v[170:173], v[192:195], v[24:27]
	v_mfma_f32_16x16x32_bf16 v[16:19], v[162:165], v[214:217], v[16:19]
	v_mfma_f32_16x16x32_bf16 v[8:11], v[170:173], v[214:217], v[8:11]
	v_mfma_f32_16x16x32_bf16 v[4:7], v[162:165], v[222:225], v[4:7]
	v_mfma_f32_16x16x32_bf16 v[0:3], v[170:173], v[222:225], v[0:3]
	s_setprio 0
	s_barrier
	s_add_i32 s36, s36, 2
	s_add_u32 s42, s42, 0x100
	s_addc_u32 s43, s43, 0
	s_add_u32 s33, s33, 0x100
	s_addc_u32 s35, s35, 0
	s_cmp_gt_u32 s36, 29
	s_cbranch_scc0 .LBB0_486
	s_and_b64 vcc, exec, s[46:47]
	s_cbranch_vccz .LBB0_489
	s_barrier

; __global__ void __launch_bounds__(512, 2) mega_fwd(Params p_) {
	.amdhsa_kernel _Z8mega_fwd6Params
		.amdhsa_group_segment_fixed_size 0
		.amdhsa_private_segment_fixed_size 0
		.amdhsa_kernarg_size 440
		.amdhsa_user_sgpr_count 2
		.amdhsa_user_sgpr_dispatch_ptr 0
		.amdhsa_user_sgpr_queue_ptr 0
		.amdhsa_user_sgpr_kernarg_segment_ptr 1
		.amdhsa_user_sgpr_dispatch_id 0
		.amdhsa_user_sgpr_kernarg_preload_length 0
		.amdhsa_user_sgpr_kernarg_preload_offset 0
		.amdhsa_user_sgpr_private_segment_size 0
		.amdhsa_uses_dynamic_stack 0
		.amdhsa_enable_private_segment 0
		.amdhsa_system_sgpr_workgroup_id_x 1
		.amdhsa_system_sgpr_workgroup_id_y 0
		.amdhsa_system_sgpr_workgroup_id_z 0
		.amdhsa_system_sgpr_workgroup_info 0
		.amdhsa_system_vgpr_workitem_id 2
		.amdhsa_next_free_vgpr 241
		.amdhsa_next_free_sgpr 100
		.amdhsa_accum_offset 244
		.amdhsa_reserve_vcc 1
		.amdhsa_float_round_mode_32 0
		.amdhsa_float_round_mode_16_64 0
		.amdhsa_float_denorm_mode_32 3
		.amdhsa_float_denorm_mode_16_64 3
		.amdhsa_dx10_clamp 1
		.amdhsa_ieee_mode 1
		.amdhsa_fp16_overflow 0
		.amdhsa_tg_split 0
		.amdhsa_exception_fp_ieee_invalid_op 0
		.amdhsa_exception_fp_denorm_src 0
		.amdhsa_exception_fp_ieee_div_zero 0
		.amdhsa_exception_fp_ieee_overflow 0
		.amdhsa_exception_fp_ieee_underflow 0
		.amdhsa_exception_fp_ieee_inexact 0
		.amdhsa_exception_int_div_zero 0
	.end_amdhsa_kernel

; __global__ void __launch_bounds__(512, 2) mega_fwd(Params p_) {
amdhsa.kernels:
  - .agpr_count:     0
    .args:
      - .offset:         0
        .size:           184
        .value_kind:     by_value
      - .offset:         184
        .size:           4
        .value_kind:     hidden_block_count_x
      - .offset:         188
        .size:           4
        .value_kind:     hidden_block_count_y
      - .offset:         192
        .size:           4
        .value_kind:     hidden_block_count_z
      - .offset:         196
        .size:           2
        .value_kind:     hidden_group_size_x
      - .offset:         198
        .size:           2
        .value_kind:     hidden_group_size_y
      - .offset:         200
        .size:           2
        .value_kind:     hidden_group_size_z
      - .offset:         202
        .size:           2
        .value_kind:     hidden_remainder_x
      - .offset:         204
        .size:           2
        .value_kind:     hidden_remainder_y
      - .offset:         206
        .size:           2
        .value_kind:     hidden_remainder_z
      - .offset:         224
        .size:           8
        .value_kind:     hidden_global_offset_x
      - .offset:         232
        .size:           8
        .value_kind:     hidden_global_offset_y
      - .offset:         240
        .size:           8
        .value_kind:     hidden_global_offset_z
      - .offset:         248
        .size:           2
        .value_kind:     hidden_grid_dims
      - .offset:         272
        .size:           8
        .value_kind:     hidden_multigrid_sync_arg
      - .offset:         304
        .size:           4
        .value_kind:     hidden_dynamic_lds_size
    .group_segment_fixed_size: 0
    .kernarg_segment_align: 8
    .kernarg_segment_size: 440
    .language:       OpenCL C
    .language_version:
      - 2
      - 0
    .max_flat_workgroup_size: 512
    .name:           _Z8mega_fwd6Params
    .private_segment_fixed_size: 0
    .sgpr_count:     106
    .sgpr_spill_count: 200
    .symbol:         _Z8mega_fwd6Params.kd
    .uniform_work_group_size: 1
    .uses_dynamic_stack: false
    .vgpr_count:     241
    .vgpr_spill_count: 0
    .wavefront_size: 64
